# MLA fast loops: LDS-DMA destinations computed straight into m0, dead m0 restores dropped, m0 wait states filled with neighbouring VALU instead of s_nop
# speedup vs baseline: 1.0040x; 1.0003x over previous
.Lmla_fast_w03:
	s_waitcnt vmcnt(6) lgkmcnt(0)
	s_barrier
	v_mfma_f32_32x32x16_bf16 v[2:17], v[134:137], v[166:169], v[2:17]
	ds_read_b64_tr_b16 v[66:67], v189 offset:28672
	ds_read_b64_tr_b16 v[68:69], v189 offset:29184
	v_exp_f32_e32 v34, v34
	v_exp_f32_e32 v35, v35
	v_exp_f32_e32 v36, v36
	v_mfma_f32_32x32x16_bf16 v[2:17], v[130:133], v[162:165], v[2:17]
	ds_read_b64_tr_b16 v[70:71], v189 offset:29696
	ds_read_b64_tr_b16 v[72:73], v189 offset:30208
	v_add_f32_e32 v74, v193, v34
	v_exp_f32_e32 v37, v37
	v_cvt_pk_bf16_f32 v150, v34, v35
	v_add_f32_e32 v78, v35, v74
	v_mfma_f32_32x32x16_bf16 v[2:17], v[126:129], v[158:161], v[2:17]
	ds_read_b64_tr_b16 v[74:75], v189 offset:30720
	ds_read_b64_tr_b16 v[76:77], v189 offset:31232
	v_exp_f32_e32 v38, v38
	v_exp_f32_e32 v39, v39
	v_add_f32_e32 v82, v78, v36
	v_cvt_pk_bf16_f32 v151, v36, v37
	v_mfma_f32_32x32x16_bf16 v[2:17], v[122:125], v[154:157], v[2:17]
	ds_read_b64_tr_b16 v[78:79], v189 offset:31744
	ds_read_b64_tr_b16 v[80:81], v189 offset:32256
	v_add_f32_e32 v82, v82, v37
	v_exp_f32_e32 v40, v40
	v_exp_f32_e32 v41, v41
	v_add_f32_e32 v86, v38, v82
	s_waitcnt lgkmcnt(6)
	v_mfma_f32_32x32x16_bf16 v[18:33], v[134:137], v[66:69], v[18:33]
	ds_read_b128 v[82:85], v182 offset:36864
	v_cvt_pk_bf16_f32 v152, v38, v39
	v_add_f32_e32 v90, v86, v39
	v_exp_f32_e32 v42, v42
	v_exp_f32_e32 v43, v43
	s_waitcnt lgkmcnt(5)
	v_mfma_f32_32x32x16_bf16 v[18:33], v[130:133], v[70:73], v[18:33]
	ds_read_b128 v[86:89], v182 offset:40960
	v_add_f32_e32 v66, v90, v40
	v_exp_f32_e32 v44, v44
	v_cvt_pk_bf16_f32 v153, v40, v41
	v_add_f32_e32 v66, v41, v66
	s_waitcnt lgkmcnt(4)
	v_mfma_f32_32x32x16_bf16 v[18:33], v[126:129], v[74:77], v[18:33]
	ds_read_b128 v[154:157], v183 offset:36864
	v_add_f32_e32 v66, v66, v42
	v_exp_f32_e32 v45, v45
	v_cvt_pk_bf16_f32 v146, v42, v43
	v_add_f32_e32 v66, v43, v66
	s_waitcnt lgkmcnt(3)
	v_mfma_f32_32x32x16_bf16 v[18:33], v[122:125], v[78:81], v[18:33]
	ds_read_b128 v[162:165], v183 offset:40960
	v_exp_f32_e32 v46, v46
	v_exp_f32_e32 v47, v47
	v_add_f32_e32 v66, v66, v44
	v_cvt_pk_bf16_f32 v147, v44, v45
	s_nop 0
	v_add_f32_e32 v66, v66, v45
	v_add_f32_e32 v91, v46, v66
	s_waitcnt lgkmcnt(3)
	v_mfma_f32_32x32x16_bf16 v[66:81], v[82:85], v[98:101], 0
	ds_read_b128 v[166:169], v184 offset:36864
	v_exp_f32_e32 v48, v48
	v_exp_f32_e32 v49, v49
	ds_read_b128 v[158:161], v184 offset:40960
	v_add_f32_e32 v193, v91, v47
	s_waitcnt lgkmcnt(4)
	v_mfma_f32_32x32x16_bf16 v[82:97], v[86:89], v[98:101], 0
	s_add_u32 s26, s20, 0xfffe0000
	s_addc_u32 s27, s21, -1
	s_add_u32 s28, s22, 0xfffff000
	s_addc_u32 s29, s23, -1
	s_add_i32 m0, 0x6000, s8
	v_exp_f32_e32 v50, v50
	global_load_lds_dwordx4 v174, s[26:27]
	s_add_i32 m0, m0, 0x2000
	v_exp_f32_e32 v51, v51
	global_load_lds_dwordx4 v192, s[28:29]
	s_mov_b32 m0, s12
	v_cvt_pk_bf16_f32 v148, v46, v47
	global_load_lds_dwordx4 v191, s[26:27]
	s_waitcnt lgkmcnt(3)
	v_mfma_f32_32x32x16_bf16 v[66:81], v[154:157], v[102:105], v[66:81]
	ds_read_b128 v[194:197], v185 offset:36864
	v_add_f32_e32 v193, v193, v48
	v_cvt_pk_bf16_f32 v149, v48, v49
	v_add_f32_e32 v193, v49, v193
	v_exp_f32_e32 v52, v52
	s_waitcnt lgkmcnt(3)
	v_mfma_f32_32x32x16_bf16 v[82:97], v[162:165], v[102:105], v[82:97]
	ds_read_b128 v[154:157], v185 offset:40960
	v_add_f32_e32 v193, v193, v50
	v_exp_f32_e32 v53, v53
	v_cvt_pk_bf16_f32 v142, v50, v51
	v_add_f32_e32 v193, v51, v193
	s_waitcnt lgkmcnt(3)
	v_mfma_f32_32x32x16_bf16 v[66:81], v[166:169], v[106:109], v[66:81]
	ds_read_b128 v[162:165], v187 offset:45056
	v_exp_f32_e32 v54, v54
	v_exp_f32_e32 v55, v55
	v_add_f32_e32 v193, v193, v52
	v_cvt_pk_bf16_f32 v143, v52, v53
	s_waitcnt lgkmcnt(3)
	v_mfma_f32_32x32x16_bf16 v[82:97], v[158:161], v[106:109], v[82:97]
	ds_read_b128 v[198:201], v187 offset:47104
	v_add_f32_e32 v166, v193, v53
	v_exp_f32_e32 v56, v56
	v_exp_f32_e32 v57, v57
	v_add_f32_e32 v166, v54, v166
	s_waitcnt lgkmcnt(3)
	v_mfma_f32_32x32x16_bf16 v[66:81], v[194:197], v[110:113], v[66:81]
	ds_read_b128 v[202:205], v188 offset:45056
	v_cvt_pk_bf16_f32 v144, v54, v55
	v_add_f32_e32 v159, v166, v55
	v_exp_f32_e32 v58, v58
	v_exp_f32_e32 v59, v59
	s_waitcnt lgkmcnt(3)
	v_mfma_f32_32x32x16_bf16 v[82:97], v[154:157], v[110:113], v[82:97]
	ds_read_b128 v[194:197], v188 offset:47104
	v_add_f32_e32 v158, v159, v56
	v_exp_f32_e32 v60, v60
	v_cvt_pk_bf16_f32 v145, v56, v57
	v_add_f32_e32 v158, v57, v158
	s_waitcnt lgkmcnt(3)
	v_mfma_f32_32x32x16_bf16 v[66:81], v[162:165], v[114:117], v[66:81]
	ds_read_b64_tr_b16 v[166:167], v189 offset:32768
	ds_read_b64_tr_b16 v[168:169], v189 offset:33280
	v_add_f32_e32 v154, v158, v58
	v_exp_f32_e32 v61, v61
	v_cvt_pk_bf16_f32 v138, v58, v59
	v_add_f32_e32 v154, v59, v154
	s_waitcnt lgkmcnt(4)
	v_mfma_f32_32x32x16_bf16 v[82:97], v[198:201], v[114:117], v[82:97]
	ds_read_b64_tr_b16 v[162:163], v189 offset:33792
	ds_read_b64_tr_b16 v[164:165], v189 offset:34304
	v_exp_f32_e32 v62, v62
	v_exp_f32_e32 v63, v63
	v_add_f32_e32 v154, v154, v60
	v_cvt_pk_bf16_f32 v139, v60, v61
	s_waitcnt lgkmcnt(5)
	v_mfma_f32_32x32x16_bf16 v[66:81], v[202:205], v[118:121], v[66:81]
	ds_read_b64_tr_b16 v[158:159], v189 offset:34816
	ds_read_b64_tr_b16 v[160:161], v189 offset:35328
	v_add_f32_e32 v154, v154, v61
	v_exp_f32_e32 v64, v64
	v_exp_f32_e32 v65, v65
	v_add_f32_e32 v198, v62, v154
	s_waitcnt lgkmcnt(6)
	v_mfma_f32_32x32x16_bf16 v[82:97], v[194:197], v[118:121], v[82:97]
	ds_read_b64_tr_b16 v[154:155], v189 offset:35840
	ds_read_b64_tr_b16 v[156:157], v189 offset:36352
	v_add_f32_e32 v141, v198, v63
	v_add_f32_e32 v198, v64, v141
	v_cvt_pk_bf16_f32 v140, v62, v63
	v_cvt_pk_bf16_f32 v141, v64, v65
	v_add_f32_e32 v194, v65, v198
	s_waitcnt vmcnt(6) lgkmcnt(0)
	s_barrier
	v_mfma_f32_32x32x16_bf16 v[2:17], v[150:153], v[166:169], v[2:17]
	ds_read_b64_tr_b16 v[34:35], v189 offset:36864
	ds_read_b64_tr_b16 v[36:37], v189 offset:37376
	v_exp_f32_e32 v66, v66
	v_exp_f32_e32 v67, v67
	v_exp_f32_e32 v68, v68
	v_mfma_f32_32x32x16_bf16 v[2:17], v[146:149], v[162:165], v[2:17]
	ds_read_b64_tr_b16 v[38:39], v189 offset:37888
	ds_read_b64_tr_b16 v[40:41], v189 offset:38400
	v_add_f32_e32 v42, v194, v66
	v_exp_f32_e32 v69, v69
	v_cvt_pk_bf16_f32 v134, v66, v67
	v_add_f32_e32 v46, v67, v42
	v_mfma_f32_32x32x16_bf16 v[2:17], v[142:145], v[158:161], v[2:17]
	ds_read_b64_tr_b16 v[42:43], v189 offset:38912
	ds_read_b64_tr_b16 v[44:45], v189 offset:39424
	v_exp_f32_e32 v70, v70
	v_exp_f32_e32 v71, v71
	v_add_f32_e32 v50, v46, v68
	v_cvt_pk_bf16_f32 v135, v68, v69
	v_mfma_f32_32x32x16_bf16 v[2:17], v[138:141], v[154:157], v[2:17]
	ds_read_b64_tr_b16 v[46:47], v189 offset:39936
	ds_read_b64_tr_b16 v[48:49], v189 offset:40448
	v_add_f32_e32 v50, v50, v69
	v_exp_f32_e32 v72, v72
	v_exp_f32_e32 v73, v73
	v_add_f32_e32 v54, v70, v50
	s_waitcnt lgkmcnt(6)
	v_mfma_f32_32x32x16_bf16 v[18:33], v[150:153], v[34:37], v[18:33]
	ds_read_b128 v[50:53], v182
	v_cvt_pk_bf16_f32 v136, v70, v71
	v_add_f32_e32 v58, v54, v71
	v_exp_f32_e32 v74, v74
	v_exp_f32_e32 v75, v75
	s_waitcnt lgkmcnt(5)
	v_mfma_f32_32x32x16_bf16 v[18:33], v[146:149], v[38:41], v[18:33]
	ds_read_b128 v[54:57], v182 offset:4096
	v_add_f32_e32 v34, v58, v72
	v_exp_f32_e32 v76, v76
	v_cvt_pk_bf16_f32 v137, v72, v73
	v_add_f32_e32 v34, v73, v34
	s_waitcnt lgkmcnt(4)
	v_mfma_f32_32x32x16_bf16 v[18:33], v[142:145], v[42:45], v[18:33]
	ds_read_b128 v[154:157], v183
	v_add_f32_e32 v34, v34, v74
	v_exp_f32_e32 v77, v77
	v_cvt_pk_bf16_f32 v130, v74, v75
	v_add_f32_e32 v34, v75, v34
	s_waitcnt lgkmcnt(3)
	v_mfma_f32_32x32x16_bf16 v[18:33], v[138:141], v[46:49], v[18:33]
	ds_read_b128 v[162:165], v183 offset:4096
	v_exp_f32_e32 v78, v78
	v_exp_f32_e32 v79, v79
	v_add_f32_e32 v34, v34, v76
	v_cvt_pk_bf16_f32 v131, v76, v77
	s_nop 0
	v_add_f32_e32 v34, v34, v77
	v_add_f32_e32 v59, v78, v34
	s_waitcnt lgkmcnt(3)
	v_mfma_f32_32x32x16_bf16 v[34:49], v[50:53], v[98:101], 0
	ds_read_b128 v[166:169], v184
	v_exp_f32_e32 v80, v80
	v_exp_f32_e32 v81, v81
	ds_read_b128 v[158:161], v184 offset:4096
	v_add_f32_e32 v193, v59, v79
	s_waitcnt lgkmcnt(4)
	v_mfma_f32_32x32x16_bf16 v[50:65], v[54:57], v[98:101], 0
	s_add_i32 m0, 0x9000, s8
	v_exp_f32_e32 v82, v82
	global_load_lds_dwordx4 v174, s[20:21]
	s_add_i32 m0, m0, 0x2000
	v_exp_f32_e32 v83, v83
	global_load_lds_dwordx4 v192, s[22:23]
	s_add_i32 m0, 0x2000, s12
	v_cvt_pk_bf16_f32 v132, v78, v79
	global_load_lds_dwordx4 v191, s[20:21]
	s_waitcnt lgkmcnt(3)
	v_mfma_f32_32x32x16_bf16 v[34:49], v[154:157], v[102:105], v[34:49]
	ds_read_b128 v[194:197], v185
	v_add_f32_e32 v154, v193, v80
	v_exp_f32_e32 v84, v84
	v_cvt_pk_bf16_f32 v133, v80, v81
	v_add_f32_e32 v193, v81, v154
	s_waitcnt lgkmcnt(3)
	v_mfma_f32_32x32x16_bf16 v[50:65], v[162:165], v[102:105], v[50:65]
	ds_read_b128 v[154:157], v185 offset:4096
	v_add_f32_e32 v193, v193, v82
	v_exp_f32_e32 v85, v85
	v_cvt_pk_bf16_f32 v126, v82, v83
	v_add_f32_e32 v193, v83, v193
	s_waitcnt lgkmcnt(3)
	v_mfma_f32_32x32x16_bf16 v[34:49], v[166:169], v[106:109], v[34:49]
	ds_read_b128 v[162:165], v187 offset:8192
	v_exp_f32_e32 v86, v86
	v_exp_f32_e32 v87, v87
	v_add_f32_e32 v193, v193, v84
	v_cvt_pk_bf16_f32 v127, v84, v85
	s_waitcnt lgkmcnt(3)
	v_mfma_f32_32x32x16_bf16 v[50:65], v[158:161], v[106:109], v[50:65]
	ds_read_b128 v[198:201], v187 offset:10240
	v_add_f32_e32 v166, v193, v85
	v_exp_f32_e32 v88, v88
	v_exp_f32_e32 v89, v89
	v_add_f32_e32 v166, v86, v166
	s_waitcnt lgkmcnt(3)
	v_mfma_f32_32x32x16_bf16 v[34:49], v[194:197], v[110:113], v[34:49]
	ds_read_b128 v[202:205], v188 offset:8192
	v_cvt_pk_bf16_f32 v128, v86, v87
	v_add_f32_e32 v159, v166, v87
	v_exp_f32_e32 v90, v90
	v_exp_f32_e32 v91, v91
	s_waitcnt lgkmcnt(3)
	v_mfma_f32_32x32x16_bf16 v[50:65], v[154:157], v[110:113], v[50:65]
	ds_read_b128 v[194:197], v188 offset:10240
	v_add_f32_e32 v158, v159, v88
	v_exp_f32_e32 v92, v92
	v_cvt_pk_bf16_f32 v129, v88, v89
	v_add_f32_e32 v158, v89, v158
	s_waitcnt lgkmcnt(3)
	v_mfma_f32_32x32x16_bf16 v[34:49], v[162:165], v[114:117], v[34:49]
	ds_read_b64_tr_b16 v[166:167], v189 offset:40960
	ds_read_b64_tr_b16 v[168:169], v189 offset:41472
	v_add_f32_e32 v154, v158, v90
	v_exp_f32_e32 v93, v93
	v_cvt_pk_bf16_f32 v122, v90, v91
	v_add_f32_e32 v154, v91, v154
	s_waitcnt lgkmcnt(4)
	v_mfma_f32_32x32x16_bf16 v[50:65], v[198:201], v[114:117], v[50:65]
	ds_read_b64_tr_b16 v[162:163], v189 offset:41984
	ds_read_b64_tr_b16 v[164:165], v189 offset:42496
	v_exp_f32_e32 v94, v94
	v_exp_f32_e32 v95, v95
	v_add_f32_e32 v154, v154, v92
	v_cvt_pk_bf16_f32 v123, v92, v93
	s_waitcnt lgkmcnt(5)
	v_mfma_f32_32x32x16_bf16 v[34:49], v[202:205], v[118:121], v[34:49]
	ds_read_b64_tr_b16 v[158:159], v189 offset:43008
	ds_read_b64_tr_b16 v[160:161], v189 offset:43520
	v_add_f32_e32 v154, v154, v93
	v_exp_f32_e32 v96, v96
	v_exp_f32_e32 v97, v97
	v_add_f32_e32 v193, v94, v154
	s_waitcnt lgkmcnt(6)
	v_mfma_f32_32x32x16_bf16 v[50:65], v[194:197], v[118:121], v[50:65]
	ds_read_b64_tr_b16 v[154:155], v189 offset:44032
	ds_read_b64_tr_b16 v[156:157], v189 offset:44544
	v_add_f32_e32 v125, v193, v95
	v_add_f32_e32 v193, v96, v125
	v_cvt_pk_bf16_f32 v124, v94, v95
	v_cvt_pk_bf16_f32 v125, v96, v97
	v_add_f32_e32 v193, v97, v193
	s_add_u32 s22, s22, 0x2000
	s_addc_u32 s23, s23, 0
	s_add_u32 s20, s20, 0x40000
	s_addc_u32 s21, s21, 0
	s_waitcnt vmcnt(6) lgkmcnt(0)
	s_barrier
	v_mfma_f32_32x32x16_bf16 v[2:17], v[134:137], v[166:169], v[2:17]
	ds_read_b64_tr_b16 v[66:67], v189 offset:45056
	ds_read_b64_tr_b16 v[68:69], v189 offset:45568
	v_exp_f32_e32 v34, v34
	v_exp_f32_e32 v35, v35
	v_exp_f32_e32 v36, v36
	v_mfma_f32_32x32x16_bf16 v[2:17], v[130:133], v[162:165], v[2:17]
	ds_read_b64_tr_b16 v[70:71], v189 offset:46080
	ds_read_b64_tr_b16 v[72:73], v189 offset:46592
	v_add_f32_e32 v74, v193, v34
	v_exp_f32_e32 v37, v37
	v_cvt_pk_bf16_f32 v150, v34, v35
	v_add_f32_e32 v78, v35, v74
	v_mfma_f32_32x32x16_bf16 v[2:17], v[126:129], v[158:161], v[2:17]
	ds_read_b64_tr_b16 v[74:75], v189 offset:47104
	ds_read_b64_tr_b16 v[76:77], v189 offset:47616
	v_exp_f32_e32 v38, v38
	v_exp_f32_e32 v39, v39
	v_add_f32_e32 v82, v78, v36
	v_cvt_pk_bf16_f32 v151, v36, v37
	v_mfma_f32_32x32x16_bf16 v[2:17], v[122:125], v[154:157], v[2:17]
	ds_read_b64_tr_b16 v[78:79], v189 offset:48128
	ds_read_b64_tr_b16 v[80:81], v189 offset:48640
	v_add_f32_e32 v82, v82, v37
	v_exp_f32_e32 v40, v40
	v_exp_f32_e32 v41, v41
	v_add_f32_e32 v86, v38, v82
	s_waitcnt lgkmcnt(6)
	v_mfma_f32_32x32x16_bf16 v[18:33], v[134:137], v[66:69], v[18:33]
	ds_read_b128 v[82:85], v182 offset:12288
	v_cvt_pk_bf16_f32 v152, v38, v39
	v_add_f32_e32 v90, v86, v39
	v_exp_f32_e32 v42, v42
	v_exp_f32_e32 v43, v43
	s_waitcnt lgkmcnt(5)
	v_mfma_f32_32x32x16_bf16 v[18:33], v[130:133], v[70:73], v[18:33]
	ds_read_b128 v[86:89], v182 offset:16384
	v_add_f32_e32 v66, v90, v40
	v_exp_f32_e32 v44, v44
	v_cvt_pk_bf16_f32 v153, v40, v41
	v_add_f32_e32 v66, v41, v66
	s_waitcnt lgkmcnt(4)
	v_mfma_f32_32x32x16_bf16 v[18:33], v[126:129], v[74:77], v[18:33]
	ds_read_b128 v[154:157], v183 offset:12288
	v_add_f32_e32 v66, v66, v42
	v_exp_f32_e32 v45, v45
	v_cvt_pk_bf16_f32 v146, v42, v43
	v_add_f32_e32 v66, v43, v66
	s_waitcnt lgkmcnt(3)
	v_mfma_f32_32x32x16_bf16 v[18:33], v[122:125], v[78:81], v[18:33]
	ds_read_b128 v[162:165], v183 offset:16384
	v_exp_f32_e32 v46, v46
	v_exp_f32_e32 v47, v47
	v_add_f32_e32 v66, v66, v44
	v_cvt_pk_bf16_f32 v147, v44, v45
	s_nop 0
	v_add_f32_e32 v66, v66, v45
	v_add_f32_e32 v91, v46, v66
	s_waitcnt lgkmcnt(3)
	v_mfma_f32_32x32x16_bf16 v[66:81], v[82:85], v[98:101], 0
	ds_read_b128 v[166:169], v184 offset:12288
	v_exp_f32_e32 v48, v48
	v_exp_f32_e32 v49, v49
	ds_read_b128 v[158:161], v184 offset:16384
	v_add_f32_e32 v193, v91, v47
	s_waitcnt lgkmcnt(4)
	v_mfma_f32_32x32x16_bf16 v[82:97], v[86:89], v[98:101], 0
	s_add_u32 s26, s20, 0xfffe0000
	s_addc_u32 s27, s21, -1
	s_add_u32 s28, s22, 0xfffff000
	s_addc_u32 s29, s23, -1
	s_mov_b32 m0, s8
	v_exp_f32_e32 v50, v50
	global_load_lds_dwordx4 v174, s[26:27]
	s_add_i32 m0, m0, 0x2000
	v_exp_f32_e32 v51, v51
	global_load_lds_dwordx4 v192, s[28:29]
	s_add_i32 m0, 0x4000, s12
	v_cvt_pk_bf16_f32 v148, v46, v47
	global_load_lds_dwordx4 v191, s[26:27]
	s_waitcnt lgkmcnt(3)
	v_mfma_f32_32x32x16_bf16 v[66:81], v[154:157], v[102:105], v[66:81]
	ds_read_b128 v[194:197], v185 offset:12288
	v_add_f32_e32 v193, v193, v48
	v_cvt_pk_bf16_f32 v149, v48, v49
	v_add_f32_e32 v193, v49, v193
	v_exp_f32_e32 v52, v52
	s_waitcnt lgkmcnt(3)
	v_mfma_f32_32x32x16_bf16 v[82:97], v[162:165], v[102:105], v[82:97]
	ds_read_b128 v[154:157], v185 offset:16384
	v_add_f32_e32 v193, v193, v50
	v_exp_f32_e32 v53, v53
	v_cvt_pk_bf16_f32 v142, v50, v51
	v_add_f32_e32 v193, v51, v193
	s_waitcnt lgkmcnt(3)
	v_mfma_f32_32x32x16_bf16 v[66:81], v[166:169], v[106:109], v[66:81]
	ds_read_b128 v[162:165], v187 offset:20480
	v_exp_f32_e32 v54, v54
	v_exp_f32_e32 v55, v55
	v_add_f32_e32 v193, v193, v52
	v_cvt_pk_bf16_f32 v143, v52, v53
	s_waitcnt lgkmcnt(3)
	v_mfma_f32_32x32x16_bf16 v[82:97], v[158:161], v[106:109], v[82:97]
	ds_read_b128 v[198:201], v187 offset:22528
	v_add_f32_e32 v166, v193, v53
	v_exp_f32_e32 v56, v56
	v_exp_f32_e32 v57, v57
	v_add_f32_e32 v166, v54, v166
	s_waitcnt lgkmcnt(3)
	v_mfma_f32_32x32x16_bf16 v[66:81], v[194:197], v[110:113], v[66:81]
	ds_read_b128 v[202:205], v188 offset:20480
	v_cvt_pk_bf16_f32 v144, v54, v55
	v_add_f32_e32 v159, v166, v55
	v_exp_f32_e32 v58, v58
	v_exp_f32_e32 v59, v59
	s_waitcnt lgkmcnt(3)
	v_mfma_f32_32x32x16_bf16 v[82:97], v[154:157], v[110:113], v[82:97]
	ds_read_b128 v[194:197], v188 offset:22528
	v_add_f32_e32 v158, v159, v56
	v_exp_f32_e32 v60, v60
	v_cvt_pk_bf16_f32 v145, v56, v57
	v_add_f32_e32 v158, v57, v158
	s_waitcnt lgkmcnt(3)
	v_mfma_f32_32x32x16_bf16 v[66:81], v[162:165], v[114:117], v[66:81]
	ds_read_b64_tr_b16 v[166:167], v189 offset:49152
	ds_read_b64_tr_b16 v[168:169], v189 offset:49664
	v_add_f32_e32 v154, v158, v58
	v_exp_f32_e32 v61, v61
	v_cvt_pk_bf16_f32 v138, v58, v59
	v_add_f32_e32 v154, v59, v154
	s_waitcnt lgkmcnt(4)
	v_mfma_f32_32x32x16_bf16 v[82:97], v[198:201], v[114:117], v[82:97]
	ds_read_b64_tr_b16 v[162:163], v189 offset:50176
	ds_read_b64_tr_b16 v[164:165], v189 offset:50688
	v_exp_f32_e32 v62, v62
	v_exp_f32_e32 v63, v63
	v_add_f32_e32 v154, v154, v60
	v_cvt_pk_bf16_f32 v139, v60, v61
	s_waitcnt lgkmcnt(5)
	v_mfma_f32_32x32x16_bf16 v[66:81], v[202:205], v[118:121], v[66:81]
	ds_read_b64_tr_b16 v[158:159], v189 offset:51200
	ds_read_b64_tr_b16 v[160:161], v189 offset:51712
	v_add_f32_e32 v154, v154, v61
	v_exp_f32_e32 v64, v64
	v_exp_f32_e32 v65, v65
	v_add_f32_e32 v198, v62, v154
	s_waitcnt lgkmcnt(6)
	v_mfma_f32_32x32x16_bf16 v[82:97], v[194:197], v[118:121], v[82:97]
	ds_read_b64_tr_b16 v[154:155], v189 offset:52224
	ds_read_b64_tr_b16 v[156:157], v189 offset:52736
	v_add_f32_e32 v141, v198, v63
	v_add_f32_e32 v198, v64, v141
	v_cvt_pk_bf16_f32 v140, v62, v63
	v_cvt_pk_bf16_f32 v141, v64, v65
	v_add_f32_e32 v194, v65, v198
	s_waitcnt vmcnt(6) lgkmcnt(0)
	s_barrier
	v_mfma_f32_32x32x16_bf16 v[2:17], v[150:153], v[166:169], v[2:17]
	ds_read_b64_tr_b16 v[34:35], v189 offset:53248
	ds_read_b64_tr_b16 v[36:37], v189 offset:53760
	v_exp_f32_e32 v66, v66
	v_exp_f32_e32 v67, v67
	v_exp_f32_e32 v68, v68
	v_mfma_f32_32x32x16_bf16 v[2:17], v[146:149], v[162:165], v[2:17]
	ds_read_b64_tr_b16 v[38:39], v189 offset:54272
	ds_read_b64_tr_b16 v[40:41], v189 offset:54784
	v_add_f32_e32 v42, v194, v66
	v_exp_f32_e32 v69, v69
	v_cvt_pk_bf16_f32 v134, v66, v67
	v_add_f32_e32 v46, v67, v42
	v_mfma_f32_32x32x16_bf16 v[2:17], v[142:145], v[158:161], v[2:17]
	ds_read_b64_tr_b16 v[42:43], v189 offset:55296
	ds_read_b64_tr_b16 v[44:45], v189 offset:55808
	v_exp_f32_e32 v70, v70
	v_exp_f32_e32 v71, v71
	v_add_f32_e32 v50, v46, v68
	v_cvt_pk_bf16_f32 v135, v68, v69
	v_mfma_f32_32x32x16_bf16 v[2:17], v[138:141], v[154:157], v[2:17]
	ds_read_b64_tr_b16 v[46:47], v189 offset:56320
	ds_read_b64_tr_b16 v[48:49], v189 offset:56832
	v_add_f32_e32 v50, v50, v69
	v_exp_f32_e32 v72, v72
	v_exp_f32_e32 v73, v73
	v_add_f32_e32 v54, v70, v50
	s_waitcnt lgkmcnt(6)
	v_mfma_f32_32x32x16_bf16 v[18:33], v[150:153], v[34:37], v[18:33]
	ds_read_b128 v[50:53], v182 offset:24576
	v_cvt_pk_bf16_f32 v136, v70, v71
	v_add_f32_e32 v58, v54, v71
	v_exp_f32_e32 v74, v74
	v_exp_f32_e32 v75, v75
	s_waitcnt lgkmcnt(5)
	v_mfma_f32_32x32x16_bf16 v[18:33], v[146:149], v[38:41], v[18:33]
	ds_read_b128 v[54:57], v182 offset:28672
	v_add_f32_e32 v34, v58, v72
	v_exp_f32_e32 v76, v76
	v_cvt_pk_bf16_f32 v137, v72, v73
	v_add_f32_e32 v34, v73, v34
	s_waitcnt lgkmcnt(4)
	v_mfma_f32_32x32x16_bf16 v[18:33], v[142:145], v[42:45], v[18:33]
	ds_read_b128 v[154:157], v183 offset:24576
	v_add_f32_e32 v34, v34, v74
	v_exp_f32_e32 v77, v77
	v_cvt_pk_bf16_f32 v130, v74, v75
	v_add_f32_e32 v34, v75, v34
	s_waitcnt lgkmcnt(3)
	v_mfma_f32_32x32x16_bf16 v[18:33], v[138:141], v[46:49], v[18:33]
	ds_read_b128 v[162:165], v183 offset:28672
	v_exp_f32_e32 v78, v78
	v_exp_f32_e32 v79, v79
	v_add_f32_e32 v34, v34, v76
	v_cvt_pk_bf16_f32 v131, v76, v77
	s_nop 0
	v_add_f32_e32 v34, v34, v77
	v_add_f32_e32 v59, v78, v34
	s_waitcnt lgkmcnt(3)
	v_mfma_f32_32x32x16_bf16 v[34:49], v[50:53], v[98:101], 0
	ds_read_b128 v[166:169], v184 offset:24576
	v_exp_f32_e32 v80, v80
	v_exp_f32_e32 v81, v81
	ds_read_b128 v[158:161], v184 offset:28672
	v_add_f32_e32 v193, v59, v79
	s_waitcnt lgkmcnt(4)
	v_mfma_f32_32x32x16_bf16 v[50:65], v[54:57], v[98:101], 0
	s_add_i32 m0, 0x3000, s8
	v_exp_f32_e32 v82, v82
	global_load_lds_dwordx4 v174, s[20:21]
	s_add_i32 m0, m0, 0x2000
	v_exp_f32_e32 v83, v83
	global_load_lds_dwordx4 v192, s[22:23]
	s_add_i32 m0, 0x6000, s12
	v_cvt_pk_bf16_f32 v132, v78, v79
	global_load_lds_dwordx4 v191, s[20:21]
	s_waitcnt lgkmcnt(3)
	v_mfma_f32_32x32x16_bf16 v[34:49], v[154:157], v[102:105], v[34:49]
	ds_read_b128 v[194:197], v185 offset:24576
	v_add_f32_e32 v154, v193, v80
	v_exp_f32_e32 v84, v84
	v_cvt_pk_bf16_f32 v133, v80, v81
	v_add_f32_e32 v193, v81, v154
	s_waitcnt lgkmcnt(3)
	v_mfma_f32_32x32x16_bf16 v[50:65], v[162:165], v[102:105], v[50:65]
	ds_read_b128 v[154:157], v185 offset:28672
	v_add_f32_e32 v193, v193, v82
	v_exp_f32_e32 v85, v85
	v_cvt_pk_bf16_f32 v126, v82, v83
	v_add_f32_e32 v193, v83, v193
	s_waitcnt lgkmcnt(3)
	v_mfma_f32_32x32x16_bf16 v[34:49], v[166:169], v[106:109], v[34:49]
	ds_read_b128 v[162:165], v187 offset:32768
	v_exp_f32_e32 v86, v86
	v_exp_f32_e32 v87, v87
	v_add_f32_e32 v193, v193, v84
	v_cvt_pk_bf16_f32 v127, v84, v85
	s_waitcnt lgkmcnt(3)
	v_mfma_f32_32x32x16_bf16 v[50:65], v[158:161], v[106:109], v[50:65]
	ds_read_b128 v[198:201], v187 offset:34816
	v_add_f32_e32 v166, v193, v85
	v_exp_f32_e32 v88, v88
	v_exp_f32_e32 v89, v89
	v_add_f32_e32 v166, v86, v166
	s_waitcnt lgkmcnt(3)
	v_mfma_f32_32x32x16_bf16 v[34:49], v[194:197], v[110:113], v[34:49]
	ds_read_b128 v[202:205], v188 offset:32768
	v_cvt_pk_bf16_f32 v128, v86, v87
	v_add_f32_e32 v159, v166, v87
	v_exp_f32_e32 v90, v90
	v_exp_f32_e32 v91, v91
	s_waitcnt lgkmcnt(3)
	v_mfma_f32_32x32x16_bf16 v[50:65], v[154:157], v[110:113], v[50:65]
	ds_read_b128 v[194:197], v188 offset:34816
	v_add_f32_e32 v158, v159, v88
	v_exp_f32_e32 v92, v92
	v_cvt_pk_bf16_f32 v129, v88, v89
	v_add_f32_e32 v158, v89, v158
	s_waitcnt lgkmcnt(3)
	v_mfma_f32_32x32x16_bf16 v[34:49], v[162:165], v[114:117], v[34:49]
	ds_read_b64_tr_b16 v[166:167], v189 offset:57344
	ds_read_b64_tr_b16 v[168:169], v189 offset:57856
	v_add_f32_e32 v154, v158, v90
	v_exp_f32_e32 v93, v93
	v_cvt_pk_bf16_f32 v122, v90, v91
	v_add_f32_e32 v154, v91, v154
	s_waitcnt lgkmcnt(4)
	v_mfma_f32_32x32x16_bf16 v[50:65], v[198:201], v[114:117], v[50:65]
	ds_read_b64_tr_b16 v[162:163], v189 offset:58368
	ds_read_b64_tr_b16 v[164:165], v189 offset:58880
	v_exp_f32_e32 v94, v94
	v_exp_f32_e32 v95, v95
	v_add_f32_e32 v154, v154, v92
	v_cvt_pk_bf16_f32 v123, v92, v93
	s_waitcnt lgkmcnt(5)
	v_mfma_f32_32x32x16_bf16 v[34:49], v[202:205], v[118:121], v[34:49]
	ds_read_b64_tr_b16 v[158:159], v189 offset:59392
	ds_read_b64_tr_b16 v[160:161], v189 offset:59904
	v_add_f32_e32 v154, v154, v93
	v_exp_f32_e32 v96, v96
	v_exp_f32_e32 v97, v97
	v_add_f32_e32 v193, v94, v154
	s_waitcnt lgkmcnt(6)
	v_mfma_f32_32x32x16_bf16 v[50:65], v[194:197], v[118:121], v[50:65]
	ds_read_b64_tr_b16 v[154:155], v189 offset:60416
	ds_read_b64_tr_b16 v[156:157], v189 offset:60928
	v_add_f32_e32 v125, v193, v95
	v_add_f32_e32 v193, v96, v125
	v_cvt_pk_bf16_f32 v124, v94, v95
	v_cvt_pk_bf16_f32 v125, v96, v97
	v_add_f32_e32 v193, v97, v193
	s_add_u32 s22, s22, 0x2000
	s_addc_u32 s23, s23, 0
	s_add_u32 s20, s20, 0x40000
	s_addc_u32 s21, s21, 0
	s_waitcnt vmcnt(6) lgkmcnt(0)
	s_barrier
	v_mfma_f32_32x32x16_bf16 v[2:17], v[134:137], v[166:169], v[2:17]
	ds_read_b64_tr_b16 v[66:67], v189 offset:61440
	ds_read_b64_tr_b16 v[68:69], v189 offset:61952
	v_exp_f32_e32 v34, v34
	v_exp_f32_e32 v35, v35
	v_exp_f32_e32 v36, v36
	v_mfma_f32_32x32x16_bf16 v[2:17], v[130:133], v[162:165], v[2:17]
	ds_read_b64_tr_b16 v[70:71], v189 offset:62464
	ds_read_b64_tr_b16 v[72:73], v189 offset:62976
	v_add_f32_e32 v74, v193, v34
	v_exp_f32_e32 v37, v37
	v_cvt_pk_bf16_f32 v150, v34, v35
	v_add_f32_e32 v78, v35, v74
	v_mfma_f32_32x32x16_bf16 v[2:17], v[126:129], v[158:161], v[2:17]
	ds_read_b64_tr_b16 v[74:75], v189 offset:63488
	ds_read_b64_tr_b16 v[76:77], v189 offset:64000
	v_exp_f32_e32 v38, v38
	v_exp_f32_e32 v39, v39
	v_add_f32_e32 v82, v78, v36
	v_cvt_pk_bf16_f32 v151, v36, v37
	v_mfma_f32_32x32x16_bf16 v[2:17], v[122:125], v[154:157], v[2:17]
	ds_read_b64_tr_b16 v[78:79], v189 offset:64512
	ds_read_b64_tr_b16 v[80:81], v189 offset:65024
	v_add_f32_e32 v82, v82, v37
	v_exp_f32_e32 v40, v40
	v_exp_f32_e32 v41, v41
	v_add_f32_e32 v86, v38, v82
	s_waitcnt lgkmcnt(6)
	v_mfma_f32_32x32x16_bf16 v[18:33], v[134:137], v[66:69], v[18:33]
	ds_read_b128 v[82:85], v182 offset:36864
	v_cvt_pk_bf16_f32 v152, v38, v39
	v_add_f32_e32 v90, v86, v39
	v_exp_f32_e32 v42, v42
	v_exp_f32_e32 v43, v43
	s_waitcnt lgkmcnt(5)
	v_mfma_f32_32x32x16_bf16 v[18:33], v[130:133], v[70:73], v[18:33]
	ds_read_b128 v[86:89], v182 offset:40960
	v_add_f32_e32 v66, v90, v40
	v_exp_f32_e32 v44, v44
	v_cvt_pk_bf16_f32 v153, v40, v41
	v_add_f32_e32 v66, v41, v66
	s_waitcnt lgkmcnt(4)
	v_mfma_f32_32x32x16_bf16 v[18:33], v[126:129], v[74:77], v[18:33]
	ds_read_b128 v[154:157], v183 offset:36864
	v_add_f32_e32 v66, v66, v42
	v_exp_f32_e32 v45, v45
	v_cvt_pk_bf16_f32 v146, v42, v43
	v_add_f32_e32 v66, v43, v66
	s_waitcnt lgkmcnt(3)
	v_mfma_f32_32x32x16_bf16 v[18:33], v[122:125], v[78:81], v[18:33]
	ds_read_b128 v[162:165], v183 offset:40960
	v_exp_f32_e32 v46, v46
	v_exp_f32_e32 v47, v47
	v_add_f32_e32 v66, v66, v44
	v_cvt_pk_bf16_f32 v147, v44, v45
	s_nop 0
	v_add_f32_e32 v66, v66, v45
	v_add_f32_e32 v91, v46, v66
	s_waitcnt lgkmcnt(3)
	v_mfma_f32_32x32x16_bf16 v[66:81], v[82:85], v[98:101], 0
	ds_read_b128 v[166:169], v184 offset:36864
	v_exp_f32_e32 v48, v48
	v_exp_f32_e32 v49, v49
	ds_read_b128 v[158:161], v184 offset:40960
	v_add_f32_e32 v193, v91, v47
	s_waitcnt lgkmcnt(4)
	v_mfma_f32_32x32x16_bf16 v[82:97], v[86:89], v[98:101], 0
	s_add_u32 s26, s20, 0xfffe0000
	s_addc_u32 s27, s21, -1
	s_add_u32 s28, s22, 0xfffff000
	s_addc_u32 s29, s23, -1
	s_add_i32 m0, 0x6000, s8
	v_exp_f32_e32 v50, v50
	global_load_lds_dwordx4 v174, s[26:27]
	s_add_i32 m0, m0, 0x2000
	v_exp_f32_e32 v51, v51
	global_load_lds_dwordx4 v192, s[28:29]
	s_add_i32 m0, 0x8000, s12
	v_cvt_pk_bf16_f32 v148, v46, v47
	global_load_lds_dwordx4 v191, s[26:27]
	s_waitcnt lgkmcnt(3)
	v_mfma_f32_32x32x16_bf16 v[66:81], v[154:157], v[102:105], v[66:81]
	ds_read_b128 v[194:197], v185 offset:36864
	v_add_f32_e32 v193, v193, v48
	v_cvt_pk_bf16_f32 v149, v48, v49
	v_add_f32_e32 v193, v49, v193
	v_exp_f32_e32 v52, v52
	s_waitcnt lgkmcnt(3)
	v_mfma_f32_32x32x16_bf16 v[82:97], v[162:165], v[102:105], v[82:97]
	ds_read_b128 v[154:157], v185 offset:40960
	v_add_f32_e32 v193, v193, v50
	v_exp_f32_e32 v53, v53
	v_cvt_pk_bf16_f32 v142, v50, v51
	v_add_f32_e32 v193, v51, v193
	s_waitcnt lgkmcnt(3)
	v_mfma_f32_32x32x16_bf16 v[66:81], v[166:169], v[106:109], v[66:81]
	ds_read_b128 v[162:165], v187 offset:45056
	v_exp_f32_e32 v54, v54
	v_exp_f32_e32 v55, v55
	v_add_f32_e32 v193, v193, v52
	v_cvt_pk_bf16_f32 v143, v52, v53
	s_waitcnt lgkmcnt(3)
	v_mfma_f32_32x32x16_bf16 v[82:97], v[158:161], v[106:109], v[82:97]
	ds_read_b128 v[198:201], v187 offset:47104
	v_add_f32_e32 v166, v193, v53
	v_exp_f32_e32 v56, v56
	v_exp_f32_e32 v57, v57
	v_add_f32_e32 v166, v54, v166
	s_waitcnt lgkmcnt(3)
	v_mfma_f32_32x32x16_bf16 v[66:81], v[194:197], v[110:113], v[66:81]
	ds_read_b128 v[202:205], v188 offset:45056
	v_cvt_pk_bf16_f32 v144, v54, v55
	v_add_f32_e32 v159, v166, v55
	v_exp_f32_e32 v58, v58
	v_exp_f32_e32 v59, v59
	s_waitcnt lgkmcnt(3)
	v_mfma_f32_32x32x16_bf16 v[82:97], v[154:157], v[110:113], v[82:97]
	ds_read_b128 v[194:197], v188 offset:47104
	v_add_f32_e32 v158, v159, v56
	v_exp_f32_e32 v60, v60
	v_cvt_pk_bf16_f32 v145, v56, v57
	v_add_f32_e32 v158, v57, v158
	s_waitcnt lgkmcnt(3)
	v_mfma_f32_32x32x16_bf16 v[66:81], v[162:165], v[114:117], v[66:81]
	ds_read_b64_tr_b16 v[166:167], v189 offset:16384
	ds_read_b64_tr_b16 v[168:169], v189 offset:16896
	v_add_f32_e32 v154, v158, v58
	v_exp_f32_e32 v61, v61
	v_cvt_pk_bf16_f32 v138, v58, v59
	v_add_f32_e32 v154, v59, v154
	s_waitcnt lgkmcnt(4)
	v_mfma_f32_32x32x16_bf16 v[82:97], v[198:201], v[114:117], v[82:97]
	ds_read_b64_tr_b16 v[162:163], v189 offset:17408
	ds_read_b64_tr_b16 v[164:165], v189 offset:17920
	v_exp_f32_e32 v62, v62
	v_exp_f32_e32 v63, v63
	v_add_f32_e32 v154, v154, v60
	v_cvt_pk_bf16_f32 v139, v60, v61
	s_waitcnt lgkmcnt(5)
	v_mfma_f32_32x32x16_bf16 v[66:81], v[202:205], v[118:121], v[66:81]
	ds_read_b64_tr_b16 v[158:159], v189 offset:18432
	ds_read_b64_tr_b16 v[160:161], v189 offset:18944
	v_add_f32_e32 v154, v154, v61
	v_exp_f32_e32 v64, v64
	v_exp_f32_e32 v65, v65
	v_add_f32_e32 v198, v62, v154
	s_waitcnt lgkmcnt(6)
	v_mfma_f32_32x32x16_bf16 v[82:97], v[194:197], v[118:121], v[82:97]
	ds_read_b64_tr_b16 v[154:155], v189 offset:19456
	ds_read_b64_tr_b16 v[156:157], v189 offset:19968
	v_add_f32_e32 v141, v198, v63
	v_add_f32_e32 v198, v64, v141
	v_cvt_pk_bf16_f32 v140, v62, v63
	v_cvt_pk_bf16_f32 v141, v64, v65
	v_add_f32_e32 v194, v65, v198
	s_waitcnt vmcnt(6) lgkmcnt(0)
	s_barrier
	v_mfma_f32_32x32x16_bf16 v[2:17], v[150:153], v[166:169], v[2:17]
	ds_read_b64_tr_b16 v[34:35], v189 offset:20480
	ds_read_b64_tr_b16 v[36:37], v189 offset:20992
	v_exp_f32_e32 v66, v66
	v_exp_f32_e32 v67, v67
	v_exp_f32_e32 v68, v68
	v_mfma_f32_32x32x16_bf16 v[2:17], v[146:149], v[162:165], v[2:17]
	ds_read_b64_tr_b16 v[38:39], v189 offset:21504
	ds_read_b64_tr_b16 v[40:41], v189 offset:22016
	v_add_f32_e32 v42, v194, v66
	v_exp_f32_e32 v69, v69
	v_cvt_pk_bf16_f32 v134, v66, v67
	v_add_f32_e32 v46, v67, v42
	v_mfma_f32_32x32x16_bf16 v[2:17], v[142:145], v[158:161], v[2:17]
	ds_read_b64_tr_b16 v[42:43], v189 offset:22528
	ds_read_b64_tr_b16 v[44:45], v189 offset:23040
	v_exp_f32_e32 v70, v70
	v_exp_f32_e32 v71, v71
	v_add_f32_e32 v50, v46, v68
	v_cvt_pk_bf16_f32 v135, v68, v69
	v_mfma_f32_32x32x16_bf16 v[2:17], v[138:141], v[154:157], v[2:17]
	ds_read_b64_tr_b16 v[46:47], v189 offset:23552
	ds_read_b64_tr_b16 v[48:49], v189 offset:24064
	v_add_f32_e32 v50, v50, v69
	v_exp_f32_e32 v72, v72
	v_exp_f32_e32 v73, v73
	v_add_f32_e32 v54, v70, v50
	s_waitcnt lgkmcnt(6)
	v_mfma_f32_32x32x16_bf16 v[18:33], v[150:153], v[34:37], v[18:33]
	ds_read_b128 v[50:53], v182
	v_cvt_pk_bf16_f32 v136, v70, v71
	v_add_f32_e32 v58, v54, v71
	v_exp_f32_e32 v74, v74
	v_exp_f32_e32 v75, v75
	s_waitcnt lgkmcnt(5)
	v_mfma_f32_32x32x16_bf16 v[18:33], v[146:149], v[38:41], v[18:33]
	ds_read_b128 v[54:57], v182 offset:4096
	v_add_f32_e32 v34, v58, v72
	v_exp_f32_e32 v76, v76
	v_cvt_pk_bf16_f32 v137, v72, v73
	v_add_f32_e32 v34, v73, v34
	s_waitcnt lgkmcnt(4)
	v_mfma_f32_32x32x16_bf16 v[18:33], v[142:145], v[42:45], v[18:33]
	ds_read_b128 v[154:157], v183
	v_add_f32_e32 v34, v34, v74
	v_exp_f32_e32 v77, v77
	v_cvt_pk_bf16_f32 v130, v74, v75
	v_add_f32_e32 v34, v75, v34
	s_waitcnt lgkmcnt(3)
	v_mfma_f32_32x32x16_bf16 v[18:33], v[138:141], v[46:49], v[18:33]
	ds_read_b128 v[162:165], v183 offset:4096
	v_exp_f32_e32 v78, v78
	v_exp_f32_e32 v79, v79
	v_add_f32_e32 v34, v34, v76
	v_cvt_pk_bf16_f32 v131, v76, v77
	s_nop 0
	v_add_f32_e32 v34, v34, v77
	v_add_f32_e32 v59, v78, v34
	s_waitcnt lgkmcnt(3)
	v_mfma_f32_32x32x16_bf16 v[34:49], v[50:53], v[98:101], 0
	ds_read_b128 v[166:169], v184
	v_exp_f32_e32 v80, v80
	v_exp_f32_e32 v81, v81
	ds_read_b128 v[158:161], v184 offset:4096
	v_add_f32_e32 v193, v59, v79
	s_waitcnt lgkmcnt(4)
	v_mfma_f32_32x32x16_bf16 v[50:65], v[54:57], v[98:101], 0
	s_add_i32 m0, 0x9000, s8
	v_exp_f32_e32 v82, v82
	global_load_lds_dwordx4 v174, s[20:21]
	s_add_i32 m0, m0, 0x2000
	v_exp_f32_e32 v83, v83
	global_load_lds_dwordx4 v192, s[22:23]
	s_add_i32 m0, 0xa000, s12
	v_cvt_pk_bf16_f32 v132, v78, v79
	global_load_lds_dwordx4 v191, s[20:21]
	s_waitcnt lgkmcnt(3)
	v_mfma_f32_32x32x16_bf16 v[34:49], v[154:157], v[102:105], v[34:49]
	ds_read_b128 v[194:197], v185
	v_add_f32_e32 v154, v193, v80
	v_exp_f32_e32 v84, v84
	v_cvt_pk_bf16_f32 v133, v80, v81
	v_add_f32_e32 v193, v81, v154
	s_waitcnt lgkmcnt(3)
	v_mfma_f32_32x32x16_bf16 v[50:65], v[162:165], v[102:105], v[50:65]
	ds_read_b128 v[154:157], v185 offset:4096
	v_add_f32_e32 v193, v193, v82
	v_exp_f32_e32 v85, v85
	v_cvt_pk_bf16_f32 v126, v82, v83
	v_add_f32_e32 v193, v83, v193
	s_waitcnt lgkmcnt(3)
	v_mfma_f32_32x32x16_bf16 v[34:49], v[166:169], v[106:109], v[34:49]
	ds_read_b128 v[162:165], v187 offset:8192
	v_exp_f32_e32 v86, v86
	v_exp_f32_e32 v87, v87
	v_add_f32_e32 v193, v193, v84
	v_cvt_pk_bf16_f32 v127, v84, v85
	s_waitcnt lgkmcnt(3)
	v_mfma_f32_32x32x16_bf16 v[50:65], v[158:161], v[106:109], v[50:65]
	ds_read_b128 v[198:201], v187 offset:10240
	v_add_f32_e32 v166, v193, v85
	v_exp_f32_e32 v88, v88
	v_exp_f32_e32 v89, v89
	v_add_f32_e32 v166, v86, v166
	s_waitcnt lgkmcnt(3)
	v_mfma_f32_32x32x16_bf16 v[34:49], v[194:197], v[110:113], v[34:49]
	ds_read_b128 v[202:205], v188 offset:8192
	v_cvt_pk_bf16_f32 v128, v86, v87
	v_add_f32_e32 v159, v166, v87
	v_exp_f32_e32 v90, v90
	v_exp_f32_e32 v91, v91
	s_waitcnt lgkmcnt(3)
	v_mfma_f32_32x32x16_bf16 v[50:65], v[154:157], v[110:113], v[50:65]
	ds_read_b128 v[194:197], v188 offset:10240
	v_add_f32_e32 v158, v159, v88
	v_exp_f32_e32 v92, v92
	v_cvt_pk_bf16_f32 v129, v88, v89
	v_add_f32_e32 v158, v89, v158
	s_waitcnt lgkmcnt(3)
	v_mfma_f32_32x32x16_bf16 v[34:49], v[162:165], v[114:117], v[34:49]
	ds_read_b64_tr_b16 v[166:167], v189 offset:24576
	ds_read_b64_tr_b16 v[168:169], v189 offset:25088
	v_add_f32_e32 v154, v158, v90
	v_exp_f32_e32 v93, v93
	v_cvt_pk_bf16_f32 v122, v90, v91
	v_add_f32_e32 v154, v91, v154
	s_waitcnt lgkmcnt(4)
	v_mfma_f32_32x32x16_bf16 v[50:65], v[198:201], v[114:117], v[50:65]
	ds_read_b64_tr_b16 v[162:163], v189 offset:25600
	ds_read_b64_tr_b16 v[164:165], v189 offset:26112
	v_exp_f32_e32 v94, v94
	v_exp_f32_e32 v95, v95
	v_add_f32_e32 v154, v154, v92
	v_cvt_pk_bf16_f32 v123, v92, v93
	s_waitcnt lgkmcnt(5)
	v_mfma_f32_32x32x16_bf16 v[34:49], v[202:205], v[118:121], v[34:49]
	ds_read_b64_tr_b16 v[158:159], v189 offset:26624
	ds_read_b64_tr_b16 v[160:161], v189 offset:27136
	v_add_f32_e32 v154, v154, v93
	v_exp_f32_e32 v96, v96
	v_exp_f32_e32 v97, v97
	v_add_f32_e32 v193, v94, v154
	s_waitcnt lgkmcnt(6)
	v_mfma_f32_32x32x16_bf16 v[50:65], v[194:197], v[118:121], v[50:65]
	ds_read_b64_tr_b16 v[154:155], v189 offset:27648
	ds_read_b64_tr_b16 v[156:157], v189 offset:28160
	v_add_f32_e32 v125, v193, v95
	v_add_f32_e32 v193, v96, v125
	v_cvt_pk_bf16_f32 v124, v94, v95
	v_cvt_pk_bf16_f32 v125, v96, v97
	v_add_f32_e32 v193, v97, v193
	s_add_u32 s22, s22, 0x2000
	s_addc_u32 s23, s23, 0
	s_add_u32 s20, s20, 0x40000
	s_addc_u32 s21, s21, 0
	s_waitcnt vmcnt(6) lgkmcnt(0)
	s_barrier
	v_mfma_f32_32x32x16_bf16 v[2:17], v[134:137], v[166:169], v[2:17]
	ds_read_b64_tr_b16 v[66:67], v189 offset:28672
	ds_read_b64_tr_b16 v[68:69], v189 offset:29184
	v_exp_f32_e32 v34, v34
	v_exp_f32_e32 v35, v35
	v_exp_f32_e32 v36, v36
	v_mfma_f32_32x32x16_bf16 v[2:17], v[130:133], v[162:165], v[2:17]
	ds_read_b64_tr_b16 v[70:71], v189 offset:29696
	ds_read_b64_tr_b16 v[72:73], v189 offset:30208
	v_add_f32_e32 v74, v193, v34
	v_exp_f32_e32 v37, v37
	v_cvt_pk_bf16_f32 v150, v34, v35
	v_add_f32_e32 v78, v35, v74
	v_mfma_f32_32x32x16_bf16 v[2:17], v[126:129], v[158:161], v[2:17]
	ds_read_b64_tr_b16 v[74:75], v189 offset:30720
	ds_read_b64_tr_b16 v[76:77], v189 offset:31232
	v_exp_f32_e32 v38, v38
	v_exp_f32_e32 v39, v39
	v_add_f32_e32 v82, v78, v36
	v_cvt_pk_bf16_f32 v151, v36, v37
	v_mfma_f32_32x32x16_bf16 v[2:17], v[122:125], v[154:157], v[2:17]
	ds_read_b64_tr_b16 v[78:79], v189 offset:31744
	ds_read_b64_tr_b16 v[80:81], v189 offset:32256
	v_add_f32_e32 v82, v82, v37
	v_exp_f32_e32 v40, v40
	v_exp_f32_e32 v41, v41
	v_add_f32_e32 v86, v38, v82
	s_waitcnt lgkmcnt(6)
	v_mfma_f32_32x32x16_bf16 v[18:33], v[134:137], v[66:69], v[18:33]
	ds_read_b128 v[82:85], v182 offset:12288
	v_cvt_pk_bf16_f32 v152, v38, v39
	v_add_f32_e32 v90, v86, v39
	v_exp_f32_e32 v42, v42
	v_exp_f32_e32 v43, v43
	s_waitcnt lgkmcnt(5)
	v_mfma_f32_32x32x16_bf16 v[18:33], v[130:133], v[70:73], v[18:33]
	ds_read_b128 v[86:89], v182 offset:16384
	v_add_f32_e32 v66, v90, v40
	v_exp_f32_e32 v44, v44
	v_cvt_pk_bf16_f32 v153, v40, v41
	v_add_f32_e32 v66, v41, v66
	s_waitcnt lgkmcnt(4)
	v_mfma_f32_32x32x16_bf16 v[18:33], v[126:129], v[74:77], v[18:33]
	ds_read_b128 v[154:157], v183 offset:12288
	v_add_f32_e32 v66, v66, v42
	v_exp_f32_e32 v45, v45
	v_cvt_pk_bf16_f32 v146, v42, v43
	v_add_f32_e32 v66, v43, v66
	s_waitcnt lgkmcnt(3)
	v_mfma_f32_32x32x16_bf16 v[18:33], v[122:125], v[78:81], v[18:33]
	ds_read_b128 v[162:165], v183 offset:16384
	v_exp_f32_e32 v46, v46
	v_exp_f32_e32 v47, v47
	v_add_f32_e32 v66, v66, v44
	v_cvt_pk_bf16_f32 v147, v44, v45
	s_nop 0
	v_add_f32_e32 v66, v66, v45
	v_add_f32_e32 v91, v46, v66
	s_waitcnt lgkmcnt(3)
	v_mfma_f32_32x32x16_bf16 v[66:81], v[82:85], v[98:101], 0
	ds_read_b128 v[166:169], v184 offset:12288
	v_exp_f32_e32 v48, v48
	v_exp_f32_e32 v49, v49
	ds_read_b128 v[158:161], v184 offset:16384
	v_add_f32_e32 v193, v91, v47
	s_waitcnt lgkmcnt(4)
	v_mfma_f32_32x32x16_bf16 v[82:97], v[86:89], v[98:101], 0
	s_add_u32 s26, s20, 0xfffe0000
	s_addc_u32 s27, s21, -1
	s_add_u32 s28, s22, 0xfffff000
	s_addc_u32 s29, s23, -1
	s_mov_b32 m0, s8
	v_exp_f32_e32 v50, v50
	global_load_lds_dwordx4 v174, s[26:27]
	s_add_i32 m0, m0, 0x2000
	v_exp_f32_e32 v51, v51
	global_load_lds_dwordx4 v192, s[28:29]
	s_mov_b32 m0, s12
	v_cvt_pk_bf16_f32 v148, v46, v47
	global_load_lds_dwordx4 v191, s[26:27]
	s_waitcnt lgkmcnt(3)
	v_mfma_f32_32x32x16_bf16 v[66:81], v[154:157], v[102:105], v[66:81]
	ds_read_b128 v[194:197], v185 offset:12288
	v_add_f32_e32 v193, v193, v48
	v_cvt_pk_bf16_f32 v149, v48, v49
	v_add_f32_e32 v193, v49, v193
	v_exp_f32_e32 v52, v52
	s_waitcnt lgkmcnt(3)
	v_mfma_f32_32x32x16_bf16 v[82:97], v[162:165], v[102:105], v[82:97]
	ds_read_b128 v[154:157], v185 offset:16384
	v_add_f32_e32 v193, v193, v50
	v_exp_f32_e32 v53, v53
	v_cvt_pk_bf16_f32 v142, v50, v51
	v_add_f32_e32 v193, v51, v193
	s_waitcnt lgkmcnt(3)
	v_mfma_f32_32x32x16_bf16 v[66:81], v[166:169], v[106:109], v[66:81]
	ds_read_b128 v[162:165], v187 offset:20480
	v_exp_f32_e32 v54, v54
	v_exp_f32_e32 v55, v55
	v_add_f32_e32 v193, v193, v52
	v_cvt_pk_bf16_f32 v143, v52, v53
	s_waitcnt lgkmcnt(3)
	v_mfma_f32_32x32x16_bf16 v[82:97], v[158:161], v[106:109], v[82:97]
	ds_read_b128 v[198:201], v187 offset:22528
	v_add_f32_e32 v166, v193, v53
	v_exp_f32_e32 v56, v56
	v_exp_f32_e32 v57, v57
	v_add_f32_e32 v166, v54, v166
	s_waitcnt lgkmcnt(3)
	v_mfma_f32_32x32x16_bf16 v[66:81], v[194:197], v[110:113], v[66:81]
	ds_read_b128 v[202:205], v188 offset:20480
	v_cvt_pk_bf16_f32 v144, v54, v55
	v_add_f32_e32 v159, v166, v55
	v_exp_f32_e32 v58, v58
	v_exp_f32_e32 v59, v59
	s_waitcnt lgkmcnt(3)
	v_mfma_f32_32x32x16_bf16 v[82:97], v[154:157], v[110:113], v[82:97]
	ds_read_b128 v[194:197], v188 offset:22528
	v_add_f32_e32 v158, v159, v56
	v_exp_f32_e32 v60, v60
	v_cvt_pk_bf16_f32 v145, v56, v57
	v_add_f32_e32 v158, v57, v158
	s_waitcnt lgkmcnt(3)
	v_mfma_f32_32x32x16_bf16 v[66:81], v[162:165], v[114:117], v[66:81]
	ds_read_b64_tr_b16 v[166:167], v189 offset:32768
	ds_read_b64_tr_b16 v[168:169], v189 offset:33280
	v_add_f32_e32 v154, v158, v58
	v_exp_f32_e32 v61, v61
	v_cvt_pk_bf16_f32 v138, v58, v59
	v_add_f32_e32 v154, v59, v154
	s_waitcnt lgkmcnt(4)
	v_mfma_f32_32x32x16_bf16 v[82:97], v[198:201], v[114:117], v[82:97]
	ds_read_b64_tr_b16 v[162:163], v189 offset:33792
	ds_read_b64_tr_b16 v[164:165], v189 offset:34304
	v_exp_f32_e32 v62, v62
	v_exp_f32_e32 v63, v63
	v_add_f32_e32 v154, v154, v60
	v_cvt_pk_bf16_f32 v139, v60, v61
	s_waitcnt lgkmcnt(5)
	v_mfma_f32_32x32x16_bf16 v[66:81], v[202:205], v[118:121], v[66:81]
	ds_read_b64_tr_b16 v[158:159], v189 offset:34816
	ds_read_b64_tr_b16 v[160:161], v189 offset:35328
	v_add_f32_e32 v154, v154, v61
	v_exp_f32_e32 v64, v64
	v_exp_f32_e32 v65, v65
	v_add_f32_e32 v198, v62, v154
	s_waitcnt lgkmcnt(6)
	v_mfma_f32_32x32x16_bf16 v[82:97], v[194:197], v[118:121], v[82:97]
	ds_read_b64_tr_b16 v[154:155], v189 offset:35840
	ds_read_b64_tr_b16 v[156:157], v189 offset:36352
	v_add_f32_e32 v141, v198, v63
	v_add_f32_e32 v198, v64, v141
	v_cvt_pk_bf16_f32 v140, v62, v63
	v_cvt_pk_bf16_f32 v141, v64, v65
	v_add_f32_e32 v194, v65, v198
	s_waitcnt vmcnt(6) lgkmcnt(0)
	s_barrier
	v_mfma_f32_32x32x16_bf16 v[2:17], v[150:153], v[166:169], v[2:17]
	ds_read_b64_tr_b16 v[34:35], v189 offset:36864
	ds_read_b64_tr_b16 v[36:37], v189 offset:37376
	v_exp_f32_e32 v66, v66
	v_exp_f32_e32 v67, v67
	v_exp_f32_e32 v68, v68
	v_mfma_f32_32x32x16_bf16 v[2:17], v[146:149], v[162:165], v[2:17]
	ds_read_b64_tr_b16 v[38:39], v189 offset:37888
	ds_read_b64_tr_b16 v[40:41], v189 offset:38400
	v_add_f32_e32 v42, v194, v66
	v_exp_f32_e32 v69, v69
	v_cvt_pk_bf16_f32 v134, v66, v67
	v_add_f32_e32 v46, v67, v42
	v_mfma_f32_32x32x16_bf16 v[2:17], v[142:145], v[158:161], v[2:17]
	ds_read_b64_tr_b16 v[42:43], v189 offset:38912
	ds_read_b64_tr_b16 v[44:45], v189 offset:39424
	v_exp_f32_e32 v70, v70
	v_exp_f32_e32 v71, v71
	v_add_f32_e32 v50, v46, v68
	v_cvt_pk_bf16_f32 v135, v68, v69
	v_mfma_f32_32x32x16_bf16 v[2:17], v[138:141], v[154:157], v[2:17]
	ds_read_b64_tr_b16 v[46:47], v189 offset:39936
	ds_read_b64_tr_b16 v[48:49], v189 offset:40448
	v_add_f32_e32 v50, v50, v69
	v_exp_f32_e32 v72, v72
	v_exp_f32_e32 v73, v73
	v_add_f32_e32 v54, v70, v50
	s_waitcnt lgkmcnt(6)
	v_mfma_f32_32x32x16_bf16 v[18:33], v[150:153], v[34:37], v[18:33]
	ds_read_b128 v[50:53], v182 offset:24576
	v_cvt_pk_bf16_f32 v136, v70, v71
	v_add_f32_e32 v58, v54, v71
	v_exp_f32_e32 v74, v74
	v_exp_f32_e32 v75, v75
	s_waitcnt lgkmcnt(5)
	v_mfma_f32_32x32x16_bf16 v[18:33], v[146:149], v[38:41], v[18:33]
	ds_read_b128 v[54:57], v182 offset:28672
	v_add_f32_e32 v34, v58, v72
	v_exp_f32_e32 v76, v76
	v_cvt_pk_bf16_f32 v137, v72, v73
	v_add_f32_e32 v34, v73, v34
	s_waitcnt lgkmcnt(4)
	v_mfma_f32_32x32x16_bf16 v[18:33], v[142:145], v[42:45], v[18:33]
	ds_read_b128 v[154:157], v183 offset:24576
	v_add_f32_e32 v34, v34, v74
	v_exp_f32_e32 v77, v77
	v_cvt_pk_bf16_f32 v130, v74, v75
	v_add_f32_e32 v34, v75, v34
	s_waitcnt lgkmcnt(3)
	v_mfma_f32_32x32x16_bf16 v[18:33], v[138:141], v[46:49], v[18:33]
	ds_read_b128 v[162:165], v183 offset:28672
	v_exp_f32_e32 v78, v78
	v_exp_f32_e32 v79, v79
	v_add_f32_e32 v34, v34, v76
	v_cvt_pk_bf16_f32 v131, v76, v77
	s_nop 0
	v_add_f32_e32 v34, v34, v77
	v_add_f32_e32 v59, v78, v34
	s_waitcnt lgkmcnt(3)
	v_mfma_f32_32x32x16_bf16 v[34:49], v[50:53], v[98:101], 0
	ds_read_b128 v[166:169], v184 offset:24576
	v_exp_f32_e32 v80, v80
	v_exp_f32_e32 v81, v81
	ds_read_b128 v[158:161], v184 offset:28672
	v_add_f32_e32 v193, v59, v79
	s_waitcnt lgkmcnt(4)
	v_mfma_f32_32x32x16_bf16 v[50:65], v[54:57], v[98:101], 0
	s_add_i32 m0, 0x3000, s8
	v_exp_f32_e32 v82, v82
	global_load_lds_dwordx4 v174, s[20:21]
	s_add_i32 m0, m0, 0x2000
	v_exp_f32_e32 v83, v83
	global_load_lds_dwordx4 v192, s[22:23]
	s_add_i32 m0, 0x2000, s12
	v_cvt_pk_bf16_f32 v132, v78, v79
	global_load_lds_dwordx4 v191, s[20:21]
	s_waitcnt lgkmcnt(3)
	v_mfma_f32_32x32x16_bf16 v[34:49], v[154:157], v[102:105], v[34:49]
	ds_read_b128 v[194:197], v185 offset:24576
	v_add_f32_e32 v154, v193, v80
	v_exp_f32_e32 v84, v84
	v_cvt_pk_bf16_f32 v133, v80, v81
	v_add_f32_e32 v193, v81, v154
	s_waitcnt lgkmcnt(3)
	v_mfma_f32_32x32x16_bf16 v[50:65], v[162:165], v[102:105], v[50:65]
	ds_read_b128 v[154:157], v185 offset:28672
	v_add_f32_e32 v193, v193, v82
	v_exp_f32_e32 v85, v85
	v_cvt_pk_bf16_f32 v126, v82, v83
	v_add_f32_e32 v193, v83, v193
	s_waitcnt lgkmcnt(3)
	v_mfma_f32_32x32x16_bf16 v[34:49], v[166:169], v[106:109], v[34:49]
	ds_read_b128 v[162:165], v187 offset:32768
	v_exp_f32_e32 v86, v86
	v_exp_f32_e32 v87, v87
	v_add_f32_e32 v193, v193, v84
	v_cvt_pk_bf16_f32 v127, v84, v85
	s_waitcnt lgkmcnt(3)
	v_mfma_f32_32x32x16_bf16 v[50:65], v[158:161], v[106:109], v[50:65]
	ds_read_b128 v[198:201], v187 offset:34816
	v_add_f32_e32 v166, v193, v85
	v_exp_f32_e32 v88, v88
	v_exp_f32_e32 v89, v89
	v_add_f32_e32 v166, v86, v166
	s_waitcnt lgkmcnt(3)
	v_mfma_f32_32x32x16_bf16 v[34:49], v[194:197], v[110:113], v[34:49]
	ds_read_b128 v[202:205], v188 offset:32768
	v_cvt_pk_bf16_f32 v128, v86, v87
	v_add_f32_e32 v159, v166, v87
	v_exp_f32_e32 v90, v90
	v_exp_f32_e32 v91, v91
	s_waitcnt lgkmcnt(3)
	v_mfma_f32_32x32x16_bf16 v[50:65], v[154:157], v[110:113], v[50:65]
	ds_read_b128 v[194:197], v188 offset:34816
	v_add_f32_e32 v158, v159, v88
	v_exp_f32_e32 v92, v92
	v_cvt_pk_bf16_f32 v129, v88, v89
	v_add_f32_e32 v158, v89, v158
	s_waitcnt lgkmcnt(3)
	v_mfma_f32_32x32x16_bf16 v[34:49], v[162:165], v[114:117], v[34:49]
	ds_read_b64_tr_b16 v[166:167], v189 offset:40960
	ds_read_b64_tr_b16 v[168:169], v189 offset:41472
	v_add_f32_e32 v154, v158, v90
	v_exp_f32_e32 v93, v93
	v_cvt_pk_bf16_f32 v122, v90, v91
	v_add_f32_e32 v154, v91, v154
	s_waitcnt lgkmcnt(4)
	v_mfma_f32_32x32x16_bf16 v[50:65], v[198:201], v[114:117], v[50:65]
	ds_read_b64_tr_b16 v[162:163], v189 offset:41984
	ds_read_b64_tr_b16 v[164:165], v189 offset:42496
	v_exp_f32_e32 v94, v94
	v_exp_f32_e32 v95, v95
	v_add_f32_e32 v154, v154, v92
	v_cvt_pk_bf16_f32 v123, v92, v93
	s_waitcnt lgkmcnt(5)
	v_mfma_f32_32x32x16_bf16 v[34:49], v[202:205], v[118:121], v[34:49]
	ds_read_b64_tr_b16 v[158:159], v189 offset:43008
	ds_read_b64_tr_b16 v[160:161], v189 offset:43520
	v_add_f32_e32 v154, v154, v93
	v_exp_f32_e32 v96, v96
	v_exp_f32_e32 v97, v97
	v_add_f32_e32 v193, v94, v154
	s_waitcnt lgkmcnt(6)
	v_mfma_f32_32x32x16_bf16 v[50:65], v[194:197], v[118:121], v[50:65]
	ds_read_b64_tr_b16 v[154:155], v189 offset:44032
	ds_read_b64_tr_b16 v[156:157], v189 offset:44544
	v_add_f32_e32 v125, v193, v95
	v_add_f32_e32 v193, v96, v125
	v_cvt_pk_bf16_f32 v124, v94, v95
	v_cvt_pk_bf16_f32 v125, v96, v97
	v_add_f32_e32 v193, v97, v193
	s_add_u32 s22, s22, 0x2000
	s_addc_u32 s23, s23, 0
	s_add_u32 s20, s20, 0x40000
	s_addc_u32 s21, s21, 0
	s_waitcnt vmcnt(6) lgkmcnt(0)
	s_barrier
	v_mfma_f32_32x32x16_bf16 v[2:17], v[134:137], v[166:169], v[2:17]
	ds_read_b64_tr_b16 v[66:67], v189 offset:45056
	ds_read_b64_tr_b16 v[68:69], v189 offset:45568
	v_exp_f32_e32 v34, v34
	v_exp_f32_e32 v35, v35
	v_exp_f32_e32 v36, v36
	v_mfma_f32_32x32x16_bf16 v[2:17], v[130:133], v[162:165], v[2:17]
	ds_read_b64_tr_b16 v[70:71], v189 offset:46080
	ds_read_b64_tr_b16 v[72:73], v189 offset:46592
	v_add_f32_e32 v74, v193, v34
	v_exp_f32_e32 v37, v37
	v_cvt_pk_bf16_f32 v150, v34, v35
	v_add_f32_e32 v78, v35, v74
	v_mfma_f32_32x32x16_bf16 v[2:17], v[126:129], v[158:161], v[2:17]
	ds_read_b64_tr_b16 v[74:75], v189 offset:47104
	ds_read_b64_tr_b16 v[76:77], v189 offset:47616
	v_exp_f32_e32 v38, v38
	v_exp_f32_e32 v39, v39
	v_add_f32_e32 v82, v78, v36
	v_cvt_pk_bf16_f32 v151, v36, v37
	v_mfma_f32_32x32x16_bf16 v[2:17], v[122:125], v[154:157], v[2:17]
	ds_read_b64_tr_b16 v[78:79], v189 offset:48128
	ds_read_b64_tr_b16 v[80:81], v189 offset:48640
	v_add_f32_e32 v82, v82, v37
	v_exp_f32_e32 v40, v40
	v_exp_f32_e32 v41, v41
	v_add_f32_e32 v86, v38, v82
	s_waitcnt lgkmcnt(6)
	v_mfma_f32_32x32x16_bf16 v[18:33], v[134:137], v[66:69], v[18:33]
	ds_read_b128 v[82:85], v182 offset:36864
	v_cvt_pk_bf16_f32 v152, v38, v39
	v_add_f32_e32 v90, v86, v39
	v_exp_f32_e32 v42, v42
	v_exp_f32_e32 v43, v43
	s_waitcnt lgkmcnt(5)
	v_mfma_f32_32x32x16_bf16 v[18:33], v[130:133], v[70:73], v[18:33]
	ds_read_b128 v[86:89], v182 offset:40960
	v_add_f32_e32 v66, v90, v40
	v_exp_f32_e32 v44, v44
	v_cvt_pk_bf16_f32 v153, v40, v41
	v_add_f32_e32 v66, v41, v66
	s_waitcnt lgkmcnt(4)
	v_mfma_f32_32x32x16_bf16 v[18:33], v[126:129], v[74:77], v[18:33]
	ds_read_b128 v[154:157], v183 offset:36864
	v_add_f32_e32 v66, v66, v42
	v_exp_f32_e32 v45, v45
	v_cvt_pk_bf16_f32 v146, v42, v43
	v_add_f32_e32 v66, v43, v66
	s_waitcnt lgkmcnt(3)
	v_mfma_f32_32x32x16_bf16 v[18:33], v[122:125], v[78:81], v[18:33]
	ds_read_b128 v[162:165], v183 offset:40960
	v_exp_f32_e32 v46, v46
	v_exp_f32_e32 v47, v47
	v_add_f32_e32 v66, v66, v44
	v_cvt_pk_bf16_f32 v147, v44, v45
	s_nop 0
	v_add_f32_e32 v66, v66, v45
	v_add_f32_e32 v91, v46, v66
	s_waitcnt lgkmcnt(3)
	v_mfma_f32_32x32x16_bf16 v[66:81], v[82:85], v[98:101], 0
	ds_read_b128 v[166:169], v184 offset:36864
	v_exp_f32_e32 v48, v48
	v_exp_f32_e32 v49, v49
	ds_read_b128 v[158:161], v184 offset:40960
	v_add_f32_e32 v193, v91, v47
	s_waitcnt lgkmcnt(4)
	v_mfma_f32_32x32x16_bf16 v[82:97], v[86:89], v[98:101], 0
	s_add_u32 s26, s20, 0xfffe0000
	s_addc_u32 s27, s21, -1
	s_add_u32 s28, s22, 0xfffff000
	s_addc_u32 s29, s23, -1
	s_add_i32 m0, 0x6000, s8
	v_exp_f32_e32 v50, v50
	global_load_lds_dwordx4 v174, s[26:27]
	s_add_i32 m0, m0, 0x2000
	v_exp_f32_e32 v51, v51
	global_load_lds_dwordx4 v192, s[28:29]
	s_add_i32 m0, 0x4000, s12
	v_cvt_pk_bf16_f32 v148, v46, v47
	global_load_lds_dwordx4 v191, s[26:27]
	s_waitcnt lgkmcnt(3)
	v_mfma_f32_32x32x16_bf16 v[66:81], v[154:157], v[102:105], v[66:81]
	ds_read_b128 v[194:197], v185 offset:36864
	v_add_f32_e32 v193, v193, v48
	v_cvt_pk_bf16_f32 v149, v48, v49
	v_add_f32_e32 v193, v49, v193
	v_exp_f32_e32 v52, v52
	s_waitcnt lgkmcnt(3)
	v_mfma_f32_32x32x16_bf16 v[82:97], v[162:165], v[102:105], v[82:97]
	ds_read_b128 v[154:157], v185 offset:40960
	v_add_f32_e32 v193, v193, v50
	v_exp_f32_e32 v53, v53
	v_cvt_pk_bf16_f32 v142, v50, v51
	v_add_f32_e32 v193, v51, v193
	s_waitcnt lgkmcnt(3)
	v_mfma_f32_32x32x16_bf16 v[66:81], v[166:169], v[106:109], v[66:81]
	ds_read_b128 v[162:165], v187 offset:45056
	v_exp_f32_e32 v54, v54
	v_exp_f32_e32 v55, v55
	v_add_f32_e32 v193, v193, v52
	v_cvt_pk_bf16_f32 v143, v52, v53
	s_waitcnt lgkmcnt(3)
	v_mfma_f32_32x32x16_bf16 v[82:97], v[158:161], v[106:109], v[82:97]
	ds_read_b128 v[198:201], v187 offset:47104
	v_add_f32_e32 v166, v193, v53
	v_exp_f32_e32 v56, v56
	v_exp_f32_e32 v57, v57
	v_add_f32_e32 v166, v54, v166
	s_waitcnt lgkmcnt(3)
	v_mfma_f32_32x32x16_bf16 v[66:81], v[194:197], v[110:113], v[66:81]
	ds_read_b128 v[202:205], v188 offset:45056
	v_cvt_pk_bf16_f32 v144, v54, v55
	v_add_f32_e32 v159, v166, v55
	v_exp_f32_e32 v58, v58
	v_exp_f32_e32 v59, v59
	s_waitcnt lgkmcnt(3)
	v_mfma_f32_32x32x16_bf16 v[82:97], v[154:157], v[110:113], v[82:97]
	ds_read_b128 v[194:197], v188 offset:47104
	v_add_f32_e32 v158, v159, v56
	v_exp_f32_e32 v60, v60
	v_cvt_pk_bf16_f32 v145, v56, v57
	v_add_f32_e32 v158, v57, v158
	s_waitcnt lgkmcnt(3)
	v_mfma_f32_32x32x16_bf16 v[66:81], v[162:165], v[114:117], v[66:81]
	ds_read_b64_tr_b16 v[166:167], v189 offset:49152
	ds_read_b64_tr_b16 v[168:169], v189 offset:49664
	v_add_f32_e32 v154, v158, v58
	v_exp_f32_e32 v61, v61
	v_cvt_pk_bf16_f32 v138, v58, v59
	v_add_f32_e32 v154, v59, v154
	s_waitcnt lgkmcnt(4)
	v_mfma_f32_32x32x16_bf16 v[82:97], v[198:201], v[114:117], v[82:97]
	ds_read_b64_tr_b16 v[162:163], v189 offset:50176
	ds_read_b64_tr_b16 v[164:165], v189 offset:50688
	v_exp_f32_e32 v62, v62
	v_exp_f32_e32 v63, v63
	v_add_f32_e32 v154, v154, v60
	v_cvt_pk_bf16_f32 v139, v60, v61
	s_waitcnt lgkmcnt(5)
	v_mfma_f32_32x32x16_bf16 v[66:81], v[202:205], v[118:121], v[66:81]
	ds_read_b64_tr_b16 v[158:159], v189 offset:51200
	ds_read_b64_tr_b16 v[160:161], v189 offset:51712
	v_add_f32_e32 v154, v154, v61
	v_exp_f32_e32 v64, v64
	v_exp_f32_e32 v65, v65
	v_add_f32_e32 v198, v62, v154
	s_waitcnt lgkmcnt(6)
	v_mfma_f32_32x32x16_bf16 v[82:97], v[194:197], v[118:121], v[82:97]
	ds_read_b64_tr_b16 v[154:155], v189 offset:52224
	ds_read_b64_tr_b16 v[156:157], v189 offset:52736
	v_add_f32_e32 v141, v198, v63
	v_add_f32_e32 v198, v64, v141
	v_cvt_pk_bf16_f32 v140, v62, v63
	v_cvt_pk_bf16_f32 v141, v64, v65
	v_add_f32_e32 v194, v65, v198
	s_waitcnt vmcnt(6) lgkmcnt(0)
	s_barrier
	v_mfma_f32_32x32x16_bf16 v[2:17], v[150:153], v[166:169], v[2:17]
	ds_read_b64_tr_b16 v[34:35], v189 offset:53248
	ds_read_b64_tr_b16 v[36:37], v189 offset:53760
	v_exp_f32_e32 v66, v66
	v_exp_f32_e32 v67, v67
	v_exp_f32_e32 v68, v68
	v_mfma_f32_32x32x16_bf16 v[2:17], v[146:149], v[162:165], v[2:17]
	ds_read_b64_tr_b16 v[38:39], v189 offset:54272
	ds_read_b64_tr_b16 v[40:41], v189 offset:54784
	v_add_f32_e32 v42, v194, v66
	v_exp_f32_e32 v69, v69
	v_cvt_pk_bf16_f32 v134, v66, v67
	v_add_f32_e32 v46, v67, v42
	v_mfma_f32_32x32x16_bf16 v[2:17], v[142:145], v[158:161], v[2:17]
	ds_read_b64_tr_b16 v[42:43], v189 offset:55296
	ds_read_b64_tr_b16 v[44:45], v189 offset:55808
	v_exp_f32_e32 v70, v70
	v_exp_f32_e32 v71, v71
	v_add_f32_e32 v50, v46, v68
	v_cvt_pk_bf16_f32 v135, v68, v69
	v_mfma_f32_32x32x16_bf16 v[2:17], v[138:141], v[154:157], v[2:17]
	ds_read_b64_tr_b16 v[46:47], v189 offset:56320
	ds_read_b64_tr_b16 v[48:49], v189 offset:56832
	v_add_f32_e32 v50, v50, v69
	v_exp_f32_e32 v72, v72
	v_exp_f32_e32 v73, v73
	v_add_f32_e32 v54, v70, v50
	s_waitcnt lgkmcnt(6)
	v_mfma_f32_32x32x16_bf16 v[18:33], v[150:153], v[34:37], v[18:33]
	ds_read_b128 v[50:53], v182
	v_cvt_pk_bf16_f32 v136, v70, v71
	v_add_f32_e32 v58, v54, v71
	v_exp_f32_e32 v74, v74
	v_exp_f32_e32 v75, v75
	s_waitcnt lgkmcnt(5)
	v_mfma_f32_32x32x16_bf16 v[18:33], v[146:149], v[38:41], v[18:33]
	ds_read_b128 v[54:57], v182 offset:4096
	v_add_f32_e32 v34, v58, v72
	v_exp_f32_e32 v76, v76
	v_cvt_pk_bf16_f32 v137, v72, v73
	v_add_f32_e32 v34, v73, v34
	s_waitcnt lgkmcnt(4)
	v_mfma_f32_32x32x16_bf16 v[18:33], v[142:145], v[42:45], v[18:33]
	ds_read_b128 v[154:157], v183
	v_add_f32_e32 v34, v34, v74
	v_exp_f32_e32 v77, v77
	v_cvt_pk_bf16_f32 v130, v74, v75
	v_add_f32_e32 v34, v75, v34
	s_waitcnt lgkmcnt(3)
	v_mfma_f32_32x32x16_bf16 v[18:33], v[138:141], v[46:49], v[18:33]
	ds_read_b128 v[162:165], v183 offset:4096
	v_exp_f32_e32 v78, v78
	v_exp_f32_e32 v79, v79
	v_add_f32_e32 v34, v34, v76
	v_cvt_pk_bf16_f32 v131, v76, v77
	s_nop 0
	v_add_f32_e32 v34, v34, v77
	v_add_f32_e32 v59, v78, v34
	s_waitcnt lgkmcnt(3)
	v_mfma_f32_32x32x16_bf16 v[34:49], v[50:53], v[98:101], 0
	ds_read_b128 v[166:169], v184
	v_exp_f32_e32 v80, v80
	v_exp_f32_e32 v81, v81
	ds_read_b128 v[158:161], v184 offset:4096
	v_add_f32_e32 v193, v59, v79
	s_waitcnt lgkmcnt(4)
	v_mfma_f32_32x32x16_bf16 v[50:65], v[54:57], v[98:101], 0
	s_add_i32 m0, 0x9000, s8
	v_exp_f32_e32 v82, v82
	global_load_lds_dwordx4 v174, s[20:21]
	s_add_i32 m0, m0, 0x2000
	v_exp_f32_e32 v83, v83
	global_load_lds_dwordx4 v192, s[22:23]
	s_add_i32 m0, 0x6000, s12
	v_cvt_pk_bf16_f32 v132, v78, v79
	global_load_lds_dwordx4 v191, s[20:21]
	s_waitcnt lgkmcnt(3)
	v_mfma_f32_32x32x16_bf16 v[34:49], v[154:157], v[102:105], v[34:49]
	ds_read_b128 v[194:197], v185
	v_add_f32_e32 v154, v193, v80
	v_exp_f32_e32 v84, v84
	v_cvt_pk_bf16_f32 v133, v80, v81
	v_add_f32_e32 v193, v81, v154
	s_waitcnt lgkmcnt(3)
	v_mfma_f32_32x32x16_bf16 v[50:65], v[162:165], v[102:105], v[50:65]
	ds_read_b128 v[154:157], v185 offset:4096
	v_add_f32_e32 v193, v193, v82
	v_exp_f32_e32 v85, v85
	v_cvt_pk_bf16_f32 v126, v82, v83
	v_add_f32_e32 v193, v83, v193
	s_waitcnt lgkmcnt(3)
	v_mfma_f32_32x32x16_bf16 v[34:49], v[166:169], v[106:109], v[34:49]
	ds_read_b128 v[162:165], v187 offset:8192
	v_exp_f32_e32 v86, v86
	v_exp_f32_e32 v87, v87
	v_add_f32_e32 v193, v193, v84
	v_cvt_pk_bf16_f32 v127, v84, v85
	s_waitcnt lgkmcnt(3)
	v_mfma_f32_32x32x16_bf16 v[50:65], v[158:161], v[106:109], v[50:65]
	ds_read_b128 v[198:201], v187 offset:10240
	v_add_f32_e32 v166, v193, v85
	v_exp_f32_e32 v88, v88
	v_exp_f32_e32 v89, v89
	v_add_f32_e32 v166, v86, v166
	s_waitcnt lgkmcnt(3)
	v_mfma_f32_32x32x16_bf16 v[34:49], v[194:197], v[110:113], v[34:49]
	ds_read_b128 v[202:205], v188 offset:8192
	v_cvt_pk_bf16_f32 v128, v86, v87
	v_add_f32_e32 v159, v166, v87
	v_exp_f32_e32 v90, v90
	v_exp_f32_e32 v91, v91
	s_waitcnt lgkmcnt(3)
	v_mfma_f32_32x32x16_bf16 v[50:65], v[154:157], v[110:113], v[50:65]
	ds_read_b128 v[194:197], v188 offset:10240
	v_add_f32_e32 v158, v159, v88
	v_exp_f32_e32 v92, v92
	v_cvt_pk_bf16_f32 v129, v88, v89
	v_add_f32_e32 v158, v89, v158
	s_waitcnt lgkmcnt(3)
	v_mfma_f32_32x32x16_bf16 v[34:49], v[162:165], v[114:117], v[34:49]
	ds_read_b64_tr_b16 v[166:167], v189 offset:57344
	ds_read_b64_tr_b16 v[168:169], v189 offset:57856
	v_add_f32_e32 v154, v158, v90
	v_exp_f32_e32 v93, v93
	v_cvt_pk_bf16_f32 v122, v90, v91
	v_add_f32_e32 v154, v91, v154
	s_waitcnt lgkmcnt(4)
	v_mfma_f32_32x32x16_bf16 v[50:65], v[198:201], v[114:117], v[50:65]
	ds_read_b64_tr_b16 v[162:163], v189 offset:58368
	ds_read_b64_tr_b16 v[164:165], v189 offset:58880
	v_exp_f32_e32 v94, v94
	v_exp_f32_e32 v95, v95
	v_add_f32_e32 v154, v154, v92
	v_cvt_pk_bf16_f32 v123, v92, v93
	s_waitcnt lgkmcnt(5)
	v_mfma_f32_32x32x16_bf16 v[34:49], v[202:205], v[118:121], v[34:49]
	ds_read_b64_tr_b16 v[158:159], v189 offset:59392
	ds_read_b64_tr_b16 v[160:161], v189 offset:59904
	v_add_f32_e32 v154, v154, v93
	v_exp_f32_e32 v96, v96
	v_exp_f32_e32 v97, v97
	v_add_f32_e32 v193, v94, v154
	s_waitcnt lgkmcnt(6)
	v_mfma_f32_32x32x16_bf16 v[50:65], v[194:197], v[118:121], v[50:65]
	ds_read_b64_tr_b16 v[154:155], v189 offset:60416
	ds_read_b64_tr_b16 v[156:157], v189 offset:60928
	v_add_f32_e32 v125, v193, v95
	v_add_f32_e32 v193, v96, v125
	v_cvt_pk_bf16_f32 v124, v94, v95
	v_cvt_pk_bf16_f32 v125, v96, v97
	v_add_f32_e32 v193, v97, v193
	s_add_u32 s22, s22, 0x2000
	s_addc_u32 s23, s23, 0
	s_add_u32 s20, s20, 0x40000
	s_addc_u32 s21, s21, 0
	s_waitcnt vmcnt(6) lgkmcnt(0)
	s_barrier
	v_mfma_f32_32x32x16_bf16 v[2:17], v[134:137], v[166:169], v[2:17]
	ds_read_b64_tr_b16 v[66:67], v189 offset:61440
	ds_read_b64_tr_b16 v[68:69], v189 offset:61952
	v_exp_f32_e32 v34, v34
	v_exp_f32_e32 v35, v35
	v_exp_f32_e32 v36, v36
	v_mfma_f32_32x32x16_bf16 v[2:17], v[130:133], v[162:165], v[2:17]
	ds_read_b64_tr_b16 v[70:71], v189 offset:62464
	ds_read_b64_tr_b16 v[72:73], v189 offset:62976
	v_add_f32_e32 v74, v193, v34
	v_exp_f32_e32 v37, v37
	v_cvt_pk_bf16_f32 v150, v34, v35
	v_add_f32_e32 v78, v35, v74
	v_mfma_f32_32x32x16_bf16 v[2:17], v[126:129], v[158:161], v[2:17]
	ds_read_b64_tr_b16 v[74:75], v189 offset:63488
	ds_read_b64_tr_b16 v[76:77], v189 offset:64000
	v_exp_f32_e32 v38, v38
	v_exp_f32_e32 v39, v39
	v_add_f32_e32 v82, v78, v36
	v_cvt_pk_bf16_f32 v151, v36, v37
	v_mfma_f32_32x32x16_bf16 v[2:17], v[122:125], v[154:157], v[2:17]
	ds_read_b64_tr_b16 v[78:79], v189 offset:64512
	ds_read_b64_tr_b16 v[80:81], v189 offset:65024
	v_add_f32_e32 v82, v82, v37
	v_exp_f32_e32 v40, v40
	v_exp_f32_e32 v41, v41
	v_add_f32_e32 v86, v38, v82
	s_waitcnt lgkmcnt(6)
	v_mfma_f32_32x32x16_bf16 v[18:33], v[134:137], v[66:69], v[18:33]
	ds_read_b128 v[82:85], v182 offset:12288
	v_cvt_pk_bf16_f32 v152, v38, v39
	v_add_f32_e32 v90, v86, v39
	v_exp_f32_e32 v42, v42
	v_exp_f32_e32 v43, v43
	s_waitcnt lgkmcnt(5)
	v_mfma_f32_32x32x16_bf16 v[18:33], v[130:133], v[70:73], v[18:33]
	ds_read_b128 v[86:89], v182 offset:16384
	v_add_f32_e32 v66, v90, v40
	v_exp_f32_e32 v44, v44
	v_cvt_pk_bf16_f32 v153, v40, v41
	v_add_f32_e32 v66, v41, v66
	s_waitcnt lgkmcnt(4)
	v_mfma_f32_32x32x16_bf16 v[18:33], v[126:129], v[74:77], v[18:33]
	ds_read_b128 v[154:157], v183 offset:12288
	v_add_f32_e32 v66, v66, v42
	v_exp_f32_e32 v45, v45
	v_cvt_pk_bf16_f32 v146, v42, v43
	v_add_f32_e32 v66, v43, v66
	s_waitcnt lgkmcnt(3)
	v_mfma_f32_32x32x16_bf16 v[18:33], v[122:125], v[78:81], v[18:33]
	ds_read_b128 v[162:165], v183 offset:16384
	v_exp_f32_e32 v46, v46
	v_exp_f32_e32 v47, v47
	v_add_f32_e32 v66, v66, v44
	v_cvt_pk_bf16_f32 v147, v44, v45
	s_nop 0
	v_add_f32_e32 v66, v66, v45
	v_add_f32_e32 v91, v46, v66
	s_waitcnt lgkmcnt(3)
	v_mfma_f32_32x32x16_bf16 v[66:81], v[82:85], v[98:101], 0
	ds_read_b128 v[166:169], v184 offset:12288
	v_exp_f32_e32 v48, v48
	v_exp_f32_e32 v49, v49
	ds_read_b128 v[158:161], v184 offset:16384
	v_add_f32_e32 v193, v91, v47
	s_waitcnt lgkmcnt(4)
	v_mfma_f32_32x32x16_bf16 v[82:97], v[86:89], v[98:101], 0
	s_add_u32 s26, s20, 0xfffe0000
	s_addc_u32 s27, s21, -1
	s_add_u32 s28, s22, 0xfffff000
	s_addc_u32 s29, s23, -1
	s_mov_b32 m0, s8
	v_exp_f32_e32 v50, v50
	global_load_lds_dwordx4 v174, s[26:27]
	s_add_i32 m0, m0, 0x2000
	v_exp_f32_e32 v51, v51
	global_load_lds_dwordx4 v192, s[28:29]
	s_add_i32 m0, 0x8000, s12
	v_cvt_pk_bf16_f32 v148, v46, v47
	global_load_lds_dwordx4 v191, s[26:27]
	s_waitcnt lgkmcnt(3)
	v_mfma_f32_32x32x16_bf16 v[66:81], v[154:157], v[102:105], v[66:81]
	ds_read_b128 v[194:197], v185 offset:12288
	v_add_f32_e32 v193, v193, v48
	v_cvt_pk_bf16_f32 v149, v48, v49
	v_add_f32_e32 v193, v49, v193
	v_exp_f32_e32 v52, v52
	s_waitcnt lgkmcnt(3)
	v_mfma_f32_32x32x16_bf16 v[82:97], v[162:165], v[102:105], v[82:97]
	ds_read_b128 v[154:157], v185 offset:16384
	v_add_f32_e32 v193, v193, v50
	v_exp_f32_e32 v53, v53
	v_cvt_pk_bf16_f32 v142, v50, v51
	v_add_f32_e32 v193, v51, v193
	s_waitcnt lgkmcnt(3)
	v_mfma_f32_32x32x16_bf16 v[66:81], v[166:169], v[106:109], v[66:81]
	ds_read_b128 v[162:165], v187 offset:20480
	v_exp_f32_e32 v54, v54
	v_exp_f32_e32 v55, v55
	v_add_f32_e32 v193, v193, v52
	v_cvt_pk_bf16_f32 v143, v52, v53
	s_waitcnt lgkmcnt(3)
	v_mfma_f32_32x32x16_bf16 v[82:97], v[158:161], v[106:109], v[82:97]
	ds_read_b128 v[198:201], v187 offset:22528
	v_add_f32_e32 v166, v193, v53
	v_exp_f32_e32 v56, v56
	v_exp_f32_e32 v57, v57
	v_add_f32_e32 v166, v54, v166
	s_waitcnt lgkmcnt(3)
	v_mfma_f32_32x32x16_bf16 v[66:81], v[194:197], v[110:113], v[66:81]
	ds_read_b128 v[202:205], v188 offset:20480
	v_cvt_pk_bf16_f32 v144, v54, v55
	v_add_f32_e32 v159, v166, v55
	v_exp_f32_e32 v58, v58
	v_exp_f32_e32 v59, v59
	s_waitcnt lgkmcnt(3)
	v_mfma_f32_32x32x16_bf16 v[82:97], v[154:157], v[110:113], v[82:97]
	ds_read_b128 v[194:197], v188 offset:22528
	v_add_f32_e32 v158, v159, v56
	v_exp_f32_e32 v60, v60
	v_cvt_pk_bf16_f32 v145, v56, v57
	v_add_f32_e32 v158, v57, v158
	s_waitcnt lgkmcnt(3)
	v_mfma_f32_32x32x16_bf16 v[66:81], v[162:165], v[114:117], v[66:81]
	ds_read_b64_tr_b16 v[166:167], v189 offset:16384
	ds_read_b64_tr_b16 v[168:169], v189 offset:16896
	v_add_f32_e32 v154, v158, v58
	v_exp_f32_e32 v61, v61
	v_cvt_pk_bf16_f32 v138, v58, v59
	v_add_f32_e32 v154, v59, v154
	s_waitcnt lgkmcnt(4)
	v_mfma_f32_32x32x16_bf16 v[82:97], v[198:201], v[114:117], v[82:97]
	ds_read_b64_tr_b16 v[162:163], v189 offset:17408
	ds_read_b64_tr_b16 v[164:165], v189 offset:17920
	v_exp_f32_e32 v62, v62
	v_exp_f32_e32 v63, v63
	v_add_f32_e32 v154, v154, v60
	v_cvt_pk_bf16_f32 v139, v60, v61
	s_waitcnt lgkmcnt(5)
	v_mfma_f32_32x32x16_bf16 v[66:81], v[202:205], v[118:121], v[66:81]
	ds_read_b64_tr_b16 v[158:159], v189 offset:18432
	ds_read_b64_tr_b16 v[160:161], v189 offset:18944
	v_add_f32_e32 v154, v154, v61
	v_exp_f32_e32 v64, v64
	v_exp_f32_e32 v65, v65
	v_add_f32_e32 v198, v62, v154
	s_waitcnt lgkmcnt(6)
	v_mfma_f32_32x32x16_bf16 v[82:97], v[194:197], v[118:121], v[82:97]
	ds_read_b64_tr_b16 v[154:155], v189 offset:19456
	ds_read_b64_tr_b16 v[156:157], v189 offset:19968
	v_add_f32_e32 v141, v198, v63
	v_add_f32_e32 v198, v64, v141
	v_cvt_pk_bf16_f32 v140, v62, v63
	v_cvt_pk_bf16_f32 v141, v64, v65
	v_add_f32_e32 v194, v65, v198
	s_waitcnt vmcnt(6) lgkmcnt(0)
	s_barrier
	v_mfma_f32_32x32x16_bf16 v[2:17], v[150:153], v[166:169], v[2:17]
	ds_read_b64_tr_b16 v[34:35], v189 offset:20480
	ds_read_b64_tr_b16 v[36:37], v189 offset:20992
	v_exp_f32_e32 v66, v66
	v_exp_f32_e32 v67, v67
	v_exp_f32_e32 v68, v68
	v_mfma_f32_32x32x16_bf16 v[2:17], v[146:149], v[162:165], v[2:17]
	ds_read_b64_tr_b16 v[38:39], v189 offset:21504
	ds_read_b64_tr_b16 v[40:41], v189 offset:22016
	v_add_f32_e32 v42, v194, v66
	v_exp_f32_e32 v69, v69
	v_cvt_pk_bf16_f32 v134, v66, v67
	v_add_f32_e32 v46, v67, v42
	v_mfma_f32_32x32x16_bf16 v[2:17], v[142:145], v[158:161], v[2:17]
	ds_read_b64_tr_b16 v[42:43], v189 offset:22528
	ds_read_b64_tr_b16 v[44:45], v189 offset:23040
	v_exp_f32_e32 v70, v70
	v_exp_f32_e32 v71, v71
	v_add_f32_e32 v50, v46, v68
	v_cvt_pk_bf16_f32 v135, v68, v69
	v_mfma_f32_32x32x16_bf16 v[2:17], v[138:141], v[154:157], v[2:17]
	ds_read_b64_tr_b16 v[46:47], v189 offset:23552
	ds_read_b64_tr_b16 v[48:49], v189 offset:24064
	v_add_f32_e32 v50, v50, v69
	v_exp_f32_e32 v72, v72
	v_exp_f32_e32 v73, v73
	v_add_f32_e32 v54, v70, v50
	s_waitcnt lgkmcnt(6)
	v_mfma_f32_32x32x16_bf16 v[18:33], v[150:153], v[34:37], v[18:33]
	ds_read_b128 v[50:53], v182 offset:24576
	v_cvt_pk_bf16_f32 v136, v70, v71
	v_add_f32_e32 v58, v54, v71
	v_exp_f32_e32 v74, v74
	v_exp_f32_e32 v75, v75
	s_waitcnt lgkmcnt(5)
	v_mfma_f32_32x32x16_bf16 v[18:33], v[146:149], v[38:41], v[18:33]
	ds_read_b128 v[54:57], v182 offset:28672
	v_add_f32_e32 v34, v58, v72
	v_exp_f32_e32 v76, v76
	v_cvt_pk_bf16_f32 v137, v72, v73
	v_add_f32_e32 v34, v73, v34
	s_waitcnt lgkmcnt(4)
	v_mfma_f32_32x32x16_bf16 v[18:33], v[142:145], v[42:45], v[18:33]
	ds_read_b128 v[154:157], v183 offset:24576
	v_add_f32_e32 v34, v34, v74
	v_exp_f32_e32 v77, v77
	v_cvt_pk_bf16_f32 v130, v74, v75
	v_add_f32_e32 v34, v75, v34
	s_waitcnt lgkmcnt(3)
	v_mfma_f32_32x32x16_bf16 v[18:33], v[138:141], v[46:49], v[18:33]
	ds_read_b128 v[162:165], v183 offset:28672
	v_exp_f32_e32 v78, v78
	v_exp_f32_e32 v79, v79
	v_add_f32_e32 v34, v34, v76
	v_cvt_pk_bf16_f32 v131, v76, v77
	s_nop 0
	v_add_f32_e32 v34, v34, v77
	v_add_f32_e32 v59, v78, v34
	s_waitcnt lgkmcnt(3)
	v_mfma_f32_32x32x16_bf16 v[34:49], v[50:53], v[98:101], 0
	ds_read_b128 v[166:169], v184 offset:24576
	v_exp_f32_e32 v80, v80
	v_exp_f32_e32 v81, v81
	ds_read_b128 v[158:161], v184 offset:28672
	v_add_f32_e32 v193, v59, v79
	s_waitcnt lgkmcnt(4)
	v_mfma_f32_32x32x16_bf16 v[50:65], v[54:57], v[98:101], 0
	s_add_i32 m0, 0x3000, s8
	v_exp_f32_e32 v82, v82
	global_load_lds_dwordx4 v174, s[20:21]
	s_add_i32 m0, m0, 0x2000
	v_exp_f32_e32 v83, v83
	global_load_lds_dwordx4 v192, s[22:23]
	s_add_i32 m0, 0xa000, s12
	v_cvt_pk_bf16_f32 v132, v78, v79
	global_load_lds_dwordx4 v191, s[20:21]
	s_waitcnt lgkmcnt(3)
	v_mfma_f32_32x32x16_bf16 v[34:49], v[154:157], v[102:105], v[34:49]
	ds_read_b128 v[194:197], v185 offset:24576
	v_add_f32_e32 v154, v193, v80
	v_exp_f32_e32 v84, v84
	v_cvt_pk_bf16_f32 v133, v80, v81
	v_add_f32_e32 v193, v81, v154
	s_waitcnt lgkmcnt(3)
	v_mfma_f32_32x32x16_bf16 v[50:65], v[162:165], v[102:105], v[50:65]
	ds_read_b128 v[154:157], v185 offset:28672
	v_add_f32_e32 v193, v193, v82
	v_exp_f32_e32 v85, v85
	v_cvt_pk_bf16_f32 v126, v82, v83
	v_add_f32_e32 v193, v83, v193
	s_waitcnt lgkmcnt(3)
	v_mfma_f32_32x32x16_bf16 v[34:49], v[166:169], v[106:109], v[34:49]
	ds_read_b128 v[162:165], v187 offset:32768
	v_exp_f32_e32 v86, v86
	v_exp_f32_e32 v87, v87
	v_add_f32_e32 v193, v193, v84
	v_cvt_pk_bf16_f32 v127, v84, v85
	s_waitcnt lgkmcnt(3)
	v_mfma_f32_32x32x16_bf16 v[50:65], v[158:161], v[106:109], v[50:65]
	ds_read_b128 v[198:201], v187 offset:34816
	v_add_f32_e32 v166, v193, v85
	v_exp_f32_e32 v88, v88
	v_exp_f32_e32 v89, v89
	v_add_f32_e32 v166, v86, v166
	s_waitcnt lgkmcnt(3)
	v_mfma_f32_32x32x16_bf16 v[34:49], v[194:197], v[110:113], v[34:49]
	ds_read_b128 v[202:205], v188 offset:32768
	v_cvt_pk_bf16_f32 v128, v86, v87
	v_add_f32_e32 v159, v166, v87
	v_exp_f32_e32 v90, v90
	v_exp_f32_e32 v91, v91
	s_waitcnt lgkmcnt(3)
	v_mfma_f32_32x32x16_bf16 v[50:65], v[154:157], v[110:113], v[50:65]
	ds_read_b128 v[194:197], v188 offset:34816
	v_add_f32_e32 v158, v159, v88
	v_exp_f32_e32 v92, v92
	v_cvt_pk_bf16_f32 v129, v88, v89
	v_add_f32_e32 v158, v89, v158
	s_waitcnt lgkmcnt(3)
	v_mfma_f32_32x32x16_bf16 v[34:49], v[162:165], v[114:117], v[34:49]
	ds_read_b64_tr_b16 v[166:167], v189 offset:24576
	ds_read_b64_tr_b16 v[168:169], v189 offset:25088
	v_add_f32_e32 v154, v158, v90
	v_exp_f32_e32 v93, v93
	v_cvt_pk_bf16_f32 v122, v90, v91
	v_add_f32_e32 v154, v91, v154
	s_waitcnt lgkmcnt(4)
	v_mfma_f32_32x32x16_bf16 v[50:65], v[198:201], v[114:117], v[50:65]
	ds_read_b64_tr_b16 v[162:163], v189 offset:25600
	ds_read_b64_tr_b16 v[164:165], v189 offset:26112
	v_exp_f32_e32 v94, v94
	v_exp_f32_e32 v95, v95
	v_add_f32_e32 v154, v154, v92
	v_cvt_pk_bf16_f32 v123, v92, v93
	s_waitcnt lgkmcnt(5)
	v_mfma_f32_32x32x16_bf16 v[34:49], v[202:205], v[118:121], v[34:49]
	ds_read_b64_tr_b16 v[158:159], v189 offset:26624
	ds_read_b64_tr_b16 v[160:161], v189 offset:27136
	v_add_f32_e32 v154, v154, v93
	v_exp_f32_e32 v96, v96
	v_exp_f32_e32 v97, v97
	v_add_f32_e32 v193, v94, v154
	s_waitcnt lgkmcnt(6)
	v_mfma_f32_32x32x16_bf16 v[50:65], v[194:197], v[118:121], v[50:65]
	ds_read_b64_tr_b16 v[154:155], v189 offset:27648
	ds_read_b64_tr_b16 v[156:157], v189 offset:28160
	v_add_f32_e32 v125, v193, v95
	v_add_f32_e32 v193, v96, v125
	v_cvt_pk_bf16_f32 v124, v94, v95
	v_cvt_pk_bf16_f32 v125, v96, v97
	v_add_f32_e32 v193, v97, v193
	s_add_u32 s22, s22, 0x2000
	s_addc_u32 s23, s23, 0
	s_add_u32 s20, s20, 0x40000
	s_addc_u32 s21, s21, 0
	s_add_i32 s13, s13, 12
	s_cmp_le_i32 s13, 108
	s_cbranch_scc1 .Lmla_fast_w03
	v_subrev_u32_e32 v189, 0x8000, v189
	s_mov_b32 s2, 0x4000
	s_mov_b32 s17, 0x6000
	s_mov_b32 s26, 0x2000
	s_mov_b32 s14, 0x0
	s_mov_b32 s15, 0x9000
	s_branch .LBB0_1278
.Lmla_fast_w47:
	s_waitcnt vmcnt(4) lgkmcnt(0)
	s_barrier
	v_mfma_f32_32x32x16_bf16 v[2:17], v[134:137], v[166:169], v[2:17]
	ds_read_b64_tr_b16 v[66:67], v189 offset:28672
	ds_read_b64_tr_b16 v[68:69], v189 offset:29184
	v_exp_f32_e32 v34, v34
	v_exp_f32_e32 v35, v35
	v_exp_f32_e32 v36, v36
	v_mfma_f32_32x32x16_bf16 v[2:17], v[130:133], v[162:165], v[2:17]
	ds_read_b64_tr_b16 v[70:71], v189 offset:29696
	ds_read_b64_tr_b16 v[72:73], v189 offset:30208
	v_add_f32_e32 v74, v193, v34
	v_exp_f32_e32 v37, v37
	v_cvt_pk_bf16_f32 v150, v34, v35
	v_add_f32_e32 v78, v35, v74
	v_mfma_f32_32x32x16_bf16 v[2:17], v[126:129], v[158:161], v[2:17]
	ds_read_b64_tr_b16 v[74:75], v189 offset:30720
	ds_read_b64_tr_b16 v[76:77], v189 offset:31232
	v_exp_f32_e32 v38, v38
	v_exp_f32_e32 v39, v39
	v_add_f32_e32 v82, v78, v36
	v_cvt_pk_bf16_f32 v151, v36, v37
	v_mfma_f32_32x32x16_bf16 v[2:17], v[122:125], v[154:157], v[2:17]
	ds_read_b64_tr_b16 v[78:79], v189 offset:31744
	ds_read_b64_tr_b16 v[80:81], v189 offset:32256
	v_add_f32_e32 v82, v82, v37
	v_exp_f32_e32 v40, v40
	v_exp_f32_e32 v41, v41
	v_add_f32_e32 v86, v38, v82
	s_waitcnt lgkmcnt(6)
	v_mfma_f32_32x32x16_bf16 v[18:33], v[134:137], v[66:69], v[18:33]
	ds_read_b128 v[82:85], v182 offset:36864
	v_cvt_pk_bf16_f32 v152, v38, v39
	v_add_f32_e32 v90, v86, v39
	v_exp_f32_e32 v42, v42
	v_exp_f32_e32 v43, v43
	s_waitcnt lgkmcnt(5)
	v_mfma_f32_32x32x16_bf16 v[18:33], v[130:133], v[70:73], v[18:33]
	ds_read_b128 v[86:89], v182 offset:40960
	v_add_f32_e32 v66, v90, v40
	v_exp_f32_e32 v44, v44
	v_cvt_pk_bf16_f32 v153, v40, v41
	v_add_f32_e32 v66, v41, v66
	s_waitcnt lgkmcnt(4)
	v_mfma_f32_32x32x16_bf16 v[18:33], v[126:129], v[74:77], v[18:33]
	ds_read_b128 v[154:157], v183 offset:36864
	v_add_f32_e32 v66, v66, v42
	v_exp_f32_e32 v45, v45
	v_cvt_pk_bf16_f32 v146, v42, v43
	v_add_f32_e32 v66, v43, v66
	s_waitcnt lgkmcnt(3)
	v_mfma_f32_32x32x16_bf16 v[18:33], v[122:125], v[78:81], v[18:33]
	ds_read_b128 v[162:165], v183 offset:40960
	v_exp_f32_e32 v46, v46
	v_exp_f32_e32 v47, v47
	v_add_f32_e32 v66, v66, v44
	v_cvt_pk_bf16_f32 v147, v44, v45
	s_nop 0
	v_add_f32_e32 v66, v66, v45
	v_add_f32_e32 v91, v46, v66
	s_waitcnt lgkmcnt(3)
	v_mfma_f32_32x32x16_bf16 v[66:81], v[82:85], v[98:101], 0
	ds_read_b128 v[166:169], v184 offset:36864
	v_exp_f32_e32 v48, v48
	v_exp_f32_e32 v49, v49
	ds_read_b128 v[158:161], v184 offset:40960
	v_add_f32_e32 v193, v91, v47
	s_waitcnt lgkmcnt(4)
	v_mfma_f32_32x32x16_bf16 v[82:97], v[86:89], v[98:101], 0
	v_exp_f32_e32 v50, v50
	s_add_u32 s26, s20, 0xfffe0000
	s_addc_u32 s27, s21, -1
	s_add_i32 m0, 0x6000, s8
	v_exp_f32_e32 v51, v51
	global_load_lds_dwordx4 v174, s[26:27]
	s_mov_b32 m0, s12
	v_cvt_pk_bf16_f32 v148, v46, v47
	global_load_lds_dwordx4 v191, s[26:27]
	s_waitcnt lgkmcnt(3)
	v_mfma_f32_32x32x16_bf16 v[66:81], v[154:157], v[102:105], v[66:81]
	ds_read_b128 v[194:197], v185 offset:36864
	v_add_f32_e32 v193, v193, v48
	v_cvt_pk_bf16_f32 v149, v48, v49
	v_add_f32_e32 v193, v49, v193
	v_exp_f32_e32 v52, v52
	s_waitcnt lgkmcnt(3)
	v_mfma_f32_32x32x16_bf16 v[82:97], v[162:165], v[102:105], v[82:97]
	ds_read_b128 v[154:157], v185 offset:40960
	v_add_f32_e32 v193, v193, v50
	v_exp_f32_e32 v53, v53
	v_cvt_pk_bf16_f32 v142, v50, v51
	v_add_f32_e32 v193, v51, v193
	s_waitcnt lgkmcnt(3)
	v_mfma_f32_32x32x16_bf16 v[66:81], v[166:169], v[106:109], v[66:81]
	ds_read_b128 v[162:165], v187 offset:45056
	v_exp_f32_e32 v54, v54
	v_exp_f32_e32 v55, v55
	v_add_f32_e32 v193, v193, v52
	v_cvt_pk_bf16_f32 v143, v52, v53
	s_waitcnt lgkmcnt(3)
	v_mfma_f32_32x32x16_bf16 v[82:97], v[158:161], v[106:109], v[82:97]
	ds_read_b128 v[198:201], v187 offset:47104
	v_add_f32_e32 v166, v193, v53
	v_exp_f32_e32 v56, v56
	v_exp_f32_e32 v57, v57
	v_add_f32_e32 v166, v54, v166
	s_waitcnt lgkmcnt(3)
	v_mfma_f32_32x32x16_bf16 v[66:81], v[194:197], v[110:113], v[66:81]
	ds_read_b128 v[202:205], v188 offset:45056
	v_cvt_pk_bf16_f32 v144, v54, v55
	v_add_f32_e32 v159, v166, v55
	v_exp_f32_e32 v58, v58
	v_exp_f32_e32 v59, v59
	s_waitcnt lgkmcnt(3)
	v_mfma_f32_32x32x16_bf16 v[82:97], v[154:157], v[110:113], v[82:97]
	ds_read_b128 v[194:197], v188 offset:47104
	v_add_f32_e32 v158, v159, v56
	v_exp_f32_e32 v60, v60
	v_cvt_pk_bf16_f32 v145, v56, v57
	v_add_f32_e32 v158, v57, v158
	s_waitcnt lgkmcnt(3)
	v_mfma_f32_32x32x16_bf16 v[66:81], v[162:165], v[114:117], v[66:81]
	ds_read_b64_tr_b16 v[166:167], v189 offset:32768
	ds_read_b64_tr_b16 v[168:169], v189 offset:33280
	v_add_f32_e32 v154, v158, v58
	v_exp_f32_e32 v61, v61
	v_cvt_pk_bf16_f32 v138, v58, v59
	v_add_f32_e32 v154, v59, v154
	s_waitcnt lgkmcnt(4)
	v_mfma_f32_32x32x16_bf16 v[82:97], v[198:201], v[114:117], v[82:97]
	ds_read_b64_tr_b16 v[162:163], v189 offset:33792
	ds_read_b64_tr_b16 v[164:165], v189 offset:34304
	v_exp_f32_e32 v62, v62
	v_exp_f32_e32 v63, v63
	v_add_f32_e32 v154, v154, v60
	v_cvt_pk_bf16_f32 v139, v60, v61
	s_waitcnt lgkmcnt(5)
	v_mfma_f32_32x32x16_bf16 v[66:81], v[202:205], v[118:121], v[66:81]
	ds_read_b64_tr_b16 v[158:159], v189 offset:34816
	ds_read_b64_tr_b16 v[160:161], v189 offset:35328
	v_add_f32_e32 v154, v154, v61
	v_exp_f32_e32 v64, v64
	v_exp_f32_e32 v65, v65
	v_add_f32_e32 v198, v62, v154
	s_waitcnt lgkmcnt(6)
	v_mfma_f32_32x32x16_bf16 v[82:97], v[194:197], v[118:121], v[82:97]
	ds_read_b64_tr_b16 v[154:155], v189 offset:35840
	ds_read_b64_tr_b16 v[156:157], v189 offset:36352
	v_add_f32_e32 v141, v198, v63
	v_add_f32_e32 v198, v64, v141
	v_cvt_pk_bf16_f32 v140, v62, v63
	v_cvt_pk_bf16_f32 v141, v64, v65
	v_add_f32_e32 v194, v65, v198
	s_waitcnt vmcnt(4) lgkmcnt(0)
	s_barrier
	v_mfma_f32_32x32x16_bf16 v[2:17], v[150:153], v[166:169], v[2:17]
	ds_read_b64_tr_b16 v[34:35], v189 offset:36864
	ds_read_b64_tr_b16 v[36:37], v189 offset:37376
	v_exp_f32_e32 v66, v66
	v_exp_f32_e32 v67, v67
	v_exp_f32_e32 v68, v68
	v_mfma_f32_32x32x16_bf16 v[2:17], v[146:149], v[162:165], v[2:17]
	ds_read_b64_tr_b16 v[38:39], v189 offset:37888
	ds_read_b64_tr_b16 v[40:41], v189 offset:38400
	v_add_f32_e32 v42, v194, v66
	v_exp_f32_e32 v69, v69
	v_cvt_pk_bf16_f32 v134, v66, v67
	v_add_f32_e32 v46, v67, v42
	v_mfma_f32_32x32x16_bf16 v[2:17], v[142:145], v[158:161], v[2:17]
	ds_read_b64_tr_b16 v[42:43], v189 offset:38912
	ds_read_b64_tr_b16 v[44:45], v189 offset:39424
	v_exp_f32_e32 v70, v70
	v_exp_f32_e32 v71, v71
	v_add_f32_e32 v50, v46, v68
	v_cvt_pk_bf16_f32 v135, v68, v69
	v_mfma_f32_32x32x16_bf16 v[2:17], v[138:141], v[154:157], v[2:17]
	ds_read_b64_tr_b16 v[46:47], v189 offset:39936
	ds_read_b64_tr_b16 v[48:49], v189 offset:40448
	v_add_f32_e32 v50, v50, v69
	v_exp_f32_e32 v72, v72
	v_exp_f32_e32 v73, v73
	v_add_f32_e32 v54, v70, v50
	s_waitcnt lgkmcnt(6)
	v_mfma_f32_32x32x16_bf16 v[18:33], v[150:153], v[34:37], v[18:33]
	ds_read_b128 v[50:53], v182
	v_cvt_pk_bf16_f32 v136, v70, v71
	v_add_f32_e32 v58, v54, v71
	v_exp_f32_e32 v74, v74
	v_exp_f32_e32 v75, v75
	s_waitcnt lgkmcnt(5)
	v_mfma_f32_32x32x16_bf16 v[18:33], v[146:149], v[38:41], v[18:33]
	ds_read_b128 v[54:57], v182 offset:4096
	v_add_f32_e32 v34, v58, v72
	v_exp_f32_e32 v76, v76
	v_cvt_pk_bf16_f32 v137, v72, v73
	v_add_f32_e32 v34, v73, v34
	s_waitcnt lgkmcnt(4)
	v_mfma_f32_32x32x16_bf16 v[18:33], v[142:145], v[42:45], v[18:33]
	ds_read_b128 v[154:157], v183
	v_add_f32_e32 v34, v34, v74
	v_exp_f32_e32 v77, v77
	v_cvt_pk_bf16_f32 v130, v74, v75
	v_add_f32_e32 v34, v75, v34
	s_waitcnt lgkmcnt(3)
	v_mfma_f32_32x32x16_bf16 v[18:33], v[138:141], v[46:49], v[18:33]
	ds_read_b128 v[162:165], v183 offset:4096
	v_exp_f32_e32 v78, v78
	v_exp_f32_e32 v79, v79
	v_add_f32_e32 v34, v34, v76
	v_cvt_pk_bf16_f32 v131, v76, v77
	s_nop 0
	v_add_f32_e32 v34, v34, v77
	v_add_f32_e32 v59, v78, v34
	s_waitcnt lgkmcnt(3)
	v_mfma_f32_32x32x16_bf16 v[34:49], v[50:53], v[98:101], 0
	ds_read_b128 v[166:169], v184
	v_exp_f32_e32 v80, v80
	v_exp_f32_e32 v81, v81
	ds_read_b128 v[158:161], v184 offset:4096
	v_add_f32_e32 v193, v59, v79
	s_waitcnt lgkmcnt(4)
	v_mfma_f32_32x32x16_bf16 v[50:65], v[54:57], v[98:101], 0
	v_exp_f32_e32 v82, v82
	s_add_i32 m0, 0x9000, s8
	v_exp_f32_e32 v83, v83
	global_load_lds_dwordx4 v174, s[20:21]
	s_add_i32 m0, 0x2000, s12
	v_cvt_pk_bf16_f32 v132, v78, v79
	global_load_lds_dwordx4 v191, s[20:21]
	s_waitcnt lgkmcnt(3)
	v_mfma_f32_32x32x16_bf16 v[34:49], v[154:157], v[102:105], v[34:49]
	ds_read_b128 v[194:197], v185
	v_add_f32_e32 v154, v193, v80
	v_exp_f32_e32 v84, v84
	v_cvt_pk_bf16_f32 v133, v80, v81
	v_add_f32_e32 v193, v81, v154
	s_waitcnt lgkmcnt(3)
	v_mfma_f32_32x32x16_bf16 v[50:65], v[162:165], v[102:105], v[50:65]
	ds_read_b128 v[154:157], v185 offset:4096
	v_add_f32_e32 v193, v193, v82
	v_exp_f32_e32 v85, v85
	v_cvt_pk_bf16_f32 v126, v82, v83
	v_add_f32_e32 v193, v83, v193
	s_waitcnt lgkmcnt(3)
	v_mfma_f32_32x32x16_bf16 v[34:49], v[166:169], v[106:109], v[34:49]
	ds_read_b128 v[162:165], v187 offset:8192
	v_exp_f32_e32 v86, v86
	v_exp_f32_e32 v87, v87
	v_add_f32_e32 v193, v193, v84
	v_cvt_pk_bf16_f32 v127, v84, v85
	s_waitcnt lgkmcnt(3)
	v_mfma_f32_32x32x16_bf16 v[50:65], v[158:161], v[106:109], v[50:65]
	ds_read_b128 v[198:201], v187 offset:10240
	v_add_f32_e32 v166, v193, v85
	v_exp_f32_e32 v88, v88
	v_exp_f32_e32 v89, v89
	v_add_f32_e32 v166, v86, v166
	s_waitcnt lgkmcnt(3)
	v_mfma_f32_32x32x16_bf16 v[34:49], v[194:197], v[110:113], v[34:49]
	ds_read_b128 v[202:205], v188 offset:8192
	v_cvt_pk_bf16_f32 v128, v86, v87
	v_add_f32_e32 v159, v166, v87
	v_exp_f32_e32 v90, v90
	v_exp_f32_e32 v91, v91
	s_waitcnt lgkmcnt(3)
	v_mfma_f32_32x32x16_bf16 v[50:65], v[154:157], v[110:113], v[50:65]
	ds_read_b128 v[194:197], v188 offset:10240
	v_add_f32_e32 v158, v159, v88
	v_exp_f32_e32 v92, v92
	v_cvt_pk_bf16_f32 v129, v88, v89
	v_add_f32_e32 v158, v89, v158
	s_waitcnt lgkmcnt(3)
	v_mfma_f32_32x32x16_bf16 v[34:49], v[162:165], v[114:117], v[34:49]
	ds_read_b64_tr_b16 v[166:167], v189 offset:40960
	ds_read_b64_tr_b16 v[168:169], v189 offset:41472
	v_add_f32_e32 v154, v158, v90
	v_exp_f32_e32 v93, v93
	v_cvt_pk_bf16_f32 v122, v90, v91
	v_add_f32_e32 v154, v91, v154
	s_waitcnt lgkmcnt(4)
	v_mfma_f32_32x32x16_bf16 v[50:65], v[198:201], v[114:117], v[50:65]
	ds_read_b64_tr_b16 v[162:163], v189 offset:41984
	ds_read_b64_tr_b16 v[164:165], v189 offset:42496
	v_exp_f32_e32 v94, v94
	v_exp_f32_e32 v95, v95
	v_add_f32_e32 v154, v154, v92
	v_cvt_pk_bf16_f32 v123, v92, v93
	s_waitcnt lgkmcnt(5)
	v_mfma_f32_32x32x16_bf16 v[34:49], v[202:205], v[118:121], v[34:49]
	ds_read_b64_tr_b16 v[158:159], v189 offset:43008
	ds_read_b64_tr_b16 v[160:161], v189 offset:43520
	v_add_f32_e32 v154, v154, v93
	v_exp_f32_e32 v96, v96
	v_exp_f32_e32 v97, v97
	v_add_f32_e32 v193, v94, v154
	s_waitcnt lgkmcnt(6)
	v_mfma_f32_32x32x16_bf16 v[50:65], v[194:197], v[118:121], v[50:65]
	ds_read_b64_tr_b16 v[154:155], v189 offset:44032
	ds_read_b64_tr_b16 v[156:157], v189 offset:44544
	v_add_f32_e32 v125, v193, v95
	v_add_f32_e32 v193, v96, v125
	v_cvt_pk_bf16_f32 v124, v94, v95
	v_cvt_pk_bf16_f32 v125, v96, v97
	v_add_f32_e32 v193, v97, v193
	s_add_u32 s22, s22, 0x2000
	s_addc_u32 s23, s23, 0
	s_add_u32 s20, s20, 0x40000
	s_addc_u32 s21, s21, 0
	s_waitcnt vmcnt(4) lgkmcnt(0)
	s_barrier
	v_mfma_f32_32x32x16_bf16 v[2:17], v[134:137], v[166:169], v[2:17]
	ds_read_b64_tr_b16 v[66:67], v189 offset:45056
	ds_read_b64_tr_b16 v[68:69], v189 offset:45568
	v_exp_f32_e32 v34, v34
	v_exp_f32_e32 v35, v35
	v_exp_f32_e32 v36, v36
	v_mfma_f32_32x32x16_bf16 v[2:17], v[130:133], v[162:165], v[2:17]
	ds_read_b64_tr_b16 v[70:71], v189 offset:46080
	ds_read_b64_tr_b16 v[72:73], v189 offset:46592
	v_add_f32_e32 v74, v193, v34
	v_exp_f32_e32 v37, v37
	v_cvt_pk_bf16_f32 v150, v34, v35
	v_add_f32_e32 v78, v35, v74
	v_mfma_f32_32x32x16_bf16 v[2:17], v[126:129], v[158:161], v[2:17]
	ds_read_b64_tr_b16 v[74:75], v189 offset:47104
	ds_read_b64_tr_b16 v[76:77], v189 offset:47616
	v_exp_f32_e32 v38, v38
	v_exp_f32_e32 v39, v39
	v_add_f32_e32 v82, v78, v36
	v_cvt_pk_bf16_f32 v151, v36, v37
	v_mfma_f32_32x32x16_bf16 v[2:17], v[122:125], v[154:157], v[2:17]
	ds_read_b64_tr_b16 v[78:79], v189 offset:48128
	ds_read_b64_tr_b16 v[80:81], v189 offset:48640
	v_add_f32_e32 v82, v82, v37
	v_exp_f32_e32 v40, v40
	v_exp_f32_e32 v41, v41
	v_add_f32_e32 v86, v38, v82
	s_waitcnt lgkmcnt(6)
	v_mfma_f32_32x32x16_bf16 v[18:33], v[134:137], v[66:69], v[18:33]
	ds_read_b128 v[82:85], v182 offset:12288
	v_cvt_pk_bf16_f32 v152, v38, v39
	v_add_f32_e32 v90, v86, v39
	v_exp_f32_e32 v42, v42
	v_exp_f32_e32 v43, v43
	s_waitcnt lgkmcnt(5)
	v_mfma_f32_32x32x16_bf16 v[18:33], v[130:133], v[70:73], v[18:33]
	ds_read_b128 v[86:89], v182 offset:16384
	v_add_f32_e32 v66, v90, v40
	v_exp_f32_e32 v44, v44
	v_cvt_pk_bf16_f32 v153, v40, v41
	v_add_f32_e32 v66, v41, v66
	s_waitcnt lgkmcnt(4)
	v_mfma_f32_32x32x16_bf16 v[18:33], v[126:129], v[74:77], v[18:33]
	ds_read_b128 v[154:157], v183 offset:12288
	v_add_f32_e32 v66, v66, v42
	v_exp_f32_e32 v45, v45
	v_cvt_pk_bf16_f32 v146, v42, v43
	v_add_f32_e32 v66, v43, v66
	s_waitcnt lgkmcnt(3)
	v_mfma_f32_32x32x16_bf16 v[18:33], v[122:125], v[78:81], v[18:33]
	ds_read_b128 v[162:165], v183 offset:16384
	v_exp_f32_e32 v46, v46
	v_exp_f32_e32 v47, v47
	v_add_f32_e32 v66, v66, v44
	v_cvt_pk_bf16_f32 v147, v44, v45
	s_nop 0
	v_add_f32_e32 v66, v66, v45
	v_add_f32_e32 v91, v46, v66
	s_waitcnt lgkmcnt(3)
	v_mfma_f32_32x32x16_bf16 v[66:81], v[82:85], v[98:101], 0
	ds_read_b128 v[166:169], v184 offset:12288
	v_exp_f32_e32 v48, v48
	v_exp_f32_e32 v49, v49
	ds_read_b128 v[158:161], v184 offset:16384
	v_add_f32_e32 v193, v91, v47
	s_waitcnt lgkmcnt(4)
	v_mfma_f32_32x32x16_bf16 v[82:97], v[86:89], v[98:101], 0
	v_exp_f32_e32 v50, v50
	s_add_u32 s26, s20, 0xfffe0000
	s_addc_u32 s27, s21, -1
	s_mov_b32 m0, s8
	v_exp_f32_e32 v51, v51
	global_load_lds_dwordx4 v174, s[26:27]
	s_add_i32 m0, 0x4000, s12
	v_cvt_pk_bf16_f32 v148, v46, v47
	global_load_lds_dwordx4 v191, s[26:27]
	s_waitcnt lgkmcnt(3)
	v_mfma_f32_32x32x16_bf16 v[66:81], v[154:157], v[102:105], v[66:81]
	ds_read_b128 v[194:197], v185 offset:12288
	v_add_f32_e32 v193, v193, v48
	v_cvt_pk_bf16_f32 v149, v48, v49
	v_add_f32_e32 v193, v49, v193
	v_exp_f32_e32 v52, v52
	s_waitcnt lgkmcnt(3)
	v_mfma_f32_32x32x16_bf16 v[82:97], v[162:165], v[102:105], v[82:97]
	ds_read_b128 v[154:157], v185 offset:16384
	v_add_f32_e32 v193, v193, v50
	v_exp_f32_e32 v53, v53
	v_cvt_pk_bf16_f32 v142, v50, v51
	v_add_f32_e32 v193, v51, v193
	s_waitcnt lgkmcnt(3)
	v_mfma_f32_32x32x16_bf16 v[66:81], v[166:169], v[106:109], v[66:81]
	ds_read_b128 v[162:165], v187 offset:20480
	v_exp_f32_e32 v54, v54
	v_exp_f32_e32 v55, v55
	v_add_f32_e32 v193, v193, v52
	v_cvt_pk_bf16_f32 v143, v52, v53
	s_waitcnt lgkmcnt(3)
	v_mfma_f32_32x32x16_bf16 v[82:97], v[158:161], v[106:109], v[82:97]
	ds_read_b128 v[198:201], v187 offset:22528
	v_add_f32_e32 v166, v193, v53
	v_exp_f32_e32 v56, v56
	v_exp_f32_e32 v57, v57
	v_add_f32_e32 v166, v54, v166
	s_waitcnt lgkmcnt(3)
	v_mfma_f32_32x32x16_bf16 v[66:81], v[194:197], v[110:113], v[66:81]
	ds_read_b128 v[202:205], v188 offset:20480
	v_cvt_pk_bf16_f32 v144, v54, v55
	v_add_f32_e32 v159, v166, v55
	v_exp_f32_e32 v58, v58
	v_exp_f32_e32 v59, v59
	s_waitcnt lgkmcnt(3)
	v_mfma_f32_32x32x16_bf16 v[82:97], v[154:157], v[110:113], v[82:97]
	ds_read_b128 v[194:197], v188 offset:22528
	v_add_f32_e32 v158, v159, v56
	v_exp_f32_e32 v60, v60
	v_cvt_pk_bf16_f32 v145, v56, v57
	v_add_f32_e32 v158, v57, v158
	s_waitcnt lgkmcnt(3)
	v_mfma_f32_32x32x16_bf16 v[66:81], v[162:165], v[114:117], v[66:81]
	ds_read_b64_tr_b16 v[166:167], v189 offset:49152
	ds_read_b64_tr_b16 v[168:169], v189 offset:49664
	v_add_f32_e32 v154, v158, v58
	v_exp_f32_e32 v61, v61
	v_cvt_pk_bf16_f32 v138, v58, v59
	v_add_f32_e32 v154, v59, v154
	s_waitcnt lgkmcnt(4)
	v_mfma_f32_32x32x16_bf16 v[82:97], v[198:201], v[114:117], v[82:97]
	ds_read_b64_tr_b16 v[162:163], v189 offset:50176
	ds_read_b64_tr_b16 v[164:165], v189 offset:50688
	v_exp_f32_e32 v62, v62
	v_exp_f32_e32 v63, v63
	v_add_f32_e32 v154, v154, v60
	v_cvt_pk_bf16_f32 v139, v60, v61
	s_waitcnt lgkmcnt(5)
	v_mfma_f32_32x32x16_bf16 v[66:81], v[202:205], v[118:121], v[66:81]
	ds_read_b64_tr_b16 v[158:159], v189 offset:51200
	ds_read_b64_tr_b16 v[160:161], v189 offset:51712
	v_add_f32_e32 v154, v154, v61
	v_exp_f32_e32 v64, v64
	v_exp_f32_e32 v65, v65
	v_add_f32_e32 v198, v62, v154
	s_waitcnt lgkmcnt(6)
	v_mfma_f32_32x32x16_bf16 v[82:97], v[194:197], v[118:121], v[82:97]
	ds_read_b64_tr_b16 v[154:155], v189 offset:52224
	ds_read_b64_tr_b16 v[156:157], v189 offset:52736
	v_add_f32_e32 v141, v198, v63
	v_add_f32_e32 v198, v64, v141
	v_cvt_pk_bf16_f32 v140, v62, v63
	v_cvt_pk_bf16_f32 v141, v64, v65
	v_add_f32_e32 v194, v65, v198
	s_waitcnt vmcnt(4) lgkmcnt(0)
	s_barrier
	v_mfma_f32_32x32x16_bf16 v[2:17], v[150:153], v[166:169], v[2:17]
	ds_read_b64_tr_b16 v[34:35], v189 offset:53248
	ds_read_b64_tr_b16 v[36:37], v189 offset:53760
	v_exp_f32_e32 v66, v66
	v_exp_f32_e32 v67, v67
	v_exp_f32_e32 v68, v68
	v_mfma_f32_32x32x16_bf16 v[2:17], v[146:149], v[162:165], v[2:17]
	ds_read_b64_tr_b16 v[38:39], v189 offset:54272
	ds_read_b64_tr_b16 v[40:41], v189 offset:54784
	v_add_f32_e32 v42, v194, v66
	v_exp_f32_e32 v69, v69
	v_cvt_pk_bf16_f32 v134, v66, v67
	v_add_f32_e32 v46, v67, v42
	v_mfma_f32_32x32x16_bf16 v[2:17], v[142:145], v[158:161], v[2:17]
	ds_read_b64_tr_b16 v[42:43], v189 offset:55296
	ds_read_b64_tr_b16 v[44:45], v189 offset:55808
	v_exp_f32_e32 v70, v70
	v_exp_f32_e32 v71, v71
	v_add_f32_e32 v50, v46, v68
	v_cvt_pk_bf16_f32 v135, v68, v69
	v_mfma_f32_32x32x16_bf16 v[2:17], v[138:141], v[154:157], v[2:17]
	ds_read_b64_tr_b16 v[46:47], v189 offset:56320
	ds_read_b64_tr_b16 v[48:49], v189 offset:56832
	v_add_f32_e32 v50, v50, v69
	v_exp_f32_e32 v72, v72
	v_exp_f32_e32 v73, v73
	v_add_f32_e32 v54, v70, v50
	s_waitcnt lgkmcnt(6)
	v_mfma_f32_32x32x16_bf16 v[18:33], v[150:153], v[34:37], v[18:33]
	ds_read_b128 v[50:53], v182 offset:24576
	v_cvt_pk_bf16_f32 v136, v70, v71
	v_add_f32_e32 v58, v54, v71
	v_exp_f32_e32 v74, v74
	v_exp_f32_e32 v75, v75
	s_waitcnt lgkmcnt(5)
	v_mfma_f32_32x32x16_bf16 v[18:33], v[146:149], v[38:41], v[18:33]
	ds_read_b128 v[54:57], v182 offset:28672
	v_add_f32_e32 v34, v58, v72
	v_exp_f32_e32 v76, v76
	v_cvt_pk_bf16_f32 v137, v72, v73
	v_add_f32_e32 v34, v73, v34
	s_waitcnt lgkmcnt(4)
	v_mfma_f32_32x32x16_bf16 v[18:33], v[142:145], v[42:45], v[18:33]
	ds_read_b128 v[154:157], v183 offset:24576
	v_add_f32_e32 v34, v34, v74
	v_exp_f32_e32 v77, v77
	v_cvt_pk_bf16_f32 v130, v74, v75
	v_add_f32_e32 v34, v75, v34
	s_waitcnt lgkmcnt(3)
	v_mfma_f32_32x32x16_bf16 v[18:33], v[138:141], v[46:49], v[18:33]
	ds_read_b128 v[162:165], v183 offset:28672
	v_exp_f32_e32 v78, v78
	v_exp_f32_e32 v79, v79
	v_add_f32_e32 v34, v34, v76
	v_cvt_pk_bf16_f32 v131, v76, v77
	s_nop 0
	v_add_f32_e32 v34, v34, v77
	v_add_f32_e32 v59, v78, v34
	s_waitcnt lgkmcnt(3)
	v_mfma_f32_32x32x16_bf16 v[34:49], v[50:53], v[98:101], 0
	ds_read_b128 v[166:169], v184 offset:24576
	v_exp_f32_e32 v80, v80
	v_exp_f32_e32 v81, v81
	ds_read_b128 v[158:161], v184 offset:28672
	v_add_f32_e32 v193, v59, v79
	s_waitcnt lgkmcnt(4)
	v_mfma_f32_32x32x16_bf16 v[50:65], v[54:57], v[98:101], 0
	v_exp_f32_e32 v82, v82
	s_add_i32 m0, 0x3000, s8
	v_exp_f32_e32 v83, v83
	global_load_lds_dwordx4 v174, s[20:21]
	s_add_i32 m0, 0x6000, s12
	v_cvt_pk_bf16_f32 v132, v78, v79
	global_load_lds_dwordx4 v191, s[20:21]
	s_waitcnt lgkmcnt(3)
	v_mfma_f32_32x32x16_bf16 v[34:49], v[154:157], v[102:105], v[34:49]
	ds_read_b128 v[194:197], v185 offset:24576
	v_add_f32_e32 v154, v193, v80
	v_exp_f32_e32 v84, v84
	v_cvt_pk_bf16_f32 v133, v80, v81
	v_add_f32_e32 v193, v81, v154
	s_waitcnt lgkmcnt(3)
	v_mfma_f32_32x32x16_bf16 v[50:65], v[162:165], v[102:105], v[50:65]
	ds_read_b128 v[154:157], v185 offset:28672
	v_add_f32_e32 v193, v193, v82
	v_exp_f32_e32 v85, v85
	v_cvt_pk_bf16_f32 v126, v82, v83
	v_add_f32_e32 v193, v83, v193
	s_waitcnt lgkmcnt(3)
	v_mfma_f32_32x32x16_bf16 v[34:49], v[166:169], v[106:109], v[34:49]
	ds_read_b128 v[162:165], v187 offset:32768
	v_exp_f32_e32 v86, v86
	v_exp_f32_e32 v87, v87
	v_add_f32_e32 v193, v193, v84
	v_cvt_pk_bf16_f32 v127, v84, v85
	s_waitcnt lgkmcnt(3)
	v_mfma_f32_32x32x16_bf16 v[50:65], v[158:161], v[106:109], v[50:65]
	ds_read_b128 v[198:201], v187 offset:34816
	v_add_f32_e32 v166, v193, v85
	v_exp_f32_e32 v88, v88
	v_exp_f32_e32 v89, v89
	v_add_f32_e32 v166, v86, v166
	s_waitcnt lgkmcnt(3)
	v_mfma_f32_32x32x16_bf16 v[34:49], v[194:197], v[110:113], v[34:49]
	ds_read_b128 v[202:205], v188 offset:32768
	v_cvt_pk_bf16_f32 v128, v86, v87
	v_add_f32_e32 v159, v166, v87
	v_exp_f32_e32 v90, v90
	v_exp_f32_e32 v91, v91
	s_waitcnt lgkmcnt(3)
	v_mfma_f32_32x32x16_bf16 v[50:65], v[154:157], v[110:113], v[50:65]
	ds_read_b128 v[194:197], v188 offset:34816
	v_add_f32_e32 v158, v159, v88
	v_exp_f32_e32 v92, v92
	v_cvt_pk_bf16_f32 v129, v88, v89
	v_add_f32_e32 v158, v89, v158
	s_waitcnt lgkmcnt(3)
	v_mfma_f32_32x32x16_bf16 v[34:49], v[162:165], v[114:117], v[34:49]
	ds_read_b64_tr_b16 v[166:167], v189 offset:57344
	ds_read_b64_tr_b16 v[168:169], v189 offset:57856
	v_add_f32_e32 v154, v158, v90
	v_exp_f32_e32 v93, v93
	v_cvt_pk_bf16_f32 v122, v90, v91
	v_add_f32_e32 v154, v91, v154
	s_waitcnt lgkmcnt(4)
	v_mfma_f32_32x32x16_bf16 v[50:65], v[198:201], v[114:117], v[50:65]
	ds_read_b64_tr_b16 v[162:163], v189 offset:58368
	ds_read_b64_tr_b16 v[164:165], v189 offset:58880
	v_exp_f32_e32 v94, v94
	v_exp_f32_e32 v95, v95
	v_add_f32_e32 v154, v154, v92
	v_cvt_pk_bf16_f32 v123, v92, v93
	s_waitcnt lgkmcnt(5)
	v_mfma_f32_32x32x16_bf16 v[34:49], v[202:205], v[118:121], v[34:49]
	ds_read_b64_tr_b16 v[158:159], v189 offset:59392
	ds_read_b64_tr_b16 v[160:161], v189 offset:59904
	v_add_f32_e32 v154, v154, v93
	v_exp_f32_e32 v96, v96
	v_exp_f32_e32 v97, v97
	v_add_f32_e32 v193, v94, v154
	s_waitcnt lgkmcnt(6)
	v_mfma_f32_32x32x16_bf16 v[50:65], v[194:197], v[118:121], v[50:65]
	ds_read_b64_tr_b16 v[154:155], v189 offset:60416
	ds_read_b64_tr_b16 v[156:157], v189 offset:60928
	v_add_f32_e32 v125, v193, v95
	v_add_f32_e32 v193, v96, v125
	v_cvt_pk_bf16_f32 v124, v94, v95
	v_cvt_pk_bf16_f32 v125, v96, v97
	v_add_f32_e32 v193, v97, v193
	s_add_u32 s22, s22, 0x2000
	s_addc_u32 s23, s23, 0
	s_add_u32 s20, s20, 0x40000
	s_addc_u32 s21, s21, 0
	s_waitcnt vmcnt(4) lgkmcnt(0)
	s_barrier
	v_mfma_f32_32x32x16_bf16 v[2:17], v[134:137], v[166:169], v[2:17]
	ds_read_b64_tr_b16 v[66:67], v189 offset:61440
	ds_read_b64_tr_b16 v[68:69], v189 offset:61952
	v_exp_f32_e32 v34, v34
	v_exp_f32_e32 v35, v35
	v_exp_f32_e32 v36, v36
	v_mfma_f32_32x32x16_bf16 v[2:17], v[130:133], v[162:165], v[2:17]
	ds_read_b64_tr_b16 v[70:71], v189 offset:62464
	ds_read_b64_tr_b16 v[72:73], v189 offset:62976
	v_add_f32_e32 v74, v193, v34
	v_exp_f32_e32 v37, v37
	v_cvt_pk_bf16_f32 v150, v34, v35
	v_add_f32_e32 v78, v35, v74
	v_mfma_f32_32x32x16_bf16 v[2:17], v[126:129], v[158:161], v[2:17]
	ds_read_b64_tr_b16 v[74:75], v189 offset:63488
	ds_read_b64_tr_b16 v[76:77], v189 offset:64000
	v_exp_f32_e32 v38, v38
	v_exp_f32_e32 v39, v39
	v_add_f32_e32 v82, v78, v36
	v_cvt_pk_bf16_f32 v151, v36, v37
	v_mfma_f32_32x32x16_bf16 v[2:17], v[122:125], v[154:157], v[2:17]
	ds_read_b64_tr_b16 v[78:79], v189 offset:64512
	ds_read_b64_tr_b16 v[80:81], v189 offset:65024
	v_add_f32_e32 v82, v82, v37
	v_exp_f32_e32 v40, v40
	v_exp_f32_e32 v41, v41
	v_add_f32_e32 v86, v38, v82
	s_waitcnt lgkmcnt(6)
	v_mfma_f32_32x32x16_bf16 v[18:33], v[134:137], v[66:69], v[18:33]
	ds_read_b128 v[82:85], v182 offset:36864
	v_cvt_pk_bf16_f32 v152, v38, v39
	v_add_f32_e32 v90, v86, v39
	v_exp_f32_e32 v42, v42
	v_exp_f32_e32 v43, v43
	s_waitcnt lgkmcnt(5)
	v_mfma_f32_32x32x16_bf16 v[18:33], v[130:133], v[70:73], v[18:33]
	ds_read_b128 v[86:89], v182 offset:40960
	v_add_f32_e32 v66, v90, v40
	v_exp_f32_e32 v44, v44
	v_cvt_pk_bf16_f32 v153, v40, v41
	v_add_f32_e32 v66, v41, v66
	s_waitcnt lgkmcnt(4)
	v_mfma_f32_32x32x16_bf16 v[18:33], v[126:129], v[74:77], v[18:33]
	ds_read_b128 v[154:157], v183 offset:36864
	v_add_f32_e32 v66, v66, v42
	v_exp_f32_e32 v45, v45
	v_cvt_pk_bf16_f32 v146, v42, v43
	v_add_f32_e32 v66, v43, v66
	s_waitcnt lgkmcnt(3)
	v_mfma_f32_32x32x16_bf16 v[18:33], v[122:125], v[78:81], v[18:33]
	ds_read_b128 v[162:165], v183 offset:40960
	v_exp_f32_e32 v46, v46
	v_exp_f32_e32 v47, v47
	v_add_f32_e32 v66, v66, v44
	v_cvt_pk_bf16_f32 v147, v44, v45
	s_nop 0
	v_add_f32_e32 v66, v66, v45
	v_add_f32_e32 v91, v46, v66
	s_waitcnt lgkmcnt(3)
	v_mfma_f32_32x32x16_bf16 v[66:81], v[82:85], v[98:101], 0
	ds_read_b128 v[166:169], v184 offset:36864
	v_exp_f32_e32 v48, v48
	v_exp_f32_e32 v49, v49
	ds_read_b128 v[158:161], v184 offset:40960
	v_add_f32_e32 v193, v91, v47
	s_waitcnt lgkmcnt(4)
	v_mfma_f32_32x32x16_bf16 v[82:97], v[86:89], v[98:101], 0
	v_exp_f32_e32 v50, v50
	s_add_u32 s26, s20, 0xfffe0000
	s_addc_u32 s27, s21, -1
	s_add_i32 m0, 0x6000, s8
	v_exp_f32_e32 v51, v51
	global_load_lds_dwordx4 v174, s[26:27]
	s_add_i32 m0, 0x8000, s12
	v_cvt_pk_bf16_f32 v148, v46, v47
	global_load_lds_dwordx4 v191, s[26:27]
	s_waitcnt lgkmcnt(3)
	v_mfma_f32_32x32x16_bf16 v[66:81], v[154:157], v[102:105], v[66:81]
	ds_read_b128 v[194:197], v185 offset:36864
	v_add_f32_e32 v193, v193, v48
	v_cvt_pk_bf16_f32 v149, v48, v49
	v_add_f32_e32 v193, v49, v193
	v_exp_f32_e32 v52, v52
	s_waitcnt lgkmcnt(3)
	v_mfma_f32_32x32x16_bf16 v[82:97], v[162:165], v[102:105], v[82:97]
	ds_read_b128 v[154:157], v185 offset:40960
	v_add_f32_e32 v193, v193, v50
	v_exp_f32_e32 v53, v53
	v_cvt_pk_bf16_f32 v142, v50, v51
	v_add_f32_e32 v193, v51, v193
	s_waitcnt lgkmcnt(3)
	v_mfma_f32_32x32x16_bf16 v[66:81], v[166:169], v[106:109], v[66:81]
	ds_read_b128 v[162:165], v187 offset:45056
	v_exp_f32_e32 v54, v54
	v_exp_f32_e32 v55, v55
	v_add_f32_e32 v193, v193, v52
	v_cvt_pk_bf16_f32 v143, v52, v53
	s_waitcnt lgkmcnt(3)
	v_mfma_f32_32x32x16_bf16 v[82:97], v[158:161], v[106:109], v[82:97]
	ds_read_b128 v[198:201], v187 offset:47104
	v_add_f32_e32 v166, v193, v53
	v_exp_f32_e32 v56, v56
	v_exp_f32_e32 v57, v57
	v_add_f32_e32 v166, v54, v166
	s_waitcnt lgkmcnt(3)
	v_mfma_f32_32x32x16_bf16 v[66:81], v[194:197], v[110:113], v[66:81]
	ds_read_b128 v[202:205], v188 offset:45056
	v_cvt_pk_bf16_f32 v144, v54, v55
	v_add_f32_e32 v159, v166, v55
	v_exp_f32_e32 v58, v58
	v_exp_f32_e32 v59, v59
	s_waitcnt lgkmcnt(3)
	v_mfma_f32_32x32x16_bf16 v[82:97], v[154:157], v[110:113], v[82:97]
	ds_read_b128 v[194:197], v188 offset:47104
	v_add_f32_e32 v158, v159, v56
	v_exp_f32_e32 v60, v60
	v_cvt_pk_bf16_f32 v145, v56, v57
	v_add_f32_e32 v158, v57, v158
	s_waitcnt lgkmcnt(3)
	v_mfma_f32_32x32x16_bf16 v[66:81], v[162:165], v[114:117], v[66:81]
	ds_read_b64_tr_b16 v[166:167], v189 offset:16384
	ds_read_b64_tr_b16 v[168:169], v189 offset:16896
	v_add_f32_e32 v154, v158, v58
	v_exp_f32_e32 v61, v61
	v_cvt_pk_bf16_f32 v138, v58, v59
	v_add_f32_e32 v154, v59, v154
	s_waitcnt lgkmcnt(4)
	v_mfma_f32_32x32x16_bf16 v[82:97], v[198:201], v[114:117], v[82:97]
	ds_read_b64_tr_b16 v[162:163], v189 offset:17408
	ds_read_b64_tr_b16 v[164:165], v189 offset:17920
	v_exp_f32_e32 v62, v62
	v_exp_f32_e32 v63, v63
	v_add_f32_e32 v154, v154, v60
	v_cvt_pk_bf16_f32 v139, v60, v61
	s_waitcnt lgkmcnt(5)
	v_mfma_f32_32x32x16_bf16 v[66:81], v[202:205], v[118:121], v[66:81]
	ds_read_b64_tr_b16 v[158:159], v189 offset:18432
	ds_read_b64_tr_b16 v[160:161], v189 offset:18944
	v_add_f32_e32 v154, v154, v61
	v_exp_f32_e32 v64, v64
	v_exp_f32_e32 v65, v65
	v_add_f32_e32 v198, v62, v154
	s_waitcnt lgkmcnt(6)
	v_mfma_f32_32x32x16_bf16 v[82:97], v[194:197], v[118:121], v[82:97]
	ds_read_b64_tr_b16 v[154:155], v189 offset:19456
	ds_read_b64_tr_b16 v[156:157], v189 offset:19968
	v_add_f32_e32 v141, v198, v63
	v_add_f32_e32 v198, v64, v141
	v_cvt_pk_bf16_f32 v140, v62, v63
	v_cvt_pk_bf16_f32 v141, v64, v65
	v_add_f32_e32 v194, v65, v198
	s_waitcnt vmcnt(4) lgkmcnt(0)
	s_barrier
	v_mfma_f32_32x32x16_bf16 v[2:17], v[150:153], v[166:169], v[2:17]
	ds_read_b64_tr_b16 v[34:35], v189 offset:20480
	ds_read_b64_tr_b16 v[36:37], v189 offset:20992
	v_exp_f32_e32 v66, v66
	v_exp_f32_e32 v67, v67
	v_exp_f32_e32 v68, v68
	v_mfma_f32_32x32x16_bf16 v[2:17], v[146:149], v[162:165], v[2:17]
	ds_read_b64_tr_b16 v[38:39], v189 offset:21504
	ds_read_b64_tr_b16 v[40:41], v189 offset:22016
	v_add_f32_e32 v42, v194, v66
	v_exp_f32_e32 v69, v69
	v_cvt_pk_bf16_f32 v134, v66, v67
	v_add_f32_e32 v46, v67, v42
	v_mfma_f32_32x32x16_bf16 v[2:17], v[142:145], v[158:161], v[2:17]
	ds_read_b64_tr_b16 v[42:43], v189 offset:22528
	ds_read_b64_tr_b16 v[44:45], v189 offset:23040
	v_exp_f32_e32 v70, v70
	v_exp_f32_e32 v71, v71
	v_add_f32_e32 v50, v46, v68
	v_cvt_pk_bf16_f32 v135, v68, v69
	v_mfma_f32_32x32x16_bf16 v[2:17], v[138:141], v[154:157], v[2:17]
	ds_read_b64_tr_b16 v[46:47], v189 offset:23552
	ds_read_b64_tr_b16 v[48:49], v189 offset:24064
	v_add_f32_e32 v50, v50, v69
	v_exp_f32_e32 v72, v72
	v_exp_f32_e32 v73, v73
	v_add_f32_e32 v54, v70, v50
	s_waitcnt lgkmcnt(6)
	v_mfma_f32_32x32x16_bf16 v[18:33], v[150:153], v[34:37], v[18:33]
	ds_read_b128 v[50:53], v182
	v_cvt_pk_bf16_f32 v136, v70, v71
	v_add_f32_e32 v58, v54, v71
	v_exp_f32_e32 v74, v74
	v_exp_f32_e32 v75, v75
	s_waitcnt lgkmcnt(5)
	v_mfma_f32_32x32x16_bf16 v[18:33], v[146:149], v[38:41], v[18:33]
	ds_read_b128 v[54:57], v182 offset:4096
	v_add_f32_e32 v34, v58, v72
	v_exp_f32_e32 v76, v76
	v_cvt_pk_bf16_f32 v137, v72, v73
	v_add_f32_e32 v34, v73, v34
	s_waitcnt lgkmcnt(4)
	v_mfma_f32_32x32x16_bf16 v[18:33], v[142:145], v[42:45], v[18:33]
	ds_read_b128 v[154:157], v183
	v_add_f32_e32 v34, v34, v74
	v_exp_f32_e32 v77, v77
	v_cvt_pk_bf16_f32 v130, v74, v75
	v_add_f32_e32 v34, v75, v34
	s_waitcnt lgkmcnt(3)
	v_mfma_f32_32x32x16_bf16 v[18:33], v[138:141], v[46:49], v[18:33]
	ds_read_b128 v[162:165], v183 offset:4096
	v_exp_f32_e32 v78, v78
	v_exp_f32_e32 v79, v79
	v_add_f32_e32 v34, v34, v76
	v_cvt_pk_bf16_f32 v131, v76, v77
	s_nop 0
	v_add_f32_e32 v34, v34, v77
	v_add_f32_e32 v59, v78, v34
	s_waitcnt lgkmcnt(3)
	v_mfma_f32_32x32x16_bf16 v[34:49], v[50:53], v[98:101], 0
	ds_read_b128 v[166:169], v184
	v_exp_f32_e32 v80, v80
	v_exp_f32_e32 v81, v81
	ds_read_b128 v[158:161], v184 offset:4096
	v_add_f32_e32 v193, v59, v79
	s_waitcnt lgkmcnt(4)
	v_mfma_f32_32x32x16_bf16 v[50:65], v[54:57], v[98:101], 0
	v_exp_f32_e32 v82, v82
	s_add_i32 m0, 0x9000, s8
	v_exp_f32_e32 v83, v83
	global_load_lds_dwordx4 v174, s[20:21]
	s_add_i32 m0, 0xa000, s12
	v_cvt_pk_bf16_f32 v132, v78, v79
	global_load_lds_dwordx4 v191, s[20:21]
	s_waitcnt lgkmcnt(3)
	v_mfma_f32_32x32x16_bf16 v[34:49], v[154:157], v[102:105], v[34:49]
	ds_read_b128 v[194:197], v185
	v_add_f32_e32 v154, v193, v80
	v_exp_f32_e32 v84, v84
	v_cvt_pk_bf16_f32 v133, v80, v81
	v_add_f32_e32 v193, v81, v154
	s_waitcnt lgkmcnt(3)
	v_mfma_f32_32x32x16_bf16 v[50:65], v[162:165], v[102:105], v[50:65]
	ds_read_b128 v[154:157], v185 offset:4096
	v_add_f32_e32 v193, v193, v82
	v_exp_f32_e32 v85, v85
	v_cvt_pk_bf16_f32 v126, v82, v83
	v_add_f32_e32 v193, v83, v193
	s_waitcnt lgkmcnt(3)
	v_mfma_f32_32x32x16_bf16 v[34:49], v[166:169], v[106:109], v[34:49]
	ds_read_b128 v[162:165], v187 offset:8192
	v_exp_f32_e32 v86, v86
	v_exp_f32_e32 v87, v87
	v_add_f32_e32 v193, v193, v84
	v_cvt_pk_bf16_f32 v127, v84, v85
	s_waitcnt lgkmcnt(3)
	v_mfma_f32_32x32x16_bf16 v[50:65], v[158:161], v[106:109], v[50:65]
	ds_read_b128 v[198:201], v187 offset:10240
	v_add_f32_e32 v166, v193, v85
	v_exp_f32_e32 v88, v88
	v_exp_f32_e32 v89, v89
	v_add_f32_e32 v166, v86, v166
	s_waitcnt lgkmcnt(3)
	v_mfma_f32_32x32x16_bf16 v[34:49], v[194:197], v[110:113], v[34:49]
	ds_read_b128 v[202:205], v188 offset:8192
	v_cvt_pk_bf16_f32 v128, v86, v87
	v_add_f32_e32 v159, v166, v87
	v_exp_f32_e32 v90, v90
	v_exp_f32_e32 v91, v91
	s_waitcnt lgkmcnt(3)
	v_mfma_f32_32x32x16_bf16 v[50:65], v[154:157], v[110:113], v[50:65]
	ds_read_b128 v[194:197], v188 offset:10240
	v_add_f32_e32 v158, v159, v88
	v_exp_f32_e32 v92, v92
	v_cvt_pk_bf16_f32 v129, v88, v89
	v_add_f32_e32 v158, v89, v158
	s_waitcnt lgkmcnt(3)
	v_mfma_f32_32x32x16_bf16 v[34:49], v[162:165], v[114:117], v[34:49]
	ds_read_b64_tr_b16 v[166:167], v189 offset:24576
	ds_read_b64_tr_b16 v[168:169], v189 offset:25088
	v_add_f32_e32 v154, v158, v90
	v_exp_f32_e32 v93, v93
	v_cvt_pk_bf16_f32 v122, v90, v91
	v_add_f32_e32 v154, v91, v154
	s_waitcnt lgkmcnt(4)
	v_mfma_f32_32x32x16_bf16 v[50:65], v[198:201], v[114:117], v[50:65]
	ds_read_b64_tr_b16 v[162:163], v189 offset:25600
	ds_read_b64_tr_b16 v[164:165], v189 offset:26112
	v_exp_f32_e32 v94, v94
	v_exp_f32_e32 v95, v95
	v_add_f32_e32 v154, v154, v92
	v_cvt_pk_bf16_f32 v123, v92, v93
	s_waitcnt lgkmcnt(5)
	v_mfma_f32_32x32x16_bf16 v[34:49], v[202:205], v[118:121], v[34:49]
	ds_read_b64_tr_b16 v[158:159], v189 offset:26624
	ds_read_b64_tr_b16 v[160:161], v189 offset:27136
	v_add_f32_e32 v154, v154, v93
	v_exp_f32_e32 v96, v96
	v_exp_f32_e32 v97, v97
	v_add_f32_e32 v193, v94, v154
	s_waitcnt lgkmcnt(6)
	v_mfma_f32_32x32x16_bf16 v[50:65], v[194:197], v[118:121], v[50:65]
	ds_read_b64_tr_b16 v[154:155], v189 offset:27648
	ds_read_b64_tr_b16 v[156:157], v189 offset:28160
	v_add_f32_e32 v125, v193, v95
	v_add_f32_e32 v193, v96, v125
	v_cvt_pk_bf16_f32 v124, v94, v95
	v_cvt_pk_bf16_f32 v125, v96, v97
	v_add_f32_e32 v193, v97, v193
	s_add_u32 s22, s22, 0x2000
	s_addc_u32 s23, s23, 0
	s_add_u32 s20, s20, 0x40000
	s_addc_u32 s21, s21, 0
	s_waitcnt vmcnt(4) lgkmcnt(0)
	s_barrier
	v_mfma_f32_32x32x16_bf16 v[2:17], v[134:137], v[166:169], v[2:17]
	ds_read_b64_tr_b16 v[66:67], v189 offset:28672
	ds_read_b64_tr_b16 v[68:69], v189 offset:29184
	v_exp_f32_e32 v34, v34
	v_exp_f32_e32 v35, v35
	v_exp_f32_e32 v36, v36
	v_mfma_f32_32x32x16_bf16 v[2:17], v[130:133], v[162:165], v[2:17]
	ds_read_b64_tr_b16 v[70:71], v189 offset:29696
	ds_read_b64_tr_b16 v[72:73], v189 offset:30208
	v_add_f32_e32 v74, v193, v34
	v_exp_f32_e32 v37, v37
	v_cvt_pk_bf16_f32 v150, v34, v35
	v_add_f32_e32 v78, v35, v74
	v_mfma_f32_32x32x16_bf16 v[2:17], v[126:129], v[158:161], v[2:17]
	ds_read_b64_tr_b16 v[74:75], v189 offset:30720
	ds_read_b64_tr_b16 v[76:77], v189 offset:31232
	v_exp_f32_e32 v38, v38
	v_exp_f32_e32 v39, v39
	v_add_f32_e32 v82, v78, v36
	v_cvt_pk_bf16_f32 v151, v36, v37
	v_mfma_f32_32x32x16_bf16 v[2:17], v[122:125], v[154:157], v[2:17]
	ds_read_b64_tr_b16 v[78:79], v189 offset:31744
	ds_read_b64_tr_b16 v[80:81], v189 offset:32256
	v_add_f32_e32 v82, v82, v37
	v_exp_f32_e32 v40, v40
	v_exp_f32_e32 v41, v41
	v_add_f32_e32 v86, v38, v82
	s_waitcnt lgkmcnt(6)
	v_mfma_f32_32x32x16_bf16 v[18:33], v[134:137], v[66:69], v[18:33]
	ds_read_b128 v[82:85], v182 offset:12288
	v_cvt_pk_bf16_f32 v152, v38, v39
	v_add_f32_e32 v90, v86, v39
	v_exp_f32_e32 v42, v42
	v_exp_f32_e32 v43, v43
	s_waitcnt lgkmcnt(5)
	v_mfma_f32_32x32x16_bf16 v[18:33], v[130:133], v[70:73], v[18:33]
	ds_read_b128 v[86:89], v182 offset:16384
	v_add_f32_e32 v66, v90, v40
	v_exp_f32_e32 v44, v44
	v_cvt_pk_bf16_f32 v153, v40, v41
	v_add_f32_e32 v66, v41, v66
	s_waitcnt lgkmcnt(4)
	v_mfma_f32_32x32x16_bf16 v[18:33], v[126:129], v[74:77], v[18:33]
	ds_read_b128 v[154:157], v183 offset:12288
	v_add_f32_e32 v66, v66, v42
	v_exp_f32_e32 v45, v45
	v_cvt_pk_bf16_f32 v146, v42, v43
	v_add_f32_e32 v66, v43, v66
	s_waitcnt lgkmcnt(3)
	v_mfma_f32_32x32x16_bf16 v[18:33], v[122:125], v[78:81], v[18:33]
	ds_read_b128 v[162:165], v183 offset:16384
	v_exp_f32_e32 v46, v46
	v_exp_f32_e32 v47, v47
	v_add_f32_e32 v66, v66, v44
	v_cvt_pk_bf16_f32 v147, v44, v45
	s_nop 0
	v_add_f32_e32 v66, v66, v45
	v_add_f32_e32 v91, v46, v66
	s_waitcnt lgkmcnt(3)
	v_mfma_f32_32x32x16_bf16 v[66:81], v[82:85], v[98:101], 0
	ds_read_b128 v[166:169], v184 offset:12288
	v_exp_f32_e32 v48, v48
	v_exp_f32_e32 v49, v49
	ds_read_b128 v[158:161], v184 offset:16384
	v_add_f32_e32 v193, v91, v47
	s_waitcnt lgkmcnt(4)
	v_mfma_f32_32x32x16_bf16 v[82:97], v[86:89], v[98:101], 0
	v_exp_f32_e32 v50, v50
	s_add_u32 s26, s20, 0xfffe0000
	s_addc_u32 s27, s21, -1
	s_mov_b32 m0, s8
	v_exp_f32_e32 v51, v51
	global_load_lds_dwordx4 v174, s[26:27]
	s_mov_b32 m0, s12
	v_cvt_pk_bf16_f32 v148, v46, v47
	global_load_lds_dwordx4 v191, s[26:27]
	s_waitcnt lgkmcnt(3)
	v_mfma_f32_32x32x16_bf16 v[66:81], v[154:157], v[102:105], v[66:81]
	ds_read_b128 v[194:197], v185 offset:12288
	v_add_f32_e32 v193, v193, v48
	v_cvt_pk_bf16_f32 v149, v48, v49
	v_add_f32_e32 v193, v49, v193
	v_exp_f32_e32 v52, v52
	s_waitcnt lgkmcnt(3)
	v_mfma_f32_32x32x16_bf16 v[82:97], v[162:165], v[102:105], v[82:97]
	ds_read_b128 v[154:157], v185 offset:16384
	v_add_f32_e32 v193, v193, v50
	v_exp_f32_e32 v53, v53
	v_cvt_pk_bf16_f32 v142, v50, v51
	v_add_f32_e32 v193, v51, v193
	s_waitcnt lgkmcnt(3)
	v_mfma_f32_32x32x16_bf16 v[66:81], v[166:169], v[106:109], v[66:81]
	ds_read_b128 v[162:165], v187 offset:20480
	v_exp_f32_e32 v54, v54
	v_exp_f32_e32 v55, v55
	v_add_f32_e32 v193, v193, v52
	v_cvt_pk_bf16_f32 v143, v52, v53
	s_waitcnt lgkmcnt(3)
	v_mfma_f32_32x32x16_bf16 v[82:97], v[158:161], v[106:109], v[82:97]
	ds_read_b128 v[198:201], v187 offset:22528
	v_add_f32_e32 v166, v193, v53
	v_exp_f32_e32 v56, v56
	v_exp_f32_e32 v57, v57
	v_add_f32_e32 v166, v54, v166
	s_waitcnt lgkmcnt(3)
	v_mfma_f32_32x32x16_bf16 v[66:81], v[194:197], v[110:113], v[66:81]
	ds_read_b128 v[202:205], v188 offset:20480
	v_cvt_pk_bf16_f32 v144, v54, v55
	v_add_f32_e32 v159, v166, v55
	v_exp_f32_e32 v58, v58
	v_exp_f32_e32 v59, v59
	s_waitcnt lgkmcnt(3)
	v_mfma_f32_32x32x16_bf16 v[82:97], v[154:157], v[110:113], v[82:97]
	ds_read_b128 v[194:197], v188 offset:22528
	v_add_f32_e32 v158, v159, v56
	v_exp_f32_e32 v60, v60
	v_cvt_pk_bf16_f32 v145, v56, v57
	v_add_f32_e32 v158, v57, v158
	s_waitcnt lgkmcnt(3)
	v_mfma_f32_32x32x16_bf16 v[66:81], v[162:165], v[114:117], v[66:81]
	ds_read_b64_tr_b16 v[166:167], v189 offset:32768
	ds_read_b64_tr_b16 v[168:169], v189 offset:33280
	v_add_f32_e32 v154, v158, v58
	v_exp_f32_e32 v61, v61
	v_cvt_pk_bf16_f32 v138, v58, v59
	v_add_f32_e32 v154, v59, v154
	s_waitcnt lgkmcnt(4)
	v_mfma_f32_32x32x16_bf16 v[82:97], v[198:201], v[114:117], v[82:97]
	ds_read_b64_tr_b16 v[162:163], v189 offset:33792
	ds_read_b64_tr_b16 v[164:165], v189 offset:34304
	v_exp_f32_e32 v62, v62
	v_exp_f32_e32 v63, v63
	v_add_f32_e32 v154, v154, v60
	v_cvt_pk_bf16_f32 v139, v60, v61
	s_waitcnt lgkmcnt(5)
	v_mfma_f32_32x32x16_bf16 v[66:81], v[202:205], v[118:121], v[66:81]
	ds_read_b64_tr_b16 v[158:159], v189 offset:34816
	ds_read_b64_tr_b16 v[160:161], v189 offset:35328
	v_add_f32_e32 v154, v154, v61
	v_exp_f32_e32 v64, v64
	v_exp_f32_e32 v65, v65
	v_add_f32_e32 v198, v62, v154
	s_waitcnt lgkmcnt(6)
	v_mfma_f32_32x32x16_bf16 v[82:97], v[194:197], v[118:121], v[82:97]
	ds_read_b64_tr_b16 v[154:155], v189 offset:35840
	ds_read_b64_tr_b16 v[156:157], v189 offset:36352
	v_add_f32_e32 v141, v198, v63
	v_add_f32_e32 v198, v64, v141
	v_cvt_pk_bf16_f32 v140, v62, v63
	v_cvt_pk_bf16_f32 v141, v64, v65
	v_add_f32_e32 v194, v65, v198
	s_waitcnt vmcnt(4) lgkmcnt(0)
	s_barrier
	v_mfma_f32_32x32x16_bf16 v[2:17], v[150:153], v[166:169], v[2:17]
	ds_read_b64_tr_b16 v[34:35], v189 offset:36864
	ds_read_b64_tr_b16 v[36:37], v189 offset:37376
	v_exp_f32_e32 v66, v66
	v_exp_f32_e32 v67, v67
	v_exp_f32_e32 v68, v68
	v_mfma_f32_32x32x16_bf16 v[2:17], v[146:149], v[162:165], v[2:17]
	ds_read_b64_tr_b16 v[38:39], v189 offset:37888
	ds_read_b64_tr_b16 v[40:41], v189 offset:38400
	v_add_f32_e32 v42, v194, v66
	v_exp_f32_e32 v69, v69
	v_cvt_pk_bf16_f32 v134, v66, v67
	v_add_f32_e32 v46, v67, v42
	v_mfma_f32_32x32x16_bf16 v[2:17], v[142:145], v[158:161], v[2:17]
	ds_read_b64_tr_b16 v[42:43], v189 offset:38912
	ds_read_b64_tr_b16 v[44:45], v189 offset:39424
	v_exp_f32_e32 v70, v70
	v_exp_f32_e32 v71, v71
	v_add_f32_e32 v50, v46, v68
	v_cvt_pk_bf16_f32 v135, v68, v69
	v_mfma_f32_32x32x16_bf16 v[2:17], v[138:141], v[154:157], v[2:17]
	ds_read_b64_tr_b16 v[46:47], v189 offset:39936
	ds_read_b64_tr_b16 v[48:49], v189 offset:40448
	v_add_f32_e32 v50, v50, v69
	v_exp_f32_e32 v72, v72
	v_exp_f32_e32 v73, v73
	v_add_f32_e32 v54, v70, v50
	s_waitcnt lgkmcnt(6)
	v_mfma_f32_32x32x16_bf16 v[18:33], v[150:153], v[34:37], v[18:33]
	ds_read_b128 v[50:53], v182 offset:24576
	v_cvt_pk_bf16_f32 v136, v70, v71
	v_add_f32_e32 v58, v54, v71
	v_exp_f32_e32 v74, v74
	v_exp_f32_e32 v75, v75
	s_waitcnt lgkmcnt(5)
	v_mfma_f32_32x32x16_bf16 v[18:33], v[146:149], v[38:41], v[18:33]
	ds_read_b128 v[54:57], v182 offset:28672
	v_add_f32_e32 v34, v58, v72
	v_exp_f32_e32 v76, v76
	v_cvt_pk_bf16_f32 v137, v72, v73
	v_add_f32_e32 v34, v73, v34
	s_waitcnt lgkmcnt(4)
	v_mfma_f32_32x32x16_bf16 v[18:33], v[142:145], v[42:45], v[18:33]
	ds_read_b128 v[154:157], v183 offset:24576
	v_add_f32_e32 v34, v34, v74
	v_exp_f32_e32 v77, v77
	v_cvt_pk_bf16_f32 v130, v74, v75
	v_add_f32_e32 v34, v75, v34
	s_waitcnt lgkmcnt(3)
	v_mfma_f32_32x32x16_bf16 v[18:33], v[138:141], v[46:49], v[18:33]
	ds_read_b128 v[162:165], v183 offset:28672
	v_exp_f32_e32 v78, v78
	v_exp_f32_e32 v79, v79
	v_add_f32_e32 v34, v34, v76
	v_cvt_pk_bf16_f32 v131, v76, v77
	s_nop 0
	v_add_f32_e32 v34, v34, v77
	v_add_f32_e32 v59, v78, v34
	s_waitcnt lgkmcnt(3)
	v_mfma_f32_32x32x16_bf16 v[34:49], v[50:53], v[98:101], 0
	ds_read_b128 v[166:169], v184 offset:24576
	v_exp_f32_e32 v80, v80
	v_exp_f32_e32 v81, v81
	ds_read_b128 v[158:161], v184 offset:28672
	v_add_f32_e32 v193, v59, v79
	s_waitcnt lgkmcnt(4)
	v_mfma_f32_32x32x16_bf16 v[50:65], v[54:57], v[98:101], 0
	v_exp_f32_e32 v82, v82
	s_add_i32 m0, 0x3000, s8
	v_exp_f32_e32 v83, v83
	global_load_lds_dwordx4 v174, s[20:21]
	s_add_i32 m0, 0x2000, s12
	v_cvt_pk_bf16_f32 v132, v78, v79
	global_load_lds_dwordx4 v191, s[20:21]
	s_waitcnt lgkmcnt(3)
	v_mfma_f32_32x32x16_bf16 v[34:49], v[154:157], v[102:105], v[34:49]
	ds_read_b128 v[194:197], v185 offset:24576
	v_add_f32_e32 v154, v193, v80
	v_exp_f32_e32 v84, v84
	v_cvt_pk_bf16_f32 v133, v80, v81
	v_add_f32_e32 v193, v81, v154
	s_waitcnt lgkmcnt(3)
	v_mfma_f32_32x32x16_bf16 v[50:65], v[162:165], v[102:105], v[50:65]
	ds_read_b128 v[154:157], v185 offset:28672
	v_add_f32_e32 v193, v193, v82
	v_exp_f32_e32 v85, v85
	v_cvt_pk_bf16_f32 v126, v82, v83
	v_add_f32_e32 v193, v83, v193
	s_waitcnt lgkmcnt(3)
	v_mfma_f32_32x32x16_bf16 v[34:49], v[166:169], v[106:109], v[34:49]
	ds_read_b128 v[162:165], v187 offset:32768
	v_exp_f32_e32 v86, v86
	v_exp_f32_e32 v87, v87
	v_add_f32_e32 v193, v193, v84
	v_cvt_pk_bf16_f32 v127, v84, v85
	s_waitcnt lgkmcnt(3)
	v_mfma_f32_32x32x16_bf16 v[50:65], v[158:161], v[106:109], v[50:65]
	ds_read_b128 v[198:201], v187 offset:34816
	v_add_f32_e32 v166, v193, v85
	v_exp_f32_e32 v88, v88
	v_exp_f32_e32 v89, v89
	v_add_f32_e32 v166, v86, v166
	s_waitcnt lgkmcnt(3)
	v_mfma_f32_32x32x16_bf16 v[34:49], v[194:197], v[110:113], v[34:49]
	ds_read_b128 v[202:205], v188 offset:32768
	v_cvt_pk_bf16_f32 v128, v86, v87
	v_add_f32_e32 v159, v166, v87
	v_exp_f32_e32 v90, v90
	v_exp_f32_e32 v91, v91
	s_waitcnt lgkmcnt(3)
	v_mfma_f32_32x32x16_bf16 v[50:65], v[154:157], v[110:113], v[50:65]
	ds_read_b128 v[194:197], v188 offset:34816
	v_add_f32_e32 v158, v159, v88
	v_exp_f32_e32 v92, v92
	v_cvt_pk_bf16_f32 v129, v88, v89
	v_add_f32_e32 v158, v89, v158
	s_waitcnt lgkmcnt(3)
	v_mfma_f32_32x32x16_bf16 v[34:49], v[162:165], v[114:117], v[34:49]
	ds_read_b64_tr_b16 v[166:167], v189 offset:40960
	ds_read_b64_tr_b16 v[168:169], v189 offset:41472
	v_add_f32_e32 v154, v158, v90
	v_exp_f32_e32 v93, v93
	v_cvt_pk_bf16_f32 v122, v90, v91
	v_add_f32_e32 v154, v91, v154
	s_waitcnt lgkmcnt(4)
	v_mfma_f32_32x32x16_bf16 v[50:65], v[198:201], v[114:117], v[50:65]
	ds_read_b64_tr_b16 v[162:163], v189 offset:41984
	ds_read_b64_tr_b16 v[164:165], v189 offset:42496
	v_exp_f32_e32 v94, v94
	v_exp_f32_e32 v95, v95
	v_add_f32_e32 v154, v154, v92
	v_cvt_pk_bf16_f32 v123, v92, v93
	s_waitcnt lgkmcnt(5)
	v_mfma_f32_32x32x16_bf16 v[34:49], v[202:205], v[118:121], v[34:49]
	ds_read_b64_tr_b16 v[158:159], v189 offset:43008
	ds_read_b64_tr_b16 v[160:161], v189 offset:43520
	v_add_f32_e32 v154, v154, v93
	v_exp_f32_e32 v96, v96
	v_exp_f32_e32 v97, v97
	v_add_f32_e32 v193, v94, v154
	s_waitcnt lgkmcnt(6)
	v_mfma_f32_32x32x16_bf16 v[50:65], v[194:197], v[118:121], v[50:65]
	ds_read_b64_tr_b16 v[154:155], v189 offset:44032
	ds_read_b64_tr_b16 v[156:157], v189 offset:44544
	v_add_f32_e32 v125, v193, v95
	v_add_f32_e32 v193, v96, v125
	v_cvt_pk_bf16_f32 v124, v94, v95
	v_cvt_pk_bf16_f32 v125, v96, v97
	v_add_f32_e32 v193, v97, v193
	s_add_u32 s22, s22, 0x2000
	s_addc_u32 s23, s23, 0
	s_add_u32 s20, s20, 0x40000
	s_addc_u32 s21, s21, 0
	s_waitcnt vmcnt(4) lgkmcnt(0)
	s_barrier
	v_mfma_f32_32x32x16_bf16 v[2:17], v[134:137], v[166:169], v[2:17]
	ds_read_b64_tr_b16 v[66:67], v189 offset:45056
	ds_read_b64_tr_b16 v[68:69], v189 offset:45568
	v_exp_f32_e32 v34, v34
	v_exp_f32_e32 v35, v35
	v_exp_f32_e32 v36, v36
	v_mfma_f32_32x32x16_bf16 v[2:17], v[130:133], v[162:165], v[2:17]
	ds_read_b64_tr_b16 v[70:71], v189 offset:46080
	ds_read_b64_tr_b16 v[72:73], v189 offset:46592
	v_add_f32_e32 v74, v193, v34
	v_exp_f32_e32 v37, v37
	v_cvt_pk_bf16_f32 v150, v34, v35
	v_add_f32_e32 v78, v35, v74
	v_mfma_f32_32x32x16_bf16 v[2:17], v[126:129], v[158:161], v[2:17]
	ds_read_b64_tr_b16 v[74:75], v189 offset:47104
	ds_read_b64_tr_b16 v[76:77], v189 offset:47616
	v_exp_f32_e32 v38, v38
	v_exp_f32_e32 v39, v39
	v_add_f32_e32 v82, v78, v36
	v_cvt_pk_bf16_f32 v151, v36, v37
	v_mfma_f32_32x32x16_bf16 v[2:17], v[122:125], v[154:157], v[2:17]
	ds_read_b64_tr_b16 v[78:79], v189 offset:48128
	ds_read_b64_tr_b16 v[80:81], v189 offset:48640
	v_add_f32_e32 v82, v82, v37
	v_exp_f32_e32 v40, v40
	v_exp_f32_e32 v41, v41
	v_add_f32_e32 v86, v38, v82
	s_waitcnt lgkmcnt(6)
	v_mfma_f32_32x32x16_bf16 v[18:33], v[134:137], v[66:69], v[18:33]
	ds_read_b128 v[82:85], v182 offset:36864
	v_cvt_pk_bf16_f32 v152, v38, v39
	v_add_f32_e32 v90, v86, v39
	v_exp_f32_e32 v42, v42
	v_exp_f32_e32 v43, v43
	s_waitcnt lgkmcnt(5)
	v_mfma_f32_32x32x16_bf16 v[18:33], v[130:133], v[70:73], v[18:33]
	ds_read_b128 v[86:89], v182 offset:40960
	v_add_f32_e32 v66, v90, v40
	v_exp_f32_e32 v44, v44
	v_cvt_pk_bf16_f32 v153, v40, v41
	v_add_f32_e32 v66, v41, v66
	s_waitcnt lgkmcnt(4)
	v_mfma_f32_32x32x16_bf16 v[18:33], v[126:129], v[74:77], v[18:33]
	ds_read_b128 v[154:157], v183 offset:36864
	v_add_f32_e32 v66, v66, v42
	v_exp_f32_e32 v45, v45
	v_cvt_pk_bf16_f32 v146, v42, v43
	v_add_f32_e32 v66, v43, v66
	s_waitcnt lgkmcnt(3)
	v_mfma_f32_32x32x16_bf16 v[18:33], v[122:125], v[78:81], v[18:33]
	ds_read_b128 v[162:165], v183 offset:40960
	v_exp_f32_e32 v46, v46
	v_exp_f32_e32 v47, v47
	v_add_f32_e32 v66, v66, v44
	v_cvt_pk_bf16_f32 v147, v44, v45
	s_nop 0
	v_add_f32_e32 v66, v66, v45
	v_add_f32_e32 v91, v46, v66
	s_waitcnt lgkmcnt(3)
	v_mfma_f32_32x32x16_bf16 v[66:81], v[82:85], v[98:101], 0
	ds_read_b128 v[166:169], v184 offset:36864
	v_exp_f32_e32 v48, v48
	v_exp_f32_e32 v49, v49
	ds_read_b128 v[158:161], v184 offset:40960
	v_add_f32_e32 v193, v91, v47
	s_waitcnt lgkmcnt(4)
	v_mfma_f32_32x32x16_bf16 v[82:97], v[86:89], v[98:101], 0
	v_exp_f32_e32 v50, v50
	s_add_u32 s26, s20, 0xfffe0000
	s_addc_u32 s27, s21, -1
	s_add_i32 m0, 0x6000, s8
	v_exp_f32_e32 v51, v51
	global_load_lds_dwordx4 v174, s[26:27]
	s_add_i32 m0, 0x4000, s12
	v_cvt_pk_bf16_f32 v148, v46, v47
	global_load_lds_dwordx4 v191, s[26:27]
	s_waitcnt lgkmcnt(3)
	v_mfma_f32_32x32x16_bf16 v[66:81], v[154:157], v[102:105], v[66:81]
	ds_read_b128 v[194:197], v185 offset:36864
	v_add_f32_e32 v193, v193, v48
	v_cvt_pk_bf16_f32 v149, v48, v49
	v_add_f32_e32 v193, v49, v193
	v_exp_f32_e32 v52, v52
	s_waitcnt lgkmcnt(3)
	v_mfma_f32_32x32x16_bf16 v[82:97], v[162:165], v[102:105], v[82:97]
	ds_read_b128 v[154:157], v185 offset:40960
	v_add_f32_e32 v193, v193, v50
	v_exp_f32_e32 v53, v53
	v_cvt_pk_bf16_f32 v142, v50, v51
	v_add_f32_e32 v193, v51, v193
	s_waitcnt lgkmcnt(3)
	v_mfma_f32_32x32x16_bf16 v[66:81], v[166:169], v[106:109], v[66:81]
	ds_read_b128 v[162:165], v187 offset:45056
	v_exp_f32_e32 v54, v54
	v_exp_f32_e32 v55, v55
	v_add_f32_e32 v193, v193, v52
	v_cvt_pk_bf16_f32 v143, v52, v53
	s_waitcnt lgkmcnt(3)
	v_mfma_f32_32x32x16_bf16 v[82:97], v[158:161], v[106:109], v[82:97]
	ds_read_b128 v[198:201], v187 offset:47104
	v_add_f32_e32 v166, v193, v53
	v_exp_f32_e32 v56, v56
	v_exp_f32_e32 v57, v57
	v_add_f32_e32 v166, v54, v166
	s_waitcnt lgkmcnt(3)
	v_mfma_f32_32x32x16_bf16 v[66:81], v[194:197], v[110:113], v[66:81]
	ds_read_b128 v[202:205], v188 offset:45056
	v_cvt_pk_bf16_f32 v144, v54, v55
	v_add_f32_e32 v159, v166, v55
	v_exp_f32_e32 v58, v58
	v_exp_f32_e32 v59, v59
	s_waitcnt lgkmcnt(3)
	v_mfma_f32_32x32x16_bf16 v[82:97], v[154:157], v[110:113], v[82:97]
	ds_read_b128 v[194:197], v188 offset:47104
	v_add_f32_e32 v158, v159, v56
	v_exp_f32_e32 v60, v60
	v_cvt_pk_bf16_f32 v145, v56, v57
	v_add_f32_e32 v158, v57, v158
	s_waitcnt lgkmcnt(3)
	v_mfma_f32_32x32x16_bf16 v[66:81], v[162:165], v[114:117], v[66:81]
	ds_read_b64_tr_b16 v[166:167], v189 offset:49152
	ds_read_b64_tr_b16 v[168:169], v189 offset:49664
	v_add_f32_e32 v154, v158, v58
	v_exp_f32_e32 v61, v61
	v_cvt_pk_bf16_f32 v138, v58, v59
	v_add_f32_e32 v154, v59, v154
	s_waitcnt lgkmcnt(4)
	v_mfma_f32_32x32x16_bf16 v[82:97], v[198:201], v[114:117], v[82:97]
	ds_read_b64_tr_b16 v[162:163], v189 offset:50176
	ds_read_b64_tr_b16 v[164:165], v189 offset:50688
	v_exp_f32_e32 v62, v62
	v_exp_f32_e32 v63, v63
	v_add_f32_e32 v154, v154, v60
	v_cvt_pk_bf16_f32 v139, v60, v61
	s_waitcnt lgkmcnt(5)
	v_mfma_f32_32x32x16_bf16 v[66:81], v[202:205], v[118:121], v[66:81]
	ds_read_b64_tr_b16 v[158:159], v189 offset:51200
	ds_read_b64_tr_b16 v[160:161], v189 offset:51712
	v_add_f32_e32 v154, v154, v61
	v_exp_f32_e32 v64, v64
	v_exp_f32_e32 v65, v65
	v_add_f32_e32 v198, v62, v154
	s_waitcnt lgkmcnt(6)
	v_mfma_f32_32x32x16_bf16 v[82:97], v[194:197], v[118:121], v[82:97]
	ds_read_b64_tr_b16 v[154:155], v189 offset:52224
	ds_read_b64_tr_b16 v[156:157], v189 offset:52736
	v_add_f32_e32 v141, v198, v63
	v_add_f32_e32 v198, v64, v141
	v_cvt_pk_bf16_f32 v140, v62, v63
	v_cvt_pk_bf16_f32 v141, v64, v65
	v_add_f32_e32 v194, v65, v198
	s_waitcnt vmcnt(4) lgkmcnt(0)
	s_barrier
	v_mfma_f32_32x32x16_bf16 v[2:17], v[150:153], v[166:169], v[2:17]
	ds_read_b64_tr_b16 v[34:35], v189 offset:53248
	ds_read_b64_tr_b16 v[36:37], v189 offset:53760
	v_exp_f32_e32 v66, v66
	v_exp_f32_e32 v67, v67
	v_exp_f32_e32 v68, v68
	v_mfma_f32_32x32x16_bf16 v[2:17], v[146:149], v[162:165], v[2:17]
	ds_read_b64_tr_b16 v[38:39], v189 offset:54272
	ds_read_b64_tr_b16 v[40:41], v189 offset:54784
	v_add_f32_e32 v42, v194, v66
	v_exp_f32_e32 v69, v69
	v_cvt_pk_bf16_f32 v134, v66, v67
	v_add_f32_e32 v46, v67, v42
	v_mfma_f32_32x32x16_bf16 v[2:17], v[142:145], v[158:161], v[2:17]
	ds_read_b64_tr_b16 v[42:43], v189 offset:55296
	ds_read_b64_tr_b16 v[44:45], v189 offset:55808
	v_exp_f32_e32 v70, v70
	v_exp_f32_e32 v71, v71
	v_add_f32_e32 v50, v46, v68
	v_cvt_pk_bf16_f32 v135, v68, v69
	v_mfma_f32_32x32x16_bf16 v[2:17], v[138:141], v[154:157], v[2:17]
	ds_read_b64_tr_b16 v[46:47], v189 offset:56320
	ds_read_b64_tr_b16 v[48:49], v189 offset:56832
	v_add_f32_e32 v50, v50, v69
	v_exp_f32_e32 v72, v72
	v_exp_f32_e32 v73, v73
	v_add_f32_e32 v54, v70, v50
	s_waitcnt lgkmcnt(6)
	v_mfma_f32_32x32x16_bf16 v[18:33], v[150:153], v[34:37], v[18:33]
	ds_read_b128 v[50:53], v182
	v_cvt_pk_bf16_f32 v136, v70, v71
	v_add_f32_e32 v58, v54, v71
	v_exp_f32_e32 v74, v74
	v_exp_f32_e32 v75, v75
	s_waitcnt lgkmcnt(5)
	v_mfma_f32_32x32x16_bf16 v[18:33], v[146:149], v[38:41], v[18:33]
	ds_read_b128 v[54:57], v182 offset:4096
	v_add_f32_e32 v34, v58, v72
	v_exp_f32_e32 v76, v76
	v_cvt_pk_bf16_f32 v137, v72, v73
	v_add_f32_e32 v34, v73, v34
	s_waitcnt lgkmcnt(4)
	v_mfma_f32_32x32x16_bf16 v[18:33], v[142:145], v[42:45], v[18:33]
	ds_read_b128 v[154:157], v183
	v_add_f32_e32 v34, v34, v74
	v_exp_f32_e32 v77, v77
	v_cvt_pk_bf16_f32 v130, v74, v75
	v_add_f32_e32 v34, v75, v34
	s_waitcnt lgkmcnt(3)
	v_mfma_f32_32x32x16_bf16 v[18:33], v[138:141], v[46:49], v[18:33]
	ds_read_b128 v[162:165], v183 offset:4096
	v_exp_f32_e32 v78, v78
	v_exp_f32_e32 v79, v79
	v_add_f32_e32 v34, v34, v76
	v_cvt_pk_bf16_f32 v131, v76, v77
	s_nop 0
	v_add_f32_e32 v34, v34, v77
	v_add_f32_e32 v59, v78, v34
	s_waitcnt lgkmcnt(3)
	v_mfma_f32_32x32x16_bf16 v[34:49], v[50:53], v[98:101], 0
	ds_read_b128 v[166:169], v184
	v_exp_f32_e32 v80, v80
	v_exp_f32_e32 v81, v81
	ds_read_b128 v[158:161], v184 offset:4096
	v_add_f32_e32 v193, v59, v79
	s_waitcnt lgkmcnt(4)
	v_mfma_f32_32x32x16_bf16 v[50:65], v[54:57], v[98:101], 0
	v_exp_f32_e32 v82, v82
	s_add_i32 m0, 0x9000, s8
	v_exp_f32_e32 v83, v83
	global_load_lds_dwordx4 v174, s[20:21]
	s_add_i32 m0, 0x6000, s12
	v_cvt_pk_bf16_f32 v132, v78, v79
	global_load_lds_dwordx4 v191, s[20:21]
	s_waitcnt lgkmcnt(3)
	v_mfma_f32_32x32x16_bf16 v[34:49], v[154:157], v[102:105], v[34:49]
	ds_read_b128 v[194:197], v185
	v_add_f32_e32 v154, v193, v80
	v_exp_f32_e32 v84, v84
	v_cvt_pk_bf16_f32 v133, v80, v81
	v_add_f32_e32 v193, v81, v154
	s_waitcnt lgkmcnt(3)
	v_mfma_f32_32x32x16_bf16 v[50:65], v[162:165], v[102:105], v[50:65]
	ds_read_b128 v[154:157], v185 offset:4096
	v_add_f32_e32 v193, v193, v82
	v_exp_f32_e32 v85, v85
	v_cvt_pk_bf16_f32 v126, v82, v83
	v_add_f32_e32 v193, v83, v193
	s_waitcnt lgkmcnt(3)
	v_mfma_f32_32x32x16_bf16 v[34:49], v[166:169], v[106:109], v[34:49]
	ds_read_b128 v[162:165], v187 offset:8192
	v_exp_f32_e32 v86, v86
	v_exp_f32_e32 v87, v87
	v_add_f32_e32 v193, v193, v84
	v_cvt_pk_bf16_f32 v127, v84, v85
	s_waitcnt lgkmcnt(3)
	v_mfma_f32_32x32x16_bf16 v[50:65], v[158:161], v[106:109], v[50:65]
	ds_read_b128 v[198:201], v187 offset:10240
	v_add_f32_e32 v166, v193, v85
	v_exp_f32_e32 v88, v88
	v_exp_f32_e32 v89, v89
	v_add_f32_e32 v166, v86, v166
	s_waitcnt lgkmcnt(3)
	v_mfma_f32_32x32x16_bf16 v[34:49], v[194:197], v[110:113], v[34:49]
	ds_read_b128 v[202:205], v188 offset:8192
	v_cvt_pk_bf16_f32 v128, v86, v87
	v_add_f32_e32 v159, v166, v87
	v_exp_f32_e32 v90, v90
	v_exp_f32_e32 v91, v91
	s_waitcnt lgkmcnt(3)
	v_mfma_f32_32x32x16_bf16 v[50:65], v[154:157], v[110:113], v[50:65]
	ds_read_b128 v[194:197], v188 offset:10240
	v_add_f32_e32 v158, v159, v88
	v_exp_f32_e32 v92, v92
	v_cvt_pk_bf16_f32 v129, v88, v89
	v_add_f32_e32 v158, v89, v158
	s_waitcnt lgkmcnt(3)
	v_mfma_f32_32x32x16_bf16 v[34:49], v[162:165], v[114:117], v[34:49]
	ds_read_b64_tr_b16 v[166:167], v189 offset:57344
	ds_read_b64_tr_b16 v[168:169], v189 offset:57856
	v_add_f32_e32 v154, v158, v90
	v_exp_f32_e32 v93, v93
	v_cvt_pk_bf16_f32 v122, v90, v91
	v_add_f32_e32 v154, v91, v154
	s_waitcnt lgkmcnt(4)
	v_mfma_f32_32x32x16_bf16 v[50:65], v[198:201], v[114:117], v[50:65]
	ds_read_b64_tr_b16 v[162:163], v189 offset:58368
	ds_read_b64_tr_b16 v[164:165], v189 offset:58880
	v_exp_f32_e32 v94, v94
	v_exp_f32_e32 v95, v95
	v_add_f32_e32 v154, v154, v92
	v_cvt_pk_bf16_f32 v123, v92, v93
	s_waitcnt lgkmcnt(5)
	v_mfma_f32_32x32x16_bf16 v[34:49], v[202:205], v[118:121], v[34:49]
	ds_read_b64_tr_b16 v[158:159], v189 offset:59392
	ds_read_b64_tr_b16 v[160:161], v189 offset:59904
	v_add_f32_e32 v154, v154, v93
	v_exp_f32_e32 v96, v96
	v_exp_f32_e32 v97, v97
	v_add_f32_e32 v193, v94, v154
	s_waitcnt lgkmcnt(6)
	v_mfma_f32_32x32x16_bf16 v[50:65], v[194:197], v[118:121], v[50:65]
	ds_read_b64_tr_b16 v[154:155], v189 offset:60416
	ds_read_b64_tr_b16 v[156:157], v189 offset:60928
	v_add_f32_e32 v125, v193, v95
	v_add_f32_e32 v193, v96, v125
	v_cvt_pk_bf16_f32 v124, v94, v95
	v_cvt_pk_bf16_f32 v125, v96, v97
	v_add_f32_e32 v193, v97, v193
	s_add_u32 s22, s22, 0x2000
	s_addc_u32 s23, s23, 0
	s_add_u32 s20, s20, 0x40000
	s_addc_u32 s21, s21, 0
	s_waitcnt vmcnt(4) lgkmcnt(0)
	s_barrier
	v_mfma_f32_32x32x16_bf16 v[2:17], v[134:137], v[166:169], v[2:17]
	ds_read_b64_tr_b16 v[66:67], v189 offset:61440
	ds_read_b64_tr_b16 v[68:69], v189 offset:61952
	v_exp_f32_e32 v34, v34
	v_exp_f32_e32 v35, v35
	v_exp_f32_e32 v36, v36
	v_mfma_f32_32x32x16_bf16 v[2:17], v[130:133], v[162:165], v[2:17]
	ds_read_b64_tr_b16 v[70:71], v189 offset:62464
	ds_read_b64_tr_b16 v[72:73], v189 offset:62976
	v_add_f32_e32 v74, v193, v34
	v_exp_f32_e32 v37, v37
	v_cvt_pk_bf16_f32 v150, v34, v35
	v_add_f32_e32 v78, v35, v74
	v_mfma_f32_32x32x16_bf16 v[2:17], v[126:129], v[158:161], v[2:17]
	ds_read_b64_tr_b16 v[74:75], v189 offset:63488
	ds_read_b64_tr_b16 v[76:77], v189 offset:64000
	v_exp_f32_e32 v38, v38
	v_exp_f32_e32 v39, v39
	v_add_f32_e32 v82, v78, v36
	v_cvt_pk_bf16_f32 v151, v36, v37
	v_mfma_f32_32x32x16_bf16 v[2:17], v[122:125], v[154:157], v[2:17]
	ds_read_b64_tr_b16 v[78:79], v189 offset:64512
	ds_read_b64_tr_b16 v[80:81], v189 offset:65024
	v_add_f32_e32 v82, v82, v37
	v_exp_f32_e32 v40, v40
	v_exp_f32_e32 v41, v41
	v_add_f32_e32 v86, v38, v82
	s_waitcnt lgkmcnt(6)
	v_mfma_f32_32x32x16_bf16 v[18:33], v[134:137], v[66:69], v[18:33]
	ds_read_b128 v[82:85], v182 offset:12288
	v_cvt_pk_bf16_f32 v152, v38, v39
	v_add_f32_e32 v90, v86, v39
	v_exp_f32_e32 v42, v42
	v_exp_f32_e32 v43, v43
	s_waitcnt lgkmcnt(5)
	v_mfma_f32_32x32x16_bf16 v[18:33], v[130:133], v[70:73], v[18:33]
	ds_read_b128 v[86:89], v182 offset:16384
	v_add_f32_e32 v66, v90, v40
	v_exp_f32_e32 v44, v44
	v_cvt_pk_bf16_f32 v153, v40, v41
	v_add_f32_e32 v66, v41, v66
	s_waitcnt lgkmcnt(4)
	v_mfma_f32_32x32x16_bf16 v[18:33], v[126:129], v[74:77], v[18:33]
	ds_read_b128 v[154:157], v183 offset:12288
	v_add_f32_e32 v66, v66, v42
	v_exp_f32_e32 v45, v45
	v_cvt_pk_bf16_f32 v146, v42, v43
	v_add_f32_e32 v66, v43, v66
	s_waitcnt lgkmcnt(3)
	v_mfma_f32_32x32x16_bf16 v[18:33], v[122:125], v[78:81], v[18:33]
	ds_read_b128 v[162:165], v183 offset:16384
	v_exp_f32_e32 v46, v46
	v_exp_f32_e32 v47, v47
	v_add_f32_e32 v66, v66, v44
	v_cvt_pk_bf16_f32 v147, v44, v45
	s_nop 0
	v_add_f32_e32 v66, v66, v45
	v_add_f32_e32 v91, v46, v66
	s_waitcnt lgkmcnt(3)
	v_mfma_f32_32x32x16_bf16 v[66:81], v[82:85], v[98:101], 0
	ds_read_b128 v[166:169], v184 offset:12288
	v_exp_f32_e32 v48, v48
	v_exp_f32_e32 v49, v49
	ds_read_b128 v[158:161], v184 offset:16384
	v_add_f32_e32 v193, v91, v47
	s_waitcnt lgkmcnt(4)
	v_mfma_f32_32x32x16_bf16 v[82:97], v[86:89], v[98:101], 0
	v_exp_f32_e32 v50, v50
	s_add_u32 s26, s20, 0xfffe0000
	s_addc_u32 s27, s21, -1
	s_mov_b32 m0, s8
	v_exp_f32_e32 v51, v51
	global_load_lds_dwordx4 v174, s[26:27]
	s_add_i32 m0, 0x8000, s12
	v_cvt_pk_bf16_f32 v148, v46, v47
	global_load_lds_dwordx4 v191, s[26:27]
	s_waitcnt lgkmcnt(3)
	v_mfma_f32_32x32x16_bf16 v[66:81], v[154:157], v[102:105], v[66:81]
	ds_read_b128 v[194:197], v185 offset:12288
	v_add_f32_e32 v193, v193, v48
	v_cvt_pk_bf16_f32 v149, v48, v49
	v_add_f32_e32 v193, v49, v193
	v_exp_f32_e32 v52, v52
	s_waitcnt lgkmcnt(3)
	v_mfma_f32_32x32x16_bf16 v[82:97], v[162:165], v[102:105], v[82:97]
	ds_read_b128 v[154:157], v185 offset:16384
	v_add_f32_e32 v193, v193, v50
	v_exp_f32_e32 v53, v53
	v_cvt_pk_bf16_f32 v142, v50, v51
	v_add_f32_e32 v193, v51, v193
	s_waitcnt lgkmcnt(3)
	v_mfma_f32_32x32x16_bf16 v[66:81], v[166:169], v[106:109], v[66:81]
	ds_read_b128 v[162:165], v187 offset:20480
	v_exp_f32_e32 v54, v54
	v_exp_f32_e32 v55, v55
	v_add_f32_e32 v193, v193, v52
	v_cvt_pk_bf16_f32 v143, v52, v53
	s_waitcnt lgkmcnt(3)
	v_mfma_f32_32x32x16_bf16 v[82:97], v[158:161], v[106:109], v[82:97]
	ds_read_b128 v[198:201], v187 offset:22528
	v_add_f32_e32 v166, v193, v53
	v_exp_f32_e32 v56, v56
	v_exp_f32_e32 v57, v57
	v_add_f32_e32 v166, v54, v166
	s_waitcnt lgkmcnt(3)
	v_mfma_f32_32x32x16_bf16 v[66:81], v[194:197], v[110:113], v[66:81]
	ds_read_b128 v[202:205], v188 offset:20480
	v_cvt_pk_bf16_f32 v144, v54, v55
	v_add_f32_e32 v159, v166, v55
	v_exp_f32_e32 v58, v58
	v_exp_f32_e32 v59, v59
	s_waitcnt lgkmcnt(3)
	v_mfma_f32_32x32x16_bf16 v[82:97], v[154:157], v[110:113], v[82:97]
	ds_read_b128 v[194:197], v188 offset:22528
	v_add_f32_e32 v158, v159, v56
	v_exp_f32_e32 v60, v60
	v_cvt_pk_bf16_f32 v145, v56, v57
	v_add_f32_e32 v158, v57, v158
	s_waitcnt lgkmcnt(3)
	v_mfma_f32_32x32x16_bf16 v[66:81], v[162:165], v[114:117], v[66:81]
	ds_read_b64_tr_b16 v[166:167], v189 offset:16384
	ds_read_b64_tr_b16 v[168:169], v189 offset:16896
	v_add_f32_e32 v154, v158, v58
	v_exp_f32_e32 v61, v61
	v_cvt_pk_bf16_f32 v138, v58, v59
	v_add_f32_e32 v154, v59, v154
	s_waitcnt lgkmcnt(4)
	v_mfma_f32_32x32x16_bf16 v[82:97], v[198:201], v[114:117], v[82:97]
	ds_read_b64_tr_b16 v[162:163], v189 offset:17408
	ds_read_b64_tr_b16 v[164:165], v189 offset:17920
	v_exp_f32_e32 v62, v62
	v_exp_f32_e32 v63, v63
	v_add_f32_e32 v154, v154, v60
	v_cvt_pk_bf16_f32 v139, v60, v61
	s_waitcnt lgkmcnt(5)
	v_mfma_f32_32x32x16_bf16 v[66:81], v[202:205], v[118:121], v[66:81]
	ds_read_b64_tr_b16 v[158:159], v189 offset:18432
	ds_read_b64_tr_b16 v[160:161], v189 offset:18944
	v_add_f32_e32 v154, v154, v61
	v_exp_f32_e32 v64, v64
	v_exp_f32_e32 v65, v65
	v_add_f32_e32 v198, v62, v154
	s_waitcnt lgkmcnt(6)
	v_mfma_f32_32x32x16_bf16 v[82:97], v[194:197], v[118:121], v[82:97]
	ds_read_b64_tr_b16 v[154:155], v189 offset:19456
	ds_read_b64_tr_b16 v[156:157], v189 offset:19968
	v_add_f32_e32 v141, v198, v63
	v_add_f32_e32 v198, v64, v141
	v_cvt_pk_bf16_f32 v140, v62, v63
	v_cvt_pk_bf16_f32 v141, v64, v65
	v_add_f32_e32 v194, v65, v198
	s_waitcnt vmcnt(4) lgkmcnt(0)
	s_barrier
	v_mfma_f32_32x32x16_bf16 v[2:17], v[150:153], v[166:169], v[2:17]
	ds_read_b64_tr_b16 v[34:35], v189 offset:20480
	ds_read_b64_tr_b16 v[36:37], v189 offset:20992
	v_exp_f32_e32 v66, v66
	v_exp_f32_e32 v67, v67
	v_exp_f32_e32 v68, v68
	v_mfma_f32_32x32x16_bf16 v[2:17], v[146:149], v[162:165], v[2:17]
	ds_read_b64_tr_b16 v[38:39], v189 offset:21504
	ds_read_b64_tr_b16 v[40:41], v189 offset:22016
	v_add_f32_e32 v42, v194, v66
	v_exp_f32_e32 v69, v69
	v_cvt_pk_bf16_f32 v134, v66, v67
	v_add_f32_e32 v46, v67, v42
	v_mfma_f32_32x32x16_bf16 v[2:17], v[142:145], v[158:161], v[2:17]
	ds_read_b64_tr_b16 v[42:43], v189 offset:22528
	ds_read_b64_tr_b16 v[44:45], v189 offset:23040
	v_exp_f32_e32 v70, v70
	v_exp_f32_e32 v71, v71
	v_add_f32_e32 v50, v46, v68
	v_cvt_pk_bf16_f32 v135, v68, v69
	v_mfma_f32_32x32x16_bf16 v[2:17], v[138:141], v[154:157], v[2:17]
	ds_read_b64_tr_b16 v[46:47], v189 offset:23552
	ds_read_b64_tr_b16 v[48:49], v189 offset:24064
	v_add_f32_e32 v50, v50, v69
	v_exp_f32_e32 v72, v72
	v_exp_f32_e32 v73, v73
	v_add_f32_e32 v54, v70, v50
	s_waitcnt lgkmcnt(6)
	v_mfma_f32_32x32x16_bf16 v[18:33], v[150:153], v[34:37], v[18:33]
	ds_read_b128 v[50:53], v182 offset:24576
	v_cvt_pk_bf16_f32 v136, v70, v71
	v_add_f32_e32 v58, v54, v71
	v_exp_f32_e32 v74, v74
	v_exp_f32_e32 v75, v75
	s_waitcnt lgkmcnt(5)
	v_mfma_f32_32x32x16_bf16 v[18:33], v[146:149], v[38:41], v[18:33]
	ds_read_b128 v[54:57], v182 offset:28672
	v_add_f32_e32 v34, v58, v72
	v_exp_f32_e32 v76, v76
	v_cvt_pk_bf16_f32 v137, v72, v73
	v_add_f32_e32 v34, v73, v34
	s_waitcnt lgkmcnt(4)
	v_mfma_f32_32x32x16_bf16 v[18:33], v[142:145], v[42:45], v[18:33]
	ds_read_b128 v[154:157], v183 offset:24576
	v_add_f32_e32 v34, v34, v74
	v_exp_f32_e32 v77, v77
	v_cvt_pk_bf16_f32 v130, v74, v75
	v_add_f32_e32 v34, v75, v34
	s_waitcnt lgkmcnt(3)
	v_mfma_f32_32x32x16_bf16 v[18:33], v[138:141], v[46:49], v[18:33]
	ds_read_b128 v[162:165], v183 offset:28672
	v_exp_f32_e32 v78, v78
	v_exp_f32_e32 v79, v79
	v_add_f32_e32 v34, v34, v76
	v_cvt_pk_bf16_f32 v131, v76, v77
	s_nop 0
	v_add_f32_e32 v34, v34, v77
	v_add_f32_e32 v59, v78, v34
	s_waitcnt lgkmcnt(3)
	v_mfma_f32_32x32x16_bf16 v[34:49], v[50:53], v[98:101], 0
	ds_read_b128 v[166:169], v184 offset:24576
	v_exp_f32_e32 v80, v80
	v_exp_f32_e32 v81, v81
	ds_read_b128 v[158:161], v184 offset:28672
	v_add_f32_e32 v193, v59, v79
	s_waitcnt lgkmcnt(4)
	v_mfma_f32_32x32x16_bf16 v[50:65], v[54:57], v[98:101], 0
	v_exp_f32_e32 v82, v82
	s_add_i32 m0, 0x3000, s8
	v_exp_f32_e32 v83, v83
	global_load_lds_dwordx4 v174, s[20:21]
	s_add_i32 m0, 0xa000, s12
	v_cvt_pk_bf16_f32 v132, v78, v79
	global_load_lds_dwordx4 v191, s[20:21]
	s_waitcnt lgkmcnt(3)
	v_mfma_f32_32x32x16_bf16 v[34:49], v[154:157], v[102:105], v[34:49]
	ds_read_b128 v[194:197], v185 offset:24576
	v_add_f32_e32 v154, v193, v80
	v_exp_f32_e32 v84, v84
	v_cvt_pk_bf16_f32 v133, v80, v81
	v_add_f32_e32 v193, v81, v154
	s_waitcnt lgkmcnt(3)
	v_mfma_f32_32x32x16_bf16 v[50:65], v[162:165], v[102:105], v[50:65]
	ds_read_b128 v[154:157], v185 offset:28672
	v_add_f32_e32 v193, v193, v82
	v_exp_f32_e32 v85, v85
	v_cvt_pk_bf16_f32 v126, v82, v83
	v_add_f32_e32 v193, v83, v193
	s_waitcnt lgkmcnt(3)
	v_mfma_f32_32x32x16_bf16 v[34:49], v[166:169], v[106:109], v[34:49]
	ds_read_b128 v[162:165], v187 offset:32768
	v_exp_f32_e32 v86, v86
	v_exp_f32_e32 v87, v87
	v_add_f32_e32 v193, v193, v84
	v_cvt_pk_bf16_f32 v127, v84, v85
	s_waitcnt lgkmcnt(3)
	v_mfma_f32_32x32x16_bf16 v[50:65], v[158:161], v[106:109], v[50:65]
	ds_read_b128 v[198:201], v187 offset:34816
	v_add_f32_e32 v166, v193, v85
	v_exp_f32_e32 v88, v88
	v_exp_f32_e32 v89, v89
	v_add_f32_e32 v166, v86, v166
	s_waitcnt lgkmcnt(3)
	v_mfma_f32_32x32x16_bf16 v[34:49], v[194:197], v[110:113], v[34:49]
	ds_read_b128 v[202:205], v188 offset:32768
	v_cvt_pk_bf16_f32 v128, v86, v87
	v_add_f32_e32 v159, v166, v87
	v_exp_f32_e32 v90, v90
	v_exp_f32_e32 v91, v91
	s_waitcnt lgkmcnt(3)
	v_mfma_f32_32x32x16_bf16 v[50:65], v[154:157], v[110:113], v[50:65]
	ds_read_b128 v[194:197], v188 offset:34816
	v_add_f32_e32 v158, v159, v88
	v_exp_f32_e32 v92, v92
	v_cvt_pk_bf16_f32 v129, v88, v89
	v_add_f32_e32 v158, v89, v158
	s_waitcnt lgkmcnt(3)
	v_mfma_f32_32x32x16_bf16 v[34:49], v[162:165], v[114:117], v[34:49]
	ds_read_b64_tr_b16 v[166:167], v189 offset:24576
	ds_read_b64_tr_b16 v[168:169], v189 offset:25088
	v_add_f32_e32 v154, v158, v90
	v_exp_f32_e32 v93, v93
	v_cvt_pk_bf16_f32 v122, v90, v91
	v_add_f32_e32 v154, v91, v154
	s_waitcnt lgkmcnt(4)
	v_mfma_f32_32x32x16_bf16 v[50:65], v[198:201], v[114:117], v[50:65]
	ds_read_b64_tr_b16 v[162:163], v189 offset:25600
	ds_read_b64_tr_b16 v[164:165], v189 offset:26112
	v_exp_f32_e32 v94, v94
	v_exp_f32_e32 v95, v95
	v_add_f32_e32 v154, v154, v92
	v_cvt_pk_bf16_f32 v123, v92, v93
	s_waitcnt lgkmcnt(5)
	v_mfma_f32_32x32x16_bf16 v[34:49], v[202:205], v[118:121], v[34:49]
	ds_read_b64_tr_b16 v[158:159], v189 offset:26624
	ds_read_b64_tr_b16 v[160:161], v189 offset:27136
	v_add_f32_e32 v154, v154, v93
	v_exp_f32_e32 v96, v96
	v_exp_f32_e32 v97, v97
	v_add_f32_e32 v193, v94, v154
	s_waitcnt lgkmcnt(6)
	v_mfma_f32_32x32x16_bf16 v[50:65], v[194:197], v[118:121], v[50:65]
	ds_read_b64_tr_b16 v[154:155], v189 offset:27648
	ds_read_b64_tr_b16 v[156:157], v189 offset:28160
	v_add_f32_e32 v125, v193, v95
	v_add_f32_e32 v193, v96, v125
	v_cvt_pk_bf16_f32 v124, v94, v95
	v_cvt_pk_bf16_f32 v125, v96, v97
	v_add_f32_e32 v193, v97, v193
	s_add_u32 s22, s22, 0x2000
	s_addc_u32 s23, s23, 0
	s_add_u32 s20, s20, 0x40000
	s_addc_u32 s21, s21, 0
	s_add_i32 s13, s13, 12
	s_cmp_le_i32 s13, 108
	s_cbranch_scc1 .Lmla_fast_w47
	v_subrev_u32_e32 v189, 0x8000, v189
	s_mov_b32 s2, 0x4000
	s_mov_b32 s17, 0x6000
	s_mov_b32 s26, 0x2000
	s_mov_b32 s14, 0x0
	s_mov_b32 s15, 0x9000
	s_branch .LBB0_1278
